# attention DPP + nt (non-temporal) on retc LDS-DMA streaming loads
# speedup vs baseline: 1.0180x; 1.0089x over previous
; __device__ __forceinline__ void retc_stream(const int wv, LAS unsigned char* lds, unsigned ldsb, const float* __restrict__ gn_g, const float* __restrict__ gn_b, const bf16_t* __restrict__ qkvr, const bf16_t* __restrict__ grb, const bf16_t* __restrict__ kv, ...
;     ...
;     const int t = t_, w = __builtin_amdgcn_readfirstlane(t >> 6), lane = t & 63, li = lane & 15, g = lane >> 4;
;     if (first >= count) return;
;     const size_t RS = (size_t)QKVR_LD * 2;
;     const unsigned rsub = (unsigned)w * 2u + ((unsigned)lane >> 5), cc = ((unsigned)lane & 31u) ^ rsub;
;     const size_t goffA = (size_t)rsub * RS + cc * 16;
;     const size_t goffS = (size_t)rsub * 512 + cc * 16;
;     const int q4 = li >> 2, p4 = lane & 3;
;     ...
;     unsigned koff[8], toff[8];
; #pragma unroll
;     for (int s = 0; s < 8; ++s) { koff[s] = (unsigned)li * 512u + ((((unsigned)(4 * s + g)) ^ (unsigned)li) << 4); asm volatile("" : "+v"(koff[s])); }
;     { const unsigned xx = (unsigned)(4 * g + q4) & 15u, ph = (unsigned)p4 >> 1, rb = (unsigned)(4 * g + q4) * 512u + 8u * ((unsigned)p4 & 1u);
; #pragma unroll
;       for (int c = 0; c < 8; ++c) { toff[c] = rb + (((2u * c + ph) ^ xx) << 4); asm volatile("" : "+v"(toff[c])); } }
;     int item = first;
;     RETC_ISSUE(item, 0);
.LBB0_466:
	s_or_b64 exec, exec, s[0:1]
	s_mov_b64 s[2:3], s[56:57]
	v_readlane_b32 s0, v253, 43
	s_waitcnt lgkmcnt(0)
	s_barrier
	v_mbcnt_lo_u32_b32 v1, -1, 0
	v_mbcnt_hi_u32_b32 v1, -1, v1
	v_readlane_b32 s1, v253, 44
	v_add_u32_e32 v191, s53, v1
	s_andn2_b64 vcc, exec, s[0:1]
	v_readfirstlane_b32 s4, v191
	s_cbranch_vccnz .LBB0_504
	s_load_dwordx2 s[0:1], s[2:3], 0x70
	s_load_dwordx4 s[16:19], s[2:3], 0x28
	v_bfe_u32 v2, v191, 5, 1
	v_and_b32_e32 v3, 31, v191
	s_waitcnt vmcnt(0)
	v_mov_b32_e32 v5, v0
	s_waitcnt lgkmcnt(0)
	s_add_u32 s82, s0, 0x8c00000
	s_addc_u32 s39, s1, 0
	s_add_u32 s2, s0, 0x11400000
	v_writelane_b32 v254, s2, 31
	s_addc_u32 s2, s1, 0
	v_writelane_b32 v254, s2, 33
	s_lshl_b64 s[2:3], s[80:81], 1
	s_add_u32 s2, s0, s2
	s_addc_u32 s3, s1, s3
	s_add_u32 s2, s2, 0x15400000
	v_writelane_b32 v254, s2, 35
	s_addc_u32 s2, s3, 0
	s_ashr_i32 s3, s4, 6
	v_writelane_b32 v254, s2, 37
	s_lshl_b32 s2, s3, 1
	v_or_b32_e32 v4, s2, v2
	v_bitop3_b32 v2, s2, v3, v2 bitop3:0x36
	v_bfe_u32 v1, v191, 4, 2
	v_and_b32_e32 v9, 15, v191
	v_lshlrev_b32_e32 v2, 4, v2
	v_mov_b32_e32 v3, v0
	v_lshlrev_b64 v[6:7], 9, v[4:5]
	v_lshl_add_u64 v[2:3], v[6:7], 0, v[2:3]
	v_lshlrev_b32_e32 v5, 9, v9
	v_bitop3_b32 v6, v1, v191, 15 bitop3:0x78
	v_lshl_or_b32 v192, v6, 4, v5
	v_bitop3_b32 v6, v1, v9, 4 bitop3:0x36
	v_lshl_or_b32 v193, v6, 4, v5
	v_bitop3_b32 v6, v1, v9, 8 bitop3:0x36
	v_lshl_or_b32 v194, v6, 4, v5
	v_bitop3_b32 v6, v1, v9, 12 bitop3:0x36
	v_lshl_or_b32 v195, v6, 4, v5
	v_bitop3_b32 v6, v1, v9, 16 bitop3:0x36
	v_lshl_or_b32 v196, v6, 4, v5
	v_bitop3_b32 v6, v1, v9, 20 bitop3:0x36
	v_lshl_or_b32 v197, v6, 4, v5
	v_bitop3_b32 v6, v1, v9, 24 bitop3:0x36
	v_lshl_or_b32 v198, v6, 4, v5
	v_bitop3_b32 v6, v1, v9, 28 bitop3:0x36
	v_lshl_or_b32 v199, v6, 4, v5
	v_bfe_u32 v5, v191, 2, 2
	v_lshlrev_b32_e32 v10, 2, v1
	v_lshlrev_b32_e32 v11, 3, v191
	v_or_b32_e32 v6, v10, v5
	v_bfe_u32 v7, v191, 1, 1
	v_and_b32_e32 v11, 8, v11
	v_lshl_or_b32 v6, v6, 9, v11
	v_bitop3_b32 v11, v10, v7, v5 bitop3:0x36
	v_lshl_or_b32 v200, v11, 4, v6
	v_or_b32_e32 v11, 2, v7
	v_bitop3_b32 v11, v10, v11, v5 bitop3:0x36
	v_lshl_or_b32 v201, v11, 4, v6
	v_or_b32_e32 v11, 4, v7
	v_bitop3_b32 v11, v10, v11, v5 bitop3:0x36
	v_lshl_or_b32 v202, v11, 4, v6
	v_or_b32_e32 v11, 6, v7
	v_bitop3_b32 v11, v10, v11, v5 bitop3:0x36
	v_lshl_or_b32 v203, v11, 4, v6
	v_or_b32_e32 v11, 8, v7
	s_movk_i32 s2, 0x4200
	v_bitop3_b32 v11, v10, v11, v5 bitop3:0x36
	v_mad_u64_u32 v[180:181], s[4:5], v4, s2, v[2:3]
	v_readlane_b32 s2, v253, 59
	v_lshl_or_b32 v204, v11, 4, v6
	v_or_b32_e32 v11, 10, v7
	s_add_u32 s2, s82, s2
	v_bitop3_b32 v11, v10, v11, v5 bitop3:0x36
	s_addc_u32 s5, s39, 0
	v_readlane_b32 s6, v253, 60
	v_lshl_or_b32 v205, v11, 4, v6
	v_or_b32_e32 v11, 12, v7
	v_or_b32_e32 v7, 14, v7
	v_readlane_b32 s7, v253, 61
	s_add_u32 s4, s2, s6
	v_bitop3_b32 v11, v10, v11, v5 bitop3:0x36
	v_bitop3_b32 v5, v10, v7, v5 bitop3:0x36
	s_addc_u32 s5, s5, s7
	s_lshl_b32 s2, s3, 10
	v_lshl_or_b32 v207, v5, 4, v6
	v_lshl_add_u64 v[4:5], s[4:5], 0, v[180:181]
	s_mov_b64 s[4:5], 0x2400
	s_add_i32 s58, s2, 0
	v_lshl_or_b32 v206, v11, 4, v6
	v_lshl_add_u64 v[6:7], v[4:5], 0, s[4:5]
	s_mov_b32 m0, s58
	s_mov_b64 s[4:5], 0x46400
	s_add_i32 s47, s58, 0x2000
	global_load_lds_dwordx4 v[6:7], off nt
	v_lshl_add_u64 v[6:7], v[4:5], 0, s[4:5]
	s_mov_b32 m0, s47
	s_mov_b64 s[4:5], 0x8a400
	s_add_i32 s24, s58, 0x4000
	global_load_lds_dwordx4 v[6:7], off nt
	v_lshl_add_u64 v[6:7], v[4:5], 0, s[4:5]
	s_mov_b32 m0, s24
	s_mov_b64 s[4:5], 0xce400
	s_add_i32 s25, s58, 0x6000
	global_load_lds_dwordx4 v[6:7], off nt
	v_lshl_add_u64 v[6:7], v[4:5], 0, s[4:5]
	s_mov_b32 m0, s25
	s_mov_b64 s[4:5], 0x112400
	s_add_i32 s48, s58, 0x8000
	global_load_lds_dwordx4 v[6:7], off nt
	v_lshl_add_u64 v[6:7], v[4:5], 0, s[4:5]
	s_mov_b32 m0, s48
	s_mov_b64 s[4:5], 0x156400
	s_add_i32 s49, s58, 0xa000
	global_load_lds_dwordx4 v[6:7], off nt
	v_lshl_add_u64 v[6:7], v[4:5], 0, s[4:5]
	s_mov_b32 m0, s49
	s_mov_b64 s[4:5], 0x19a400
	s_add_i32 s50, s58, 0xc000
	global_load_lds_dwordx4 v[6:7], off nt
	v_lshl_add_u64 v[6:7], v[4:5], 0, s[4:5]
	s_mov_b32 m0, s50
	s_mov_b64 s[4:5], 0x1de400
	s_add_i32 s51, s58, 0xe000
	global_load_lds_dwordx4 v[6:7], off nt
	v_lshl_add_u64 v[4:5], v[4:5], 0, s[4:5]
	s_mov_b32 m0, s51
	s_lshl_b32 s4, s3, 4
; __device__ __forceinline__ void retc_stream(const int wv, LAS unsigned char* lds, unsigned ldsb, const float* __restrict__ gn_g, const float* __restrict__ gn_b, const bf16_t* __restrict__ qkvr, const bf16_t* __restrict__ grb, const bf16_t* __restrict__ kv, ...
;     ...
;     unsigned koff[8], toff[8];
; #pragma unroll
;     for (int s = 0; s < 8; ++s) { koff[s] = (unsigned)li * 512u + ((((unsigned)(4 * s + g)) ^ (unsigned)li) << 4); asm volatile("" : "+v"(koff[s])); }
;     { const unsigned xx = (unsigned)(4 * g + q4) & 15u, ph = (unsigned)p4 >> 1, rb = (unsigned)(4 * g + q4) * 512u + 8u * ((unsigned)p4 & 1u);
; #pragma unroll
;       for (int c = 0; c < 8; ++c) { toff[c] = rb + (((2u * c + ph) ^ xx) << 4); asm volatile("" : "+v"(toff[c])); } }
;     int item = first;
;     RETC_ISSUE(item, 0);
;     ...
;                 }
; #pragma unroll
;                 for (int e = 0; e < 4; ++e) { const int kj = 16 * kt + 4 * g + e; a[e] = (kj <= qi) ? a[e] : 0.f; }
;                 sc[kt] = a;
	global_load_lds_dwordx4 v[4:5], off nt
	v_or_b32_e32 v4, s4, v9
	v_and_b32_e32 v8, 63, v191
	v_or_b32_e32 v5, s4, v10
	v_cmp_gt_i32_e64 s[4:5], v10, v4
	v_lshlrev_b32_e32 v7, 2, v8
	v_xor_b32_e32 v208, 4, v7
	v_writelane_b32 v254, s4, 39
	v_xor_b32_e32 v209, 8, v7
	v_xor_b32_e32 v210, 16, v7
	v_xor_b32_e32 v211, 32, v7
	v_lshlrev_b32_e32 v7, 1, v9
	v_writelane_b32 v254, s5, 40
	v_cmp_lt_i32_e64 s[4:5], v10, v4
	v_lshl_or_b32 v212, v5, 10, v7
	v_or_b32_e32 v7, 2, v10
	v_writelane_b32 v254, s4, 41
	s_lshl_b32 s2, s3, 13
	s_cmp_gt_i32 s3, -1
	v_writelane_b32 v254, s5, 42
	v_cmp_gt_i32_e64 s[4:5], v7, v4
	v_or_b32_e32 v7, 3, v10
	s_cselect_b64 s[22:23], -1, 0
	v_writelane_b32 v254, s4, 43
	s_cmp_gt_i32 s3, 0
	v_add_u32_e32 v6, 0xffffff81, v5
	v_writelane_b32 v254, s5, 44
	v_cmp_gt_i32_e64 s[4:5], v7, v4
	v_or_b32_e32 v7, 16, v10
	v_cvt_f32_i32_e32 v213, v6
	v_writelane_b32 v254, s4, 45
	v_add_u32_e32 v6, 0xffffff82, v5
	v_cvt_f32_i32_e32 v214, v6
	v_writelane_b32 v254, s5, 46
	s_cselect_b64 s[4:5], -1, 0
	v_writelane_b32 v254, s4, 47
	s_cmp_gt_i32 s3, 1
	s_cselect_b64 s[26:27], -1, 0
	v_writelane_b32 v254, s5, 48
	v_cmp_gt_i32_e64 s[4:5], v7, v4
	v_or_b32_e32 v7, 17, v10
	s_cmp_gt_i32 s3, 2
	v_writelane_b32 v254, s4, 49
	v_add_u32_e32 v6, 0xffffff83, v5
	v_add_u32_e32 v5, 0xffffff84, v5
	v_writelane_b32 v254, s5, 50
	v_cmp_gt_i32_e64 s[4:5], v7, v4
	v_or_b32_e32 v7, 18, v10
	v_cvt_f32_i32_e32 v215, v6
	v_writelane_b32 v254, s4, 51
	v_cvt_f32_i32_e32 v216, v5
	v_or_b32_e32 v8, 64, v10
	v_writelane_b32 v254, s5, 52
	v_cmp_gt_i32_e64 s[4:5], v7, v4
	v_or_b32_e32 v7, 19, v10
	v_or_b32_e32 v9, 0x41, v10
	v_writelane_b32 v254, s4, 53
	v_or_b32_e32 v11, 0x42, v10
	v_or_b32_e32 v12, 0x43, v10
	v_writelane_b32 v254, s5, 54
	v_cmp_gt_i32_e64 s[4:5], v7, v4
	v_or_b32_e32 v7, 32, v10
	v_or_b32_e32 v13, 0x50, v10
	v_writelane_b32 v254, s4, 55
	v_or_b32_e32 v14, 0x51, v10
	v_or_b32_e32 v15, 0x52, v10
	v_writelane_b32 v254, s5, 56
	v_cmp_gt_i32_e64 s[4:5], v7, v4
	v_or_b32_e32 v7, 33, v10
	v_or_b32_e32 v16, 0x53, v10
	v_writelane_b32 v254, s4, 57
	v_or_b32_e32 v17, 0x60, v10
	v_or_b32_e32 v18, 0x61, v10
	v_writelane_b32 v254, s5, 58
	v_cmp_gt_i32_e64 s[4:5], v7, v4
	v_or_b32_e32 v7, 34, v10
	v_or_b32_e32 v19, 0x62, v10
	v_writelane_b32 v254, s4, 59
	v_or_b32_e32 v20, 0x63, v10
	v_or_b32_e32 v21, 0x70, v10
	v_writelane_b32 v254, s5, 60
	v_cmp_gt_i32_e64 s[4:5], v7, v4
	v_or_b32_e32 v7, 35, v10
	v_cmp_gt_i32_e64 s[62:63], v7, v4
	v_writelane_b32 v254, s4, 61
	v_or_b32_e32 v7, 48, v10
	v_cmp_gt_i32_e64 s[64:65], v7, v4
	v_writelane_b32 v254, s5, 62
	s_cselect_b64 s[4:5], -1, 0
	s_cmp_gt_i32 s3, 3
	s_cselect_b64 s[30:31], -1, 0
	s_cmp_gt_i32 s3, 4
	s_cselect_b64 s[34:35], -1, 0
	s_cmp_gt_i32 s3, 5
	s_cselect_b64 s[42:43], -1, 0
	s_cmp_gt_i32 s3, 6
	s_cselect_b64 s[44:45], -1, 0
	s_add_i32 s46, s58, 0x10000
	s_add_i32 s53, s58, 0x12000
	s_add_i32 s52, s58, 0x14000
	s_add_i32 s55, s58, 0x16000
	s_add_i32 s54, s58, 0x18000
	s_add_i32 s57, s58, 0x1a000
	s_add_i32 s56, s58, 0x1c000
	s_add_i32 s59, s58, 0x1e000
	v_readlane_b32 s3, v253, 52
	s_add_u32 s0, s0, s3
	v_readlane_b32 s3, v253, 53
	s_addc_u32 s1, s1, s3
	v_writelane_b32 v254, s4, 63
	v_lshl_add_u64 v[182:183], s[0:1], 0, v[2:3]
	v_or_b32_e32 v2, 49, v10
	v_or_b32_e32 v3, 50, v10
	v_or_b32_e32 v7, 51, v10
	v_or_b32_e32 v22, 0x71, v10
	v_or_b32_e32 v23, 0x72, v10
	v_or_b32_e32 v10, 0x73, v10
	v_lshlrev_b32_e32 v217, 5, v1
	v_writelane_b32 v252, s5, 0
	v_xor_b32_e32 v218, 32, v217
	v_xor_b32_e32 v219, 64, v217
	v_xor_b32_e32 v220, 0x60, v217
	v_mov_b32_e32 v221, s2
	v_readlane_b32 s60, v253, 56
	v_readlane_b32 s61, v253, 54
	s_mov_b32 s28, s66
	v_cmp_gt_i32_e64 s[66:67], v2, v4
	v_cmp_gt_i32_e64 s[68:69], v3, v4
	v_cmp_gt_i32_e64 s[70:71], v7, v4
	v_cmp_gt_i32_e64 s[72:73], v8, v4
	v_cmp_gt_i32_e64 s[74:75], v9, v4
	v_cmp_gt_i32_e64 s[76:77], v11, v4
	v_cmp_gt_i32_e64 s[78:79], v12, v4
	v_cmp_gt_i32_e64 s[80:81], v13, v4
	v_cmp_gt_i32_e64 s[14:15], v14, v4
	v_cmp_gt_i32_e64 s[84:85], v15, v4
	v_cmp_gt_i32_e64 s[86:87], v16, v4
	v_cmp_gt_i32_e64 s[20:21], v17, v4
	v_cmp_gt_i32_e64 s[90:91], v18, v4
	v_cmp_gt_i32_e64 s[92:93], v19, v4
	v_cmp_gt_i32_e64 s[94:95], v20, v4
	v_cmp_gt_i32_e64 s[96:97], v21, v4
	v_cmp_gt_i32_e64 s[4:5], v22, v4
	v_cmp_gt_i32_e64 s[6:7], v23, v4
	v_cmp_gt_i32_e64 s[8:9], v10, v4
	s_branch .LBB0_469

; #define LAS __attribute__((address_space(3)))
; #define MFMA16(a, b, c) __builtin_amdgcn_mfma_f32_16x16x32_bf16((a), (b), (c), 0, 0, 0)
; #define WAITV0() asm volatile("s_waitcnt vmcnt(0)" ::: "memory")
; #define LBAR() do { asm volatile("s_waitcnt lgkmcnt(0)" ::: "memory"); __builtin_amdgcn_s_barrier(); asm volatile("" ::: "memory"); } while (0)
; __device__ __forceinline__ void retc_stream(const int wv, LAS unsigned char* lds, unsigned ldsb, const float* __restrict__ gn_g, const float* __restrict__ gn_b, const bf16_t* __restrict__ qkvr, const bf16_t* __restrict__ grb, const bf16_t* __restrict__ kv, ...
;     ...
;     for (;;) {
;         const int h = item >> 6, n = item & 63;
;         const int inext = item + stride;
;         const float lg2 = log2f(1.0f - exp2f(-5.0f - (float)h));
;         WAITV0(); LBAR(); RETC_ISSUE(item, 1);
;         bf16x8 qf[8];
;         { unsigned ib = (unsigned)w * 8192u; asm volatile("" : "+v"(ib));
; #pragma unroll
;         for (int s = 0; s < 8; ++s) qf[s] = *(const LAS bf16x8*)(lds + ib + koff[s]); }
;         WAITV0(); LBAR(); RETC_ISSUE(item, 2);
;         bf16x8 pf[4];
;         {
;             f32x4 sc[8];
;             const int qi = 16 * w + li;
;             unsigned ibk = 65536u; asm volatile("" : "+v"(ibk));
; #pragma unroll
;             for (int kt = 0; kt < 8; ++kt) {
;                 f32x4 a = (f32x4){0.f, 0.f, 0.f, 0.f};
;                 if (kt <= w) {
;                     bf16x8 kf[8];
; #pragma unroll
;                     for (int s = 0; s < 8; ++s) kf[s] = *(const LAS bf16x8*)(lds + ibk + kt * 8192 + koff[s]);
;                     asm volatile("s_waitcnt lgkmcnt(0)" ::: "memory");
; #pragma unroll
;                     for (int s = 0; s < 8; ++s) a = MFMA16(kf[s], qf[s], a);
.LBB0_469:
	s_ashr_i32 s40, s28, 6
	s_and_b32 s29, s28, 63
	s_lshl_b32 s0, s40, 8
	s_mul_i32 s1, s29, 0x220000
	s_add_u32 s2, s82, s1
	s_addc_u32 s3, s39, 0
	s_ashr_i32 s1, s0, 31
	s_lshl_b64 s[0:1], s[0:1], 1
	s_add_u32 s0, s2, s0
	s_addc_u32 s1, s3, s1
	s_waitcnt vmcnt(0)
	v_lshl_add_u64 v[2:3], s[0:1], 0, v[180:181]
	s_mov_b64 s[2:3], 0x2c00
	s_mov_b32 m0, s46
	s_waitcnt lgkmcnt(0)
	s_barrier
	v_lshl_add_u64 v[4:5], v[2:3], 0, s[2:3]
	s_mov_b64 s[2:3], 0x46c00
	global_load_lds_dwordx4 v[4:5], off nt
	v_lshl_add_u64 v[4:5], v[2:3], 0, s[2:3]
	s_mov_b32 m0, s53
	s_mov_b64 s[2:3], 0x8ac00
	global_load_lds_dwordx4 v[4:5], off nt
	v_lshl_add_u64 v[4:5], v[2:3], 0, s[2:3]
	s_mov_b32 m0, s52
	s_mov_b64 s[2:3], 0xcec00
	global_load_lds_dwordx4 v[4:5], off nt
	v_lshl_add_u64 v[4:5], v[2:3], 0, s[2:3]
	s_mov_b32 m0, s55
	s_mov_b64 s[2:3], 0x112c00
	global_load_lds_dwordx4 v[4:5], off nt
	v_lshl_add_u64 v[4:5], v[2:3], 0, s[2:3]
	s_mov_b32 m0, s54
	s_mov_b64 s[2:3], 0x156c00
	global_load_lds_dwordx4 v[4:5], off nt
	v_lshl_add_u64 v[4:5], v[2:3], 0, s[2:3]
	s_mov_b32 m0, s57
	s_mov_b64 s[2:3], 0x19ac00
	global_load_lds_dwordx4 v[4:5], off nt
	v_lshl_add_u64 v[4:5], v[2:3], 0, s[2:3]
	s_mov_b32 m0, s56
	s_mov_b64 s[2:3], 0x1dec00
	global_load_lds_dwordx4 v[4:5], off nt
	v_lshl_add_u64 v[2:3], v[2:3], 0, s[2:3]
	s_mov_b32 m0, s59
	v_mov_b32_e32 v1, v221
	global_load_lds_dwordx4 v[2:3], off nt
	s_ashr_i32 s41, s40, 31
	v_add_u32_e32 v1, 0, v1
	v_add_u32_e32 v2, v1, v192
	v_add_u32_e32 v3, v1, v193
	ds_read_b128 v[62:65], v2
	ds_read_b128 v[58:61], v3
	v_add_u32_e32 v2, v1, v194
	s_lshl_b64 s[2:3], s[40:41], 9
	v_add_u32_e32 v3, v1, v195
	ds_read_b128 v[54:57], v2
	ds_read_b128 v[50:53], v3
	v_add_u32_e32 v2, v1, v196
	s_add_u32 s0, s0, s2
	v_add_u32_e32 v3, v1, v197
	ds_read_b128 v[46:49], v2
	ds_read_b128 v[42:45], v3
	v_add_u32_e32 v2, v1, v198
	s_addc_u32 s1, s1, s3
	v_add_u32_e32 v1, v1, v199
	ds_read_b128 v[38:41], v2
	ds_read_b128 v[34:37], v1
	s_waitcnt vmcnt(0)
	v_lshl_add_u64 v[66:67], s[0:1], 0, v[180:181]
	s_mov_b64 s[0:1], 0x3400
	s_waitcnt lgkmcnt(0)
	s_barrier
	v_lshl_add_u64 v[2:3], v[66:67], 0, s[0:1]
	s_mov_b32 m0, s58
	s_mov_b64 s[0:1], 0x47400
	global_load_lds_dwordx4 v[2:3], off nt
	v_lshl_add_u64 v[2:3], v[66:67], 0, s[0:1]
	s_mov_b32 m0, s47
	s_mov_b64 s[0:1], 0x8b400
	global_load_lds_dwordx4 v[2:3], off nt
	v_lshl_add_u64 v[2:3], v[66:67], 0, s[0:1]
	s_mov_b32 m0, s24
	s_mov_b64 s[0:1], 0xcf400
	global_load_lds_dwordx4 v[2:3], off nt
	v_lshl_add_u64 v[2:3], v[66:67], 0, s[0:1]
	s_mov_b32 m0, s25
	s_mov_b64 s[0:1], 0x113400
	global_load_lds_dwordx4 v[2:3], off nt
	v_lshl_add_u64 v[2:3], v[66:67], 0, s[0:1]
	s_mov_b32 m0, s48
	s_mov_b64 s[0:1], 0x157400
	global_load_lds_dwordx4 v[2:3], off nt
	v_lshl_add_u64 v[2:3], v[66:67], 0, s[0:1]
	s_mov_b32 m0, s49
	s_mov_b64 s[0:1], 0x19b400
	global_load_lds_dwordx4 v[2:3], off nt
	v_lshl_add_u64 v[2:3], v[66:67], 0, s[0:1]
	s_mov_b32 m0, s50
	s_mov_b64 s[0:1], 0x1df400
	global_load_lds_dwordx4 v[2:3], off nt
	v_lshl_add_u64 v[2:3], v[66:67], 0, s[0:1]
	s_mov_b32 m0, s51
	v_mov_b32_e32 v1, 0x10000
	global_load_lds_dwordx4 v[2:3], off nt
	v_cndmask_b32_e64 v2, 0, 1, s[22:23]
	v_add_u32_e32 v1, 0, v1
	v_mov_b32_e32 v6, 0
	v_cmp_ne_u32_e64 s[12:13], 1, v2
	s_andn2_b64 vcc, exec, s[22:23]
	v_add_u32_e32 v74, v1, v192
	v_add_u32_e32 v73, v1, v193
	v_add_u32_e32 v72, v1, v194
	v_add_u32_e32 v71, v1, v195
	v_add_u32_e32 v70, v1, v196
	v_add_u32_e32 v69, v1, v197
	v_add_u32_e32 v68, v1, v198
	v_add_u32_e32 v1, v1, v199
	v_mov_b32_e32 v2, 0
	v_mov_b32_e32 v3, 0
	v_mov_b32_e32 v4, 0
	v_mov_b32_e32 v5, 0
	s_cbranch_vccnz .LBB0_471
	ds_read_b128 v[2:5], v74
	ds_read_b128 v[8:11], v73
	s_waitcnt lgkmcnt(0)
	v_mfma_f32_16x16x32_bf16 v[2:5], v[2:5], v[62:65], 0
	v_mfma_f32_16x16x32_bf16 v[2:5], v[8:11], v[58:61], v[2:5]
	ds_read_b128 v[8:11], v72
	s_waitcnt lgkmcnt(0)
	v_mfma_f32_16x16x32_bf16 v[2:5], v[8:11], v[54:57], v[2:5]
	ds_read_b128 v[8:11], v71
	s_waitcnt lgkmcnt(0)
	v_mfma_f32_16x16x32_bf16 v[2:5], v[8:11], v[50:53], v[2:5]
	ds_read_b128 v[8:11], v70
	s_waitcnt lgkmcnt(0)
	v_mfma_f32_16x16x32_bf16 v[2:5], v[8:11], v[46:49], v[2:5]
	ds_read_b128 v[8:11], v69
	s_waitcnt lgkmcnt(0)
	v_mfma_f32_16x16x32_bf16 v[2:5], v[8:11], v[42:45], v[2:5]
	ds_read_b128 v[8:11], v68
	s_waitcnt lgkmcnt(0)
	v_mfma_f32_16x16x32_bf16 v[2:5], v[8:11], v[38:41], v[2:5]
	ds_read_b128 v[8:11], v1
	s_waitcnt lgkmcnt(0)
	s_waitcnt lgkmcnt(0)
	v_mfma_f32_16x16x32_bf16 v[2:5], v[8:11], v[34:37], v[2:5]

; __device__ __forceinline__ unsigned cvt_pk_bf16(float lo, float hi) { unsigned r; asm volatile("v_cvt_pk_bf16_f32 %0, %1, %2" : "=v"(r) : "v"(lo), "v"(hi)); return r; }
; #define MFMA16(a, b, c) __builtin_amdgcn_mfma_f32_16x16x32_bf16((a), (b), (c), 0, 0, 0)
; #define WAITV0() asm volatile("s_waitcnt vmcnt(0)" ::: "memory")
; __device__ __forceinline__ void retc_stream(const int wv, LAS unsigned char* lds, unsigned ldsb, const float* __restrict__ gn_g, const float* __restrict__ gn_b, const bf16_t* __restrict__ qkvr, const bf16_t* __restrict__ grb, const bf16_t* __restrict__ kv, ...
;     ...
; #pragma unroll
;                 for (int e = 0; e < 4; ++e) { const int kj = 16 * kt + 4 * g + e; a[e] = (kj <= qi) ? a[e] : 0.f; }
;                 sc[kt] = a;
;             }
; #pragma unroll
;             for (int u = 0; u < 4; ++u) { Frag f; f.u.x = cvt_pk_bf16(sc[2 * u][0], sc[2 * u][1]); f.u.y = cvt_pk_bf16(sc[2 * u][2], sc[2 * u][3]); f.u.z = cvt_pk_bf16(sc[2 * u + 1][0], sc[2 * u + 1][1]); f.u.w = cvt_pk_bf16(sc[2 * u + 1][2], sc[2 * u + 1][3]); pf[u] = f.v; }
;         }
;         f32x4 acc[32];
; #pragma unroll
;         for (int c = 0; c < 32; ++c) acc[c] = (f32x4){0.f, 0.f, 0.f, 0.f};
; #pragma unroll
;         for (int vh = 0; vh < 2; ++vh) {
;             WAITV0(); LBAR(); RETC_ISSUE(item, 3 + vh);
;             unsigned imgb = ldsb + vh * 65536u; asm volatile("" : "+v"(imgb));
; #pragma unroll
;             for (int u = 0; u < 4; ++u) {
;                 if (2 * u <= w) {
;                     const unsigned a0 = imgb + u * 16384u, a1 = a0 + 8192u;
; #pragma unroll
;                     for (int c = 0; c < 16; c += 4) {
;                         bf16x8 v0, v1, v2, v3;
;                         const unsigned hi = (c >> 3) * 256u;
;                         tr_frag4x(a0 + hi + toff[c & 7], a1 + hi + toff[c & 7], a0 + hi + toff[(c & 7) + 1], a1 + hi + toff[(c & 7) + 1],
;                                   a0 + hi + toff[(c & 7) + 2], a1 + hi + toff[(c & 7) + 2], a0 + hi + toff[(c & 7) + 3], a1 + hi + toff[(c & 7) + 3], v0, v1, v2, v3);
;                         acc[vh * 16 + c] = MFMA16(pf[u], v0, acc[vh * 16 + c]); acc[vh * 16 + c + 1] = MFMA16(pf[u], v1, acc[vh * 16 + c + 1]);
;                         acc[vh * 16 + c + 2] = MFMA16(pf[u], v2, acc[vh * 16 + c + 2]); acc[vh * 16 + c + 3] = MFMA16(pf[u], v3, acc[vh * 16 + c + 3]);
;                     }
.LBB0_485:
	v_readlane_b32 vcc_lo, v254, 57
	v_readlane_b32 vcc_hi, v254, 58
	v_cndmask_b32_e64 v1, v30, 0, s[20:21]
	v_cndmask_b32_e64 v30, v31, 0, s[90:91]
	v_cndmask_b32_e64 v10, v10, 0, vcc
	v_readlane_b32 vcc_lo, v254, 59
	v_readlane_b32 vcc_hi, v254, 60
	v_cndmask_b32_e64 v31, v32, 0, s[92:93]
	v_cndmask_b32_e64 v32, v33, 0, s[94:95]
	v_cndmask_b32_e64 v11, v11, 0, vcc
	v_readlane_b32 vcc_lo, v254, 61
	v_readlane_b32 vcc_hi, v254, 62
	v_cndmask_b32_e64 v22, v22, 0, s[80:81]
	v_cndmask_b32_e64 v23, v23, 0, s[14:15]
	v_cndmask_b32_e64 v12, v12, 0, vcc
	v_readlane_b32 vcc_lo, v254, 49
	v_readlane_b32 vcc_hi, v254, 50
	v_cndmask_b32_e64 v24, v24, 0, s[84:85]
	v_cndmask_b32_e64 v25, v25, 0, s[86:87]
	v_cndmask_b32_e64 v6, v6, 0, vcc
	v_readlane_b32 vcc_lo, v254, 51
	v_readlane_b32 vcc_hi, v254, 52
	v_cndmask_b32_e64 v18, v18, 0, s[72:73]
	v_cndmask_b32_e64 v19, v19, 0, s[74:75]
	v_cndmask_b32_e64 v7, v7, 0, vcc
	v_readlane_b32 vcc_lo, v254, 53
	v_readlane_b32 vcc_hi, v254, 54
	v_cndmask_b32_e64 v20, v20, 0, s[76:77]
	v_cndmask_b32_e64 v21, v21, 0, s[78:79]
	v_cndmask_b32_e64 v8, v8, 0, vcc
	v_readlane_b32 vcc_lo, v254, 55
	v_readlane_b32 vcc_hi, v254, 56
	v_cndmask_b32_e64 v14, v14, 0, s[64:65]
	v_cndmask_b32_e64 v15, v15, 0, s[66:67]
	v_cndmask_b32_e64 v9, v9, 0, vcc
	v_readlane_b32 vcc_lo, v254, 39
	v_readlane_b32 vcc_hi, v254, 40
	v_cndmask_b32_e64 v16, v16, 0, s[68:69]
	v_cndmask_b32_e64 v17, v17, 0, s[70:71]
	v_cndmask_b32_e64 v2, v2, 0, vcc
	v_readlane_b32 vcc_lo, v254, 41
	v_readlane_b32 vcc_hi, v254, 42
	v_cndmask_b32_e64 v13, v13, 0, s[62:63]
	v_cndmask_b32_e64 v26, v26, 0, s[96:97]
	v_cndmask_b32_e32 v3, 0, v3, vcc
	v_readlane_b32 vcc_lo, v254, 43
	v_readlane_b32 vcc_hi, v254, 44
	v_cndmask_b32_e64 v27, v27, 0, s[4:5]
	v_cndmask_b32_e64 v28, v28, 0, s[6:7]
	v_cndmask_b32_e64 v4, v4, 0, vcc
	v_readlane_b32 vcc_lo, v254, 45
	v_readlane_b32 vcc_hi, v254, 46
	v_cndmask_b32_e64 v29, v29, 0, s[8:9]
	v_cvt_pk_bf16_f32 v146, v2, v3
	s_mov_b32 m0, s46
	v_cndmask_b32_e64 v5, v5, 0, vcc
	v_cvt_pk_bf16_f32 v147, v4, v5
	v_cvt_pk_bf16_f32 v148, v6, v7
	v_cvt_pk_bf16_f32 v149, v8, v9
	v_cvt_pk_bf16_f32 v174, v10, v11
	v_cvt_pk_bf16_f32 v175, v12, v13
	v_cvt_pk_bf16_f32 v176, v14, v15
	v_cvt_pk_bf16_f32 v177, v16, v17
	v_cvt_pk_bf16_f32 v170, v18, v19
	v_cvt_pk_bf16_f32 v171, v20, v21
	v_cvt_pk_bf16_f32 v172, v22, v23
	v_cvt_pk_bf16_f32 v173, v24, v25
	v_cvt_pk_bf16_f32 v166, v1, v30
	v_cvt_pk_bf16_f32 v167, v31, v32
	v_cvt_pk_bf16_f32 v168, v26, v27
	v_cvt_pk_bf16_f32 v169, v28, v29
	s_waitcnt vmcnt(0)
	s_mov_b64 vcc, 0x3600
	s_waitcnt lgkmcnt(0)
	s_barrier
	v_lshl_add_u64 v[2:3], v[66:67], 0, vcc
	s_mov_b64 vcc, 0x47600
	global_load_lds_dwordx4 v[2:3], off nt
	v_lshl_add_u64 v[2:3], v[66:67], 0, vcc
	s_mov_b32 m0, s53
	s_mov_b64 vcc, 0x8b600
	global_load_lds_dwordx4 v[2:3], off nt
	v_lshl_add_u64 v[2:3], v[66:67], 0, vcc
	s_mov_b32 m0, s52
	s_mov_b64 vcc, 0xcf600
	global_load_lds_dwordx4 v[2:3], off nt
	v_lshl_add_u64 v[2:3], v[66:67], 0, vcc
	s_mov_b32 m0, s55
	s_mov_b64 vcc, 0x113600
	global_load_lds_dwordx4 v[2:3], off nt
	v_lshl_add_u64 v[2:3], v[66:67], 0, vcc
	s_mov_b32 m0, s54
	s_mov_b64 vcc, 0x157600
	global_load_lds_dwordx4 v[2:3], off nt
	v_lshl_add_u64 v[2:3], v[66:67], 0, vcc
	s_mov_b32 m0, s57
	s_mov_b64 vcc, 0x19b600
	global_load_lds_dwordx4 v[2:3], off nt
	v_lshl_add_u64 v[2:3], v[66:67], 0, vcc
	s_mov_b32 m0, s56
	s_mov_b64 vcc, 0x1df600
	global_load_lds_dwordx4 v[2:3], off nt
	v_lshl_add_u64 v[2:3], v[66:67], 0, vcc
	s_mov_b32 m0, s59
	v_mov_b32_e32 v32, v0
	global_load_lds_dwordx4 v[2:3], off nt
	s_and_b64 vcc, exec, s[12:13]
	s_cbranch_vccnz .LBB0_487
	v_add_u32_e32 v1, 0x2000, v32
	v_add_u32_e32 v18, v32, v200
	v_add_u32_e32 v19, v1, v200
	v_add_u32_e32 v20, v32, v201
	v_add_u32_e32 v21, v1, v201
	v_add_u32_e32 v22, v32, v202
	v_add_u32_e32 v23, v1, v202
	v_add_u32_e32 v24, v32, v203
	v_add_u32_e32 v25, v1, v203
	ds_read_b64_tr_b16 v[14:15], v18
	ds_read_b64_tr_b16 v[16:17], v19
	ds_read_b64_tr_b16 v[10:11], v20
	ds_read_b64_tr_b16 v[12:13], v21
	ds_read_b64_tr_b16 v[6:7], v22
	ds_read_b64_tr_b16 v[8:9], v23
	ds_read_b64_tr_b16 v[2:3], v24
	ds_read_b64_tr_b16 v[4:5], v25
	s_waitcnt lgkmcnt(0)
	v_add_u32_e32 v70, v1, v205
	v_mfma_f32_16x16x32_bf16 v[16:19], v[146:149], v[14:17], 0
	v_add_u32_e32 v72, v1, v206
	v_add_u32_e32 v33, v32, v205
	v_add_u32_e32 v71, v32, v206
	v_mfma_f32_16x16x32_bf16 v[12:15], v[146:149], v[10:13], 0
	v_add_u32_e32 v73, v32, v207
	v_mfma_f32_16x16x32_bf16 v[8:11], v[146:149], v[6:9], 0
	v_mfma_f32_16x16x32_bf16 v[4:7], v[146:149], v[2:5], 0
	v_add_u32_e32 v3, v1, v204
	v_add_u32_e32 v1, v1, v207
	v_add_u32_e32 v2, v32, v204
	ds_read_b64_tr_b16 v[66:67], v2
	ds_read_b64_tr_b16 v[68:69], v3
	ds_read_b64_tr_b16 v[28:29], v33
	ds_read_b64_tr_b16 v[30:31], v70
	ds_read_b64_tr_b16 v[24:25], v71
	ds_read_b64_tr_b16 v[26:27], v72
	ds_read_b64_tr_b16 v[20:21], v73
	ds_read_b64_tr_b16 v[22:23], v1
	s_waitcnt lgkmcnt(0)
	v_add_u32_e32 v1, 0x100, v32
	v_add_u32_e32 v3, 0x2100, v32
	v_mfma_f32_16x16x32_bf16 v[162:165], v[146:149], v[66:69], 0
	v_add_u32_e32 v2, v1, v200
	v_add_u32_e32 v33, v3, v200
	v_add_u32_e32 v82, v1, v201
	v_add_u32_e32 v83, v3, v201
	v_add_u32_e32 v84, v1, v202
	v_add_u32_e32 v85, v3, v202
	v_add_u32_e32 v86, v1, v203
	v_add_u32_e32 v87, v3, v203
	ds_read_b64_tr_b16 v[78:79], v2
	ds_read_b64_tr_b16 v[80:81], v33
	ds_read_b64_tr_b16 v[74:75], v82
	ds_read_b64_tr_b16 v[76:77], v83
	ds_read_b64_tr_b16 v[70:71], v84
	ds_read_b64_tr_b16 v[72:73], v85
	ds_read_b64_tr_b16 v[66:67], v86
	ds_read_b64_tr_b16 v[68:69], v87
	s_waitcnt lgkmcnt(0)
	v_add_u32_e32 v2, v1, v204
	v_add_u32_e32 v33, v3, v204
	v_add_u32_e32 v98, v1, v205
	v_add_u32_e32 v99, v3, v205
	v_add_u32_e32 v100, v1, v206
	v_add_u32_e32 v101, v3, v206
	v_add_u32_e32 v1, v1, v207
	v_add_u32_e32 v3, v3, v207
	ds_read_b64_tr_b16 v[94:95], v2
	ds_read_b64_tr_b16 v[96:97], v33
	ds_read_b64_tr_b16 v[90:91], v98
	ds_read_b64_tr_b16 v[92:93], v99
	ds_read_b64_tr_b16 v[86:87], v100
	ds_read_b64_tr_b16 v[88:89], v101
	ds_read_b64_tr_b16 v[82:83], v1
	ds_read_b64_tr_b16 v[84:85], v3
	s_waitcnt lgkmcnt(0)
	v_mfma_f32_16x16x32_bf16 v[28:31], v[146:149], v[28:31], 0
	v_mfma_f32_16x16x32_bf16 v[24:27], v[146:149], v[24:27], 0
	v_mfma_f32_16x16x32_bf16 v[20:23], v[146:149], v[20:23], 0
	v_mfma_f32_16x16x32_bf16 v[78:81], v[146:149], v[78:81], 0
	v_mfma_f32_16x16x32_bf16 v[74:77], v[146:149], v[74:77], 0
	v_mfma_f32_16x16x32_bf16 v[70:73], v[146:149], v[70:73], 0
	v_mfma_f32_16x16x32_bf16 v[66:69], v[146:149], v[66:69], 0
	v_mfma_f32_16x16x32_bf16 v[94:97], v[146:149], v[94:97], 0
	v_mfma_f32_16x16x32_bf16 v[90:93], v[146:149], v[90:93], 0
	v_mfma_f32_16x16x32_bf16 v[86:89], v[146:149], v[86:89], 0
	v_mfma_f32_16x16x32_bf16 v[82:85], v[146:149], v[82:85], 0
	s_and_b64 vcc, exec, s[10:11]
	s_cbranch_vccz .LBB0_488
	s_branch .LBB0_489

; #define MFMA16(a, b, c) __builtin_amdgcn_mfma_f32_16x16x32_bf16((a), (b), (c), 0, 0, 0)
; #define WAITV0() asm volatile("s_waitcnt vmcnt(0)" ::: "memory")
; #define LBAR() do { asm volatile("s_waitcnt lgkmcnt(0)" ::: "memory"); __builtin_amdgcn_s_barrier(); asm volatile("" ::: "memory"); } while (0)
; __device__ __forceinline__ void retc_stream(const int wv, LAS unsigned char* lds, unsigned ldsb, const float* __restrict__ gn_g, const float* __restrict__ gn_b, const bf16_t* __restrict__ qkvr, const bf16_t* __restrict__ grb, const bf16_t* __restrict__ kv, ...
;     ...
;         for (int vh = 0; vh < 2; ++vh) {
;             WAITV0(); LBAR(); RETC_ISSUE(item, 3 + vh);
;             unsigned imgb = ldsb + vh * 65536u; asm volatile("" : "+v"(imgb));
; #pragma unroll
;             for (int u = 0; u < 4; ++u) {
;                 if (2 * u <= w) {
;                     const unsigned a0 = imgb + u * 16384u, a1 = a0 + 8192u;
; #pragma unroll
;                     for (int c = 0; c < 16; c += 4) {
;                         bf16x8 v0, v1, v2, v3;
;                         const unsigned hi = (c >> 3) * 256u;
;                         tr_frag4x(a0 + hi + toff[c & 7], a1 + hi + toff[c & 7], a0 + hi + toff[(c & 7) + 1], a1 + hi + toff[(c & 7) + 1],
;                                   a0 + hi + toff[(c & 7) + 2], a1 + hi + toff[(c & 7) + 2], a0 + hi + toff[(c & 7) + 3], a1 + hi + toff[(c & 7) + 3], v0, v1, v2, v3);
;                         acc[vh * 16 + c] = MFMA16(pf[u], v0, acc[vh * 16 + c]); acc[vh * 16 + c + 1] = MFMA16(pf[u], v1, acc[vh * 16 + c + 1]);
;                         acc[vh * 16 + c + 2] = MFMA16(pf[u], v2, acc[vh * 16 + c + 2]); acc[vh * 16 + c + 3] = MFMA16(pf[u], v3, acc[vh * 16 + c + 3]);
;                     }
;                 }
.LBB0_492:
	s_waitcnt vmcnt(0)
	s_mov_b32 m0, s58
	s_waitcnt lgkmcnt(0)
	s_barrier
	s_mov_b64 vcc, 0x2000
	global_load_lds_dwordx4 v[182:183], off nt
	v_lshl_add_u64 v[2:3], v[182:183], 0, vcc
	s_mov_b32 m0, s47
	s_mov_b64 vcc, 0x4000
	global_load_lds_dwordx4 v[2:3], off nt
	v_lshl_add_u64 v[2:3], v[182:183], 0, vcc
	s_mov_b32 m0, s24
	s_mov_b64 vcc, 0x6000
	global_load_lds_dwordx4 v[2:3], off nt
	v_lshl_add_u64 v[2:3], v[182:183], 0, vcc
	s_mov_b32 m0, s25
	s_mov_b64 vcc, 0x8000
	global_load_lds_dwordx4 v[2:3], off nt
	v_lshl_add_u64 v[2:3], v[182:183], 0, vcc
	s_mov_b32 m0, s48
	s_mov_b64 vcc, 0xa000
	global_load_lds_dwordx4 v[2:3], off nt
	v_lshl_add_u64 v[2:3], v[182:183], 0, vcc
	s_mov_b32 m0, s49
	s_mov_b64 vcc, 0xc000
	global_load_lds_dwordx4 v[2:3], off nt
	v_lshl_add_u64 v[2:3], v[182:183], 0, vcc
	s_mov_b32 m0, s50
	s_mov_b64 vcc, 0xe000
	global_load_lds_dwordx4 v[2:3], off nt
	v_lshl_add_u64 v[2:3], v[182:183], 0, vcc
	s_mov_b32 m0, s51
	s_add_i32 s41, 0, 0x10000
	global_load_lds_dwordx4 v[2:3], off nt
	v_mov_b32_e32 v32, s41
	s_and_b64 vcc, exec, s[12:13]
	s_cbranch_vccnz .LBB0_495
	v_add_u32_e32 v1, 0x2000, v32
	v_add_u32_e32 v3, v1, v200
	v_add_u32_e32 v2, v32, v200
	v_add_u32_e32 v33, v32, v201
	v_add_u32_e32 v114, v1, v201
	v_add_u32_e32 v115, v32, v202
	v_add_u32_e32 v116, v1, v202
	v_add_u32_e32 v117, v32, v203
	v_add_u32_e32 v118, v1, v203
	ds_read_b64_tr_b16 v[110:111], v2
	ds_read_b64_tr_b16 v[112:113], v3
	ds_read_b64_tr_b16 v[106:107], v33
	ds_read_b64_tr_b16 v[108:109], v114
	ds_read_b64_tr_b16 v[102:103], v115
	ds_read_b64_tr_b16 v[104:105], v116
	ds_read_b64_tr_b16 v[98:99], v117
	ds_read_b64_tr_b16 v[100:101], v118
	s_waitcnt lgkmcnt(0)
	v_add_u32_e32 v3, v1, v204
	v_add_u32_e32 v130, v1, v205
	v_add_u32_e32 v132, v1, v206
	v_add_u32_e32 v1, v1, v207
	v_add_u32_e32 v2, v32, v204
	v_add_u32_e32 v33, v32, v205
	v_add_u32_e32 v131, v32, v206
	v_add_u32_e32 v133, v32, v207
	ds_read_b64_tr_b16 v[126:127], v2
	ds_read_b64_tr_b16 v[128:129], v3
	ds_read_b64_tr_b16 v[122:123], v33
	ds_read_b64_tr_b16 v[124:125], v130
	ds_read_b64_tr_b16 v[118:119], v131
	ds_read_b64_tr_b16 v[120:121], v132
	ds_read_b64_tr_b16 v[114:115], v133
	ds_read_b64_tr_b16 v[116:117], v1
	s_waitcnt lgkmcnt(0)
	v_add_u32_e32 v1, 0x100, v32
	v_add_u32_e32 v3, 0x2100, v32
	v_add_u32_e32 v2, v1, v200
	v_add_u32_e32 v33, v3, v200
	v_add_u32_e32 v150, v1, v201
	v_add_u32_e32 v151, v3, v201
	v_add_u32_e32 v152, v1, v202
	v_add_u32_e32 v153, v3, v202
	v_add_u32_e32 v154, v1, v203
	v_add_u32_e32 v155, v3, v203
	ds_read_b64_tr_b16 v[142:143], v2
	ds_read_b64_tr_b16 v[144:145], v33
	ds_read_b64_tr_b16 v[138:139], v150
	ds_read_b64_tr_b16 v[140:141], v151
	ds_read_b64_tr_b16 v[134:135], v152
	ds_read_b64_tr_b16 v[136:137], v153
	ds_read_b64_tr_b16 v[130:131], v154
	ds_read_b64_tr_b16 v[132:133], v155
	s_waitcnt lgkmcnt(0)
	v_add_u32_e32 v2, v1, v204
	v_add_u32_e32 v33, v3, v204
	v_add_u32_e32 v226, v1, v205
	v_add_u32_e32 v227, v3, v205
	v_add_u32_e32 v228, v1, v206
	v_add_u32_e32 v229, v3, v206
	v_add_u32_e32 v1, v1, v207
	v_add_u32_e32 v3, v3, v207
	ds_read_b64_tr_b16 v[158:159], v2
	ds_read_b64_tr_b16 v[160:161], v33
	ds_read_b64_tr_b16 v[154:155], v226
	ds_read_b64_tr_b16 v[156:157], v227
	ds_read_b64_tr_b16 v[150:151], v228
	ds_read_b64_tr_b16 v[152:153], v229
	ds_read_b64_tr_b16 v[222:223], v1
	ds_read_b64_tr_b16 v[224:225], v3
	s_waitcnt lgkmcnt(0)
	v_mfma_f32_16x16x32_bf16 v[110:113], v[146:149], v[110:113], 0
	v_mfma_f32_16x16x32_bf16 v[106:109], v[146:149], v[106:109], 0
	v_mfma_f32_16x16x32_bf16 v[102:105], v[146:149], v[102:105], 0
	v_mfma_f32_16x16x32_bf16 v[98:101], v[146:149], v[98:101], 0
	v_mfma_f32_16x16x32_bf16 v[126:129], v[146:149], v[126:129], 0
	v_mfma_f32_16x16x32_bf16 v[122:125], v[146:149], v[122:125], 0
	v_mfma_f32_16x16x32_bf16 v[118:121], v[146:149], v[118:121], 0
	v_mfma_f32_16x16x32_bf16 v[114:117], v[146:149], v[114:117], 0
	v_mfma_f32_16x16x32_bf16 v[142:145], v[146:149], v[142:145], 0
	v_mfma_f32_16x16x32_bf16 v[138:141], v[146:149], v[138:141], 0
	v_mfma_f32_16x16x32_bf16 v[134:137], v[146:149], v[134:137], 0
	v_mfma_f32_16x16x32_bf16 v[130:133], v[146:149], v[130:133], 0
	v_mfma_f32_16x16x32_bf16 v[158:161], v[146:149], v[158:161], 0
	v_mfma_f32_16x16x32_bf16 v[154:157], v[146:149], v[154:157], 0
	v_mfma_f32_16x16x32_bf16 v[150:153], v[146:149], v[150:153], 0
	v_mfma_f32_16x16x32_bf16 v[146:149], v[146:149], v[222:225], 0
	s_and_b64 vcc, exec, s[10:11]
	s_cbranch_vccz .LBB0_496
	s_branch .LBB0_497

; #define LAS __attribute__((address_space(3)))
; #define MFMA16(a, b, c) __builtin_amdgcn_mfma_f32_16x16x32_bf16((a), (b), (c), 0, 0, 0)
; #define WAITV0() asm volatile("s_waitcnt vmcnt(0)" ::: "memory")
; #define LBAR() do { asm volatile("s_waitcnt lgkmcnt(0)" ::: "memory"); __builtin_amdgcn_s_barrier(); asm volatile("" ::: "memory"); } while (0)
; __device__ __forceinline__ void retc_stream(const int wv, LAS unsigned char* lds, unsigned ldsb, const float* __restrict__ gn_g, const float* __restrict__ gn_b, const bf16_t* __restrict__ qkvr, const bf16_t* __restrict__ grb, const bf16_t* __restrict__ kv, ...
;     ...
;         const float lg2 = log2f(1.0f - exp2f(-5.0f - (float)h));
;         WAITV0(); LBAR(); RETC_ISSUE(item, 1);
;     ...
; #pragma unroll
;         for (int vc = 0; vc < 4; ++vc) {
;             WAITV0(); LBAR();
;             if (vc < 3) RETC_ISSUE(item, 5 + vc);
;             unsigned img = (vc & 1) * 65536u; asm volatile("" : "+v"(img));
; #pragma unroll
;             for (int s = 0; s < 8; ++s) {
;                 bf16x8 bfr[8];
; #pragma unroll
;                 for (int c = 0; c < 8; ++c) bfr[c] = *(const LAS bf16x8*)(lds + img + c * 8192 + koff[s]);
;                 asm volatile("s_waitcnt lgkmcnt(0)" ::: "memory");
; #pragma unroll
;                 for (int c = 0; c < 8; ++c) acc[vc * 8 + c] = MFMA16(qf[s], bfr[c], acc[vc * 8 + c]);
;             }
.LBB0_500:
	v_cvt_f32_i32_e32 v1, s40
	s_mov_b32 s41, 0xc2fc0000
	s_waitcnt vmcnt(0)
	s_waitcnt lgkmcnt(0)
	v_sub_f32_e32 v1, 0xc0a00000, v1
	v_cmp_gt_f32_e32 vcc, s41, v1
	s_and_b64 s[0:1], vcc, exec
	s_cselect_b32 s0, 0xffffffc0, 0
	v_cndmask_b32_e32 v2, 0, v187, vcc
	v_add_f32_e32 v1, v1, v2
	v_exp_f32_e32 v1, v1
	s_barrier
	s_mov_b32 m0, s46
	v_ldexp_f32 v1, v1, s0
	v_sub_f32_e32 v1, 1.0, v1
	v_cmp_gt_f32_e32 vcc, s36, v1
	s_and_b64 s[0:1], vcc, exec
	s_cselect_b32 s0, 32, 0
	v_ldexp_f32 v1, v1, s0
	v_log_f32_e32 v1, v1
	v_readlane_b32 s0, v254, 2
	v_readlane_b32 s1, v254, 3
	v_cndmask_b32_e32 v2, 0, v190, vcc
	s_add_i32 s28, s28, s0
	s_mov_b64 s[0:1], 0x10000
	v_sub_f32_e32 v1, v1, v2
	v_lshl_add_u64 v[2:3], v[182:183], 0, s[0:1]
	s_mov_b64 s[0:1], 0x12000
	global_load_lds_dwordx4 v[2:3], off nt
	v_lshl_add_u64 v[2:3], v[182:183], 0, s[0:1]
	s_mov_b32 m0, s53
	s_mov_b64 s[0:1], 0x14000
	global_load_lds_dwordx4 v[2:3], off nt
	v_lshl_add_u64 v[2:3], v[182:183], 0, s[0:1]
	s_mov_b32 m0, s52
	s_mov_b64 s[0:1], 0x16000
	global_load_lds_dwordx4 v[2:3], off nt
	v_lshl_add_u64 v[2:3], v[182:183], 0, s[0:1]
	s_mov_b32 m0, s55
	s_mov_b64 s[0:1], 0x18000
	global_load_lds_dwordx4 v[2:3], off nt
	v_lshl_add_u64 v[2:3], v[182:183], 0, s[0:1]
	s_mov_b32 m0, s54
	s_mov_b64 s[0:1], 0x1a000
	global_load_lds_dwordx4 v[2:3], off nt
	v_lshl_add_u64 v[2:3], v[182:183], 0, s[0:1]
	s_mov_b32 m0, s57
	s_mov_b64 s[0:1], 0x1c000
	global_load_lds_dwordx4 v[2:3], off nt
	v_lshl_add_u64 v[2:3], v[182:183], 0, s[0:1]
	s_mov_b32 m0, s56
	s_mov_b64 s[0:1], 0x1e000
	global_load_lds_dwordx4 v[2:3], off nt
	v_lshl_add_u64 v[2:3], v[182:183], 0, s[0:1]
	s_mov_b32 m0, s59
	s_mov_b64 s[0:1], 0x20000
	global_load_lds_dwordx4 v[2:3], off nt
	v_mov_b32_e32 v2, v0
	s_mov_b32 m0, s58
	v_add_u32_e32 v242, 0, v2
	v_add_u32_e32 v2, v242, v192
	ds_read_b128 v[166:169], v2
	ds_read_b128 v[170:173], v2 offset:8192
	ds_read_b128 v[174:177], v2 offset:16384
	ds_read_b128 v[222:225], v2 offset:24576
	ds_read_b128 v[226:229], v2 offset:32768
	ds_read_b128 v[230:233], v2 offset:40960
	ds_read_b128 v[234:237], v2 offset:49152
	ds_read_b128 v[238:241], v2 offset:57344
	s_waitcnt lgkmcnt(0)
	s_waitcnt lgkmcnt(0)
	v_mfma_f32_16x16x32_bf16 v[2:5], v[62:65], v[222:225], v[4:7]
	s_lshl_b32 s2, s40, 9
	s_mov_b32 s40, 0x3b000000
	s_ashr_i32 s3, s2, 31
	v_add_u32_e32 v6, v242, v193
	v_mfma_f32_16x16x32_bf16 v[16:19], v[62:65], v[166:169], v[16:19]
	s_lshl_b64 s[12:13], s[2:3], 2
	s_add_u32 s10, s16, s12
	s_addc_u32 s11, s17, s13
	v_mfma_f32_16x16x32_bf16 v[12:15], v[62:65], v[170:173], v[12:15]
	s_lshl_b32 s29, s29, 7
	v_mfma_f32_16x16x32_bf16 v[8:11], v[62:65], v[174:177], v[8:11]
	v_mfma_f32_16x16x32_bf16 v[162:165], v[62:65], v[226:229], v[162:165]
	v_mfma_f32_16x16x32_bf16 v[28:31], v[62:65], v[230:233], v[28:31]
	v_mfma_f32_16x16x32_bf16 v[24:27], v[62:65], v[234:237], v[24:27]
	v_mfma_f32_16x16x32_bf16 v[20:23], v[62:65], v[238:241], v[20:23]
	ds_read_b128 v[166:169], v6
	ds_read_b128 v[170:173], v6 offset:8192
	ds_read_b128 v[174:177], v6 offset:16384
	ds_read_b128 v[222:225], v6 offset:24576
	ds_read_b128 v[226:229], v6 offset:32768
	ds_read_b128 v[230:233], v6 offset:40960
	ds_read_b128 v[234:237], v6 offset:49152
	ds_read_b128 v[238:241], v6 offset:57344
	s_waitcnt lgkmcnt(0)
	s_waitcnt lgkmcnt(0)
	v_mfma_f32_16x16x32_bf16 v[6:9], v[58:61], v[174:177], v[8:11]
	s_nop 2
	v_add_u32_e32 v10, v242, v194
	v_mfma_f32_16x16x32_bf16 v[16:19], v[58:61], v[166:169], v[16:19]
	v_mfma_f32_16x16x32_bf16 v[12:15], v[58:61], v[170:173], v[12:15]
	v_mfma_f32_16x16x32_bf16 v[2:5], v[58:61], v[222:225], v[2:5]
	v_mfma_f32_16x16x32_bf16 v[162:165], v[58:61], v[226:229], v[162:165]
	v_mfma_f32_16x16x32_bf16 v[28:31], v[58:61], v[230:233], v[28:31]
	v_mfma_f32_16x16x32_bf16 v[24:27], v[58:61], v[234:237], v[24:27]
	v_mfma_f32_16x16x32_bf16 v[20:23], v[58:61], v[238:241], v[20:23]
	ds_read_b128 v[166:169], v10
	ds_read_b128 v[170:173], v10 offset:8192
	ds_read_b128 v[174:177], v10 offset:16384
	ds_read_b128 v[222:225], v10 offset:24576
	ds_read_b128 v[226:229], v10 offset:32768
	ds_read_b128 v[230:233], v10 offset:40960
	ds_read_b128 v[234:237], v10 offset:49152
	ds_read_b128 v[238:241], v10 offset:57344
	s_waitcnt lgkmcnt(0)
	s_waitcnt lgkmcnt(0)
	v_mfma_f32_16x16x32_bf16 v[10:13], v[54:57], v[170:173], v[12:15]
	s_nop 2
	v_add_u32_e32 v14, v242, v195
	v_mfma_f32_16x16x32_bf16 v[16:19], v[54:57], v[166:169], v[16:19]
	v_mfma_f32_16x16x32_bf16 v[6:9], v[54:57], v[174:177], v[6:9]
	v_mfma_f32_16x16x32_bf16 v[2:5], v[54:57], v[222:225], v[2:5]
	v_mfma_f32_16x16x32_bf16 v[162:165], v[54:57], v[226:229], v[162:165]
	v_mfma_f32_16x16x32_bf16 v[28:31], v[54:57], v[230:233], v[28:31]
	v_mfma_f32_16x16x32_bf16 v[24:27], v[54:57], v[234:237], v[24:27]
	v_mfma_f32_16x16x32_bf16 v[20:23], v[54:57], v[238:241], v[20:23]
	ds_read_b128 v[166:169], v14
	ds_read_b128 v[170:173], v14 offset:8192
	ds_read_b128 v[174:177], v14 offset:16384
	ds_read_b128 v[222:225], v14 offset:24576
	ds_read_b128 v[226:229], v14 offset:32768
	ds_read_b128 v[230:233], v14 offset:40960
	ds_read_b128 v[234:237], v14 offset:49152
	ds_read_b128 v[238:241], v14 offset:57344
	s_waitcnt lgkmcnt(0)
	s_waitcnt lgkmcnt(0)
; #define LAS __attribute__((address_space(3)))
; #define MFMA16(a, b, c) __builtin_amdgcn_mfma_f32_16x16x32_bf16((a), (b), (c), 0, 0, 0)
; #define WAITV0() asm volatile("s_waitcnt vmcnt(0)" ::: "memory")
; #define LBAR() do { asm volatile("s_waitcnt lgkmcnt(0)" ::: "memory"); __builtin_amdgcn_s_barrier(); asm volatile("" ::: "memory"); } while (0)
; __device__ __forceinline__ void retc_stream(const int wv, LAS unsigned char* lds, unsigned ldsb, const float* __restrict__ gn_g, const float* __restrict__ gn_b, const bf16_t* __restrict__ qkvr, const bf16_t* __restrict__ grb, const bf16_t* __restrict__ kv, ...
;     ...
; #pragma unroll
;         for (int vc = 0; vc < 4; ++vc) {
;             WAITV0(); LBAR();
;             if (vc < 3) RETC_ISSUE(item, 5 + vc);
;             unsigned img = (vc & 1) * 65536u; asm volatile("" : "+v"(img));
; #pragma unroll
;             for (int s = 0; s < 8; ++s) {
;                 bf16x8 bfr[8];
; #pragma unroll
;                 for (int c = 0; c < 8; ++c) bfr[c] = *(const LAS bf16x8*)(lds + img + c * 8192 + koff[s]);
;                 asm volatile("s_waitcnt lgkmcnt(0)" ::: "memory");
; #pragma unroll
;                 for (int c = 0; c < 8; ++c) acc[vc * 8 + c] = MFMA16(qf[s], bfr[c], acc[vc * 8 + c]);
;             }
	v_mfma_f32_16x16x32_bf16 v[14:17], v[50:53], v[166:169], v[16:19]
	v_mfma_f32_16x16x32_bf16 v[18:21], v[50:53], v[238:241], v[20:23]
	s_nop 2
	v_add_u32_e32 v22, v242, v196
	v_mfma_f32_16x16x32_bf16 v[10:13], v[50:53], v[170:173], v[10:13]
	v_mfma_f32_16x16x32_bf16 v[6:9], v[50:53], v[174:177], v[6:9]
	v_mfma_f32_16x16x32_bf16 v[2:5], v[50:53], v[222:225], v[2:5]
	v_mfma_f32_16x16x32_bf16 v[162:165], v[50:53], v[226:229], v[162:165]
	v_mfma_f32_16x16x32_bf16 v[28:31], v[50:53], v[230:233], v[28:31]
	v_mfma_f32_16x16x32_bf16 v[24:27], v[50:53], v[234:237], v[24:27]
	ds_read_b128 v[166:169], v22
	ds_read_b128 v[170:173], v22 offset:8192
	ds_read_b128 v[174:177], v22 offset:16384
	ds_read_b128 v[222:225], v22 offset:24576
	ds_read_b128 v[226:229], v22 offset:32768
	ds_read_b128 v[230:233], v22 offset:40960
	ds_read_b128 v[234:237], v22 offset:49152
	ds_read_b128 v[238:241], v22 offset:57344
	s_waitcnt lgkmcnt(0)
	s_waitcnt lgkmcnt(0)
	v_mfma_f32_16x16x32_bf16 v[22:25], v[46:49], v[234:237], v[24:27]
	s_nop 2
	v_add_u32_e32 v26, v242, v197
	v_mfma_f32_16x16x32_bf16 v[14:17], v[46:49], v[166:169], v[14:17]
	v_mfma_f32_16x16x32_bf16 v[10:13], v[46:49], v[170:173], v[10:13]
	v_mfma_f32_16x16x32_bf16 v[6:9], v[46:49], v[174:177], v[6:9]
	v_mfma_f32_16x16x32_bf16 v[2:5], v[46:49], v[222:225], v[2:5]
	v_mfma_f32_16x16x32_bf16 v[162:165], v[46:49], v[226:229], v[162:165]
	v_mfma_f32_16x16x32_bf16 v[28:31], v[46:49], v[230:233], v[28:31]
	v_mfma_f32_16x16x32_bf16 v[18:21], v[46:49], v[238:241], v[18:21]
	ds_read_b128 v[166:169], v26
	ds_read_b128 v[170:173], v26 offset:8192
	ds_read_b128 v[174:177], v26 offset:16384
	ds_read_b128 v[222:225], v26 offset:24576
	ds_read_b128 v[226:229], v26 offset:32768
	ds_read_b128 v[230:233], v26 offset:40960
	ds_read_b128 v[234:237], v26 offset:49152
	ds_read_b128 v[238:241], v26 offset:57344
	s_waitcnt lgkmcnt(0)
	s_waitcnt lgkmcnt(0)
	v_mfma_f32_16x16x32_bf16 v[14:17], v[42:45], v[166:169], v[14:17]
	v_mfma_f32_16x16x32_bf16 v[162:165], v[42:45], v[226:229], v[162:165]
	v_mfma_f32_16x16x32_bf16 v[22:25], v[42:45], v[234:237], v[22:25]
	v_add_u32_e32 v234, v242, v198
	v_mfma_f32_16x16x32_bf16 v[10:13], v[42:45], v[170:173], v[10:13]
	v_mfma_f32_16x16x32_bf16 v[6:9], v[42:45], v[174:177], v[6:9]
	v_mfma_f32_16x16x32_bf16 v[2:5], v[42:45], v[222:225], v[2:5]
	v_mfma_f32_16x16x32_bf16 v[26:29], v[42:45], v[230:233], v[28:31]
	s_nop 2
	ds_read_b128 v[30:33], v234
	ds_read_b128 v[166:169], v234 offset:8192
	ds_read_b128 v[170:173], v234 offset:16384
	ds_read_b128 v[174:177], v234 offset:24576
	ds_read_b128 v[222:225], v234 offset:32768
	ds_read_b128 v[226:229], v234 offset:40960
	ds_read_b128 v[230:233], v234 offset:49152
	ds_read_b128 v[234:237], v234 offset:57344
	s_waitcnt lgkmcnt(0)
	v_mfma_f32_16x16x32_bf16 v[18:21], v[42:45], v[238:241], v[18:21]
	s_waitcnt lgkmcnt(0)
	v_mfma_f32_16x16x32_bf16 v[14:17], v[38:41], v[30:33], v[14:17]
	v_mfma_f32_16x16x32_bf16 v[162:165], v[38:41], v[222:225], v[162:165]
	v_mfma_f32_16x16x32_bf16 v[10:13], v[38:41], v[166:169], v[10:13]
	v_mfma_f32_16x16x32_bf16 v[166:169], v[38:41], v[226:229], v[26:29]
	s_nop 2
	v_add_u32_e32 v26, v242, v199
	v_mfma_f32_16x16x32_bf16 v[6:9], v[38:41], v[170:173], v[6:9]
	v_mfma_f32_16x16x32_bf16 v[2:5], v[38:41], v[174:177], v[2:5]
	v_mfma_f32_16x16x32_bf16 v[170:173], v[38:41], v[230:233], v[22:25]
	v_mfma_f32_16x16x32_bf16 v[174:177], v[38:41], v[234:237], v[18:21]
	s_nop 2
	ds_read_b128 v[18:21], v26
	ds_read_b128 v[22:25], v26 offset:8192
	ds_read_b128 v[222:225], v26 offset:16384
	ds_read_b128 v[226:229], v26 offset:24576
	ds_read_b128 v[230:233], v26 offset:32768
	ds_read_b128 v[234:237], v26 offset:40960
	ds_read_b128 v[238:241], v26 offset:49152
	ds_read_b128 v[242:245], v26 offset:57344
	s_waitcnt lgkmcnt(0)
	s_waitcnt vmcnt(0)
	s_waitcnt lgkmcnt(0)
	v_mfma_f32_16x16x32_bf16 v[26:29], v[34:37], v[18:21], v[14:17]
	s_waitcnt lgkmcnt(0)
	s_barrier
	v_mfma_f32_16x16x32_bf16 v[14:17], v[34:37], v[230:233], v[162:165]
	s_nop 2
	v_lshl_add_u64 v[162:163], v[182:183], 0, s[0:1]
	s_mov_b64 s[0:1], 0x22000
	global_load_lds_dwordx4 v[162:163], off nt
	v_lshl_add_u64 v[162:163], v[182:183], 0, s[0:1]
	s_mov_b32 m0, s47
	s_mov_b64 s[0:1], 0x24000
	global_load_lds_dwordx4 v[162:163], off nt
	v_lshl_add_u64 v[162:163], v[182:183], 0, s[0:1]
	s_mov_b32 m0, s24
	s_mov_b64 s[0:1], 0x26000
	global_load_lds_dwordx4 v[162:163], off nt
	v_lshl_add_u64 v[162:163], v[182:183], 0, s[0:1]
	s_mov_b32 m0, s25
	s_mov_b64 s[0:1], 0x28000
	global_load_lds_dwordx4 v[162:163], off nt
	v_lshl_add_u64 v[162:163], v[182:183], 0, s[0:1]
	s_mov_b32 m0, s48
	s_mov_b64 s[0:1], 0x2a000
	global_load_lds_dwordx4 v[162:163], off nt
	v_lshl_add_u64 v[162:163], v[182:183], 0, s[0:1]
	s_mov_b32 m0, s49
	s_mov_b64 s[0:1], 0x2c000
	global_load_lds_dwordx4 v[162:163], off nt
	v_lshl_add_u64 v[162:163], v[182:183], 0, s[0:1]
	s_mov_b32 m0, s50
	s_mov_b64 s[0:1], 0x2e000
	global_load_lds_dwordx4 v[162:163], off nt
	v_lshl_add_u64 v[162:163], v[182:183], 0, s[0:1]
	s_mov_b32 m0, s51
	v_mfma_f32_16x16x32_bf16 v[30:33], v[34:37], v[22:25], v[10:13]
	global_load_lds_dwordx4 v[162:163], off nt
	v_mov_b32_e32 v162, 0x10000
	v_mfma_f32_16x16x32_bf16 v[22:25], v[34:37], v[222:225], v[6:9]
	s_mov_b64 s[0:1], 0x30000
	s_mov_b32 m0, s46
	v_mfma_f32_16x16x32_bf16 v[6:9], v[34:37], v[238:241], v[170:173]
	v_add_u32_e32 v238, 0, v162
	v_mfma_f32_16x16x32_bf16 v[10:13], v[34:37], v[234:237], v[166:169]
	v_add_u32_e32 v234, v238, v192
	v_mfma_f32_16x16x32_bf16 v[18:21], v[34:37], v[226:229], v[2:5]
	v_mfma_f32_16x16x32_bf16 v[2:5], v[34:37], v[242:245], v[174:177]
	ds_read_b128 v[162:165], v234
	ds_read_b128 v[166:169], v234 offset:8192
	ds_read_b128 v[170:173], v234 offset:16384
	ds_read_b128 v[174:177], v234 offset:24576
	ds_read_b128 v[222:225], v234 offset:32768
	ds_read_b128 v[226:229], v234 offset:40960
	ds_read_b128 v[230:233], v234 offset:49152
	ds_read_b128 v[234:237], v234 offset:57344
	s_waitcnt lgkmcnt(0)
; #define LAS __attribute__((address_space(3)))
; #define MFMA16(a, b, c) __builtin_amdgcn_mfma_f32_16x16x32_bf16((a), (b), (c), 0, 0, 0)
; #define WAITV0() asm volatile("s_waitcnt vmcnt(0)" ::: "memory")
; #define LBAR() do { asm volatile("s_waitcnt lgkmcnt(0)" ::: "memory"); __builtin_amdgcn_s_barrier(); asm volatile("" ::: "memory"); } while (0)
; __device__ __forceinline__ void retc_stream(const int wv, LAS unsigned char* lds, unsigned ldsb, const float* __restrict__ gn_g, const float* __restrict__ gn_b, const bf16_t* __restrict__ qkvr, const bf16_t* __restrict__ grb, const bf16_t* __restrict__ kv, ...
;     ...
; #pragma unroll
;         for (int vc = 0; vc < 4; ++vc) {
;             WAITV0(); LBAR();
;             if (vc < 3) RETC_ISSUE(item, 5 + vc);
;             unsigned img = (vc & 1) * 65536u; asm volatile("" : "+v"(img));
; #pragma unroll
;             for (int s = 0; s < 8; ++s) {
;                 bf16x8 bfr[8];
; #pragma unroll
;                 for (int c = 0; c < 8; ++c) bfr[c] = *(const LAS bf16x8*)(lds + img + c * 8192 + koff[s]);
;                 asm volatile("s_waitcnt lgkmcnt(0)" ::: "memory");
; #pragma unroll
;                 for (int c = 0; c < 8; ++c) acc[vc * 8 + c] = MFMA16(qf[s], bfr[c], acc[vc * 8 + c]);
;             }
	s_waitcnt lgkmcnt(0)
	v_mfma_f32_16x16x32_bf16 v[82:85], v[62:65], v[234:237], v[82:85]
	v_add_u32_e32 v234, v238, v193
	v_mfma_f32_16x16x32_bf16 v[78:81], v[62:65], v[162:165], v[78:81]
	v_mfma_f32_16x16x32_bf16 v[74:77], v[62:65], v[166:169], v[74:77]
	v_mfma_f32_16x16x32_bf16 v[70:73], v[62:65], v[170:173], v[70:73]
	v_mfma_f32_16x16x32_bf16 v[66:69], v[62:65], v[174:177], v[66:69]
	v_mfma_f32_16x16x32_bf16 v[94:97], v[62:65], v[222:225], v[94:97]
	v_mfma_f32_16x16x32_bf16 v[90:93], v[62:65], v[226:229], v[90:93]
	v_mfma_f32_16x16x32_bf16 v[86:89], v[62:65], v[230:233], v[86:89]
	ds_read_b128 v[162:165], v234
	ds_read_b128 v[166:169], v234 offset:8192
	ds_read_b128 v[170:173], v234 offset:16384
	ds_read_b128 v[174:177], v234 offset:24576
	ds_read_b128 v[222:225], v234 offset:32768
	ds_read_b128 v[226:229], v234 offset:40960
	ds_read_b128 v[230:233], v234 offset:49152
	ds_read_b128 v[234:237], v234 offset:57344
	s_waitcnt lgkmcnt(0)
	s_waitcnt lgkmcnt(0)
	v_mfma_f32_16x16x32_bf16 v[82:85], v[58:61], v[234:237], v[82:85]
	v_add_u32_e32 v234, v238, v194
	v_mfma_f32_16x16x32_bf16 v[78:81], v[58:61], v[162:165], v[78:81]
	v_mfma_f32_16x16x32_bf16 v[74:77], v[58:61], v[166:169], v[74:77]
	v_mfma_f32_16x16x32_bf16 v[70:73], v[58:61], v[170:173], v[70:73]
	v_mfma_f32_16x16x32_bf16 v[66:69], v[58:61], v[174:177], v[66:69]
	v_mfma_f32_16x16x32_bf16 v[94:97], v[58:61], v[222:225], v[94:97]
	v_mfma_f32_16x16x32_bf16 v[90:93], v[58:61], v[226:229], v[90:93]
	v_mfma_f32_16x16x32_bf16 v[86:89], v[58:61], v[230:233], v[86:89]
	ds_read_b128 v[162:165], v234
	ds_read_b128 v[166:169], v234 offset:8192
	ds_read_b128 v[170:173], v234 offset:16384
	ds_read_b128 v[174:177], v234 offset:24576
	ds_read_b128 v[222:225], v234 offset:32768
	ds_read_b128 v[226:229], v234 offset:40960
	ds_read_b128 v[230:233], v234 offset:49152
	ds_read_b128 v[234:237], v234 offset:57344
	s_waitcnt lgkmcnt(0)
	s_waitcnt lgkmcnt(0)
	v_mfma_f32_16x16x32_bf16 v[82:85], v[54:57], v[234:237], v[82:85]
	v_add_u32_e32 v234, v238, v195
	v_mfma_f32_16x16x32_bf16 v[78:81], v[54:57], v[162:165], v[78:81]
	v_mfma_f32_16x16x32_bf16 v[74:77], v[54:57], v[166:169], v[74:77]
	v_mfma_f32_16x16x32_bf16 v[70:73], v[54:57], v[170:173], v[70:73]
	v_mfma_f32_16x16x32_bf16 v[66:69], v[54:57], v[174:177], v[66:69]
	v_mfma_f32_16x16x32_bf16 v[94:97], v[54:57], v[222:225], v[94:97]
	v_mfma_f32_16x16x32_bf16 v[90:93], v[54:57], v[226:229], v[90:93]
	v_mfma_f32_16x16x32_bf16 v[86:89], v[54:57], v[230:233], v[86:89]
	ds_read_b128 v[162:165], v234
	ds_read_b128 v[166:169], v234 offset:8192
	ds_read_b128 v[170:173], v234 offset:16384
	ds_read_b128 v[174:177], v234 offset:24576
	ds_read_b128 v[222:225], v234 offset:32768
	ds_read_b128 v[226:229], v234 offset:40960
	ds_read_b128 v[230:233], v234 offset:49152
	ds_read_b128 v[234:237], v234 offset:57344
	s_waitcnt lgkmcnt(0)
	s_waitcnt lgkmcnt(0)
	v_mfma_f32_16x16x32_bf16 v[82:85], v[50:53], v[234:237], v[82:85]
	v_add_u32_e32 v234, v238, v196
	v_mfma_f32_16x16x32_bf16 v[78:81], v[50:53], v[162:165], v[78:81]
	v_mfma_f32_16x16x32_bf16 v[74:77], v[50:53], v[166:169], v[74:77]
	v_mfma_f32_16x16x32_bf16 v[70:73], v[50:53], v[170:173], v[70:73]
	v_mfma_f32_16x16x32_bf16 v[66:69], v[50:53], v[174:177], v[66:69]
	v_mfma_f32_16x16x32_bf16 v[94:97], v[50:53], v[222:225], v[94:97]
	v_mfma_f32_16x16x32_bf16 v[90:93], v[50:53], v[226:229], v[90:93]
	v_mfma_f32_16x16x32_bf16 v[86:89], v[50:53], v[230:233], v[86:89]
	ds_read_b128 v[162:165], v234
	ds_read_b128 v[166:169], v234 offset:8192
	ds_read_b128 v[170:173], v234 offset:16384
	ds_read_b128 v[174:177], v234 offset:24576
	ds_read_b128 v[222:225], v234 offset:32768
	ds_read_b128 v[226:229], v234 offset:40960
	ds_read_b128 v[230:233], v234 offset:49152
	ds_read_b128 v[234:237], v234 offset:57344
	s_waitcnt lgkmcnt(0)
	s_waitcnt lgkmcnt(0)
	v_mfma_f32_16x16x32_bf16 v[82:85], v[46:49], v[234:237], v[82:85]
	v_add_u32_e32 v234, v238, v197
	v_mfma_f32_16x16x32_bf16 v[78:81], v[46:49], v[162:165], v[78:81]
	v_mfma_f32_16x16x32_bf16 v[74:77], v[46:49], v[166:169], v[74:77]
	v_mfma_f32_16x16x32_bf16 v[70:73], v[46:49], v[170:173], v[70:73]
	v_mfma_f32_16x16x32_bf16 v[66:69], v[46:49], v[174:177], v[66:69]
	v_mfma_f32_16x16x32_bf16 v[94:97], v[46:49], v[222:225], v[94:97]
	v_mfma_f32_16x16x32_bf16 v[90:93], v[46:49], v[226:229], v[90:93]
	v_mfma_f32_16x16x32_bf16 v[86:89], v[46:49], v[230:233], v[86:89]
	ds_read_b128 v[162:165], v234
	ds_read_b128 v[166:169], v234 offset:8192
	ds_read_b128 v[170:173], v234 offset:16384
	ds_read_b128 v[174:177], v234 offset:24576
	ds_read_b128 v[222:225], v234 offset:32768
	ds_read_b128 v[226:229], v234 offset:40960
	ds_read_b128 v[230:233], v234 offset:49152
	ds_read_b128 v[234:237], v234 offset:57344
	s_waitcnt lgkmcnt(0)
	s_waitcnt lgkmcnt(0)
	v_mfma_f32_16x16x32_bf16 v[78:81], v[42:45], v[162:165], v[78:81]
	v_mfma_f32_16x16x32_bf16 v[94:97], v[42:45], v[222:225], v[94:97]
	v_mfma_f32_16x16x32_bf16 v[82:85], v[42:45], v[234:237], v[82:85]
	v_add_u32_e32 v234, v238, v198
	v_mfma_f32_16x16x32_bf16 v[74:77], v[42:45], v[166:169], v[74:77]
	v_mfma_f32_16x16x32_bf16 v[70:73], v[42:45], v[170:173], v[70:73]
	v_mfma_f32_16x16x32_bf16 v[66:69], v[42:45], v[174:177], v[66:69]
	v_mfma_f32_16x16x32_bf16 v[90:93], v[42:45], v[226:229], v[90:93]
	v_mfma_f32_16x16x32_bf16 v[86:89], v[42:45], v[230:233], v[86:89]
	ds_read_b128 v[162:165], v234
	ds_read_b128 v[166:169], v234 offset:8192
	ds_read_b128 v[170:173], v234 offset:16384
	ds_read_b128 v[174:177], v234 offset:24576
	ds_read_b128 v[222:225], v234 offset:32768
	ds_read_b128 v[226:229], v234 offset:40960
	ds_read_b128 v[230:233], v234 offset:49152
	ds_read_b128 v[234:237], v234 offset:57344
	s_waitcnt lgkmcnt(0)
	s_waitcnt lgkmcnt(0)
	v_mfma_f32_16x16x32_bf16 v[78:81], v[38:41], v[162:165], v[78:81]
	v_mfma_f32_16x16x32_bf16 v[162:165], v[38:41], v[222:225], v[94:97]
	v_mfma_f32_16x16x32_bf16 v[74:77], v[38:41], v[166:169], v[74:77]
	v_mfma_f32_16x16x32_bf16 v[166:169], v[38:41], v[226:229], v[90:93]
	s_nop 2
	v_add_u32_e32 v90, v238, v199
	v_mfma_f32_16x16x32_bf16 v[70:73], v[38:41], v[170:173], v[70:73]
	v_mfma_f32_16x16x32_bf16 v[66:69], v[38:41], v[174:177], v[66:69]
	v_mfma_f32_16x16x32_bf16 v[170:173], v[38:41], v[230:233], v[86:89]
	v_mfma_f32_16x16x32_bf16 v[174:177], v[38:41], v[234:237], v[82:85]
	s_nop 2
	ds_read_b128 v[82:85], v90
	ds_read_b128 v[86:89], v90 offset:8192
	ds_read_b128 v[222:225], v90 offset:16384
	ds_read_b128 v[226:229], v90 offset:24576
	ds_read_b128 v[230:233], v90 offset:32768
	ds_read_b128 v[234:237], v90 offset:40960
	ds_read_b128 v[238:241], v90 offset:49152
	ds_read_b128 v[242:245], v90 offset:57344
	s_waitcnt lgkmcnt(0)
	s_waitcnt vmcnt(0)
	s_waitcnt lgkmcnt(0)
	v_mfma_f32_16x16x32_bf16 v[94:97], v[34:37], v[82:85], v[78:81]
	s_waitcnt lgkmcnt(0)
	s_barrier
; #define LAS __attribute__((address_space(3)))
; #define MFMA16(a, b, c) __builtin_amdgcn_mfma_f32_16x16x32_bf16((a), (b), (c), 0, 0, 0)
; #define WAITV0() asm volatile("s_waitcnt vmcnt(0)" ::: "memory")
; #define LBAR() do { asm volatile("s_waitcnt lgkmcnt(0)" ::: "memory"); __builtin_amdgcn_s_barrier(); asm volatile("" ::: "memory"); } while (0)
; __device__ __forceinline__ void retc_stream(const int wv, LAS unsigned char* lds, unsigned ldsb, const float* __restrict__ gn_g, const float* __restrict__ gn_b, const bf16_t* __restrict__ qkvr, const bf16_t* __restrict__ grb, const bf16_t* __restrict__ kv, ...
;     ...
; #pragma unroll
;         for (int vc = 0; vc < 4; ++vc) {
;             WAITV0(); LBAR();
;             if (vc < 3) RETC_ISSUE(item, 5 + vc);
;             unsigned img = (vc & 1) * 65536u; asm volatile("" : "+v"(img));
; #pragma unroll
;             for (int s = 0; s < 8; ++s) {
;                 bf16x8 bfr[8];
; #pragma unroll
;                 for (int c = 0; c < 8; ++c) bfr[c] = *(const LAS bf16x8*)(lds + img + c * 8192 + koff[s]);
;                 asm volatile("s_waitcnt lgkmcnt(0)" ::: "memory");
; #pragma unroll
;                 for (int c = 0; c < 8; ++c) acc[vc * 8 + c] = MFMA16(qf[s], bfr[c], acc[vc * 8 + c]);
;             }
	v_mfma_f32_16x16x32_bf16 v[78:81], v[34:37], v[230:233], v[162:165]
	s_nop 2
	v_lshl_add_u64 v[162:163], v[182:183], 0, s[0:1]
	s_mov_b64 s[0:1], 0x32000
	global_load_lds_dwordx4 v[162:163], off nt
	v_lshl_add_u64 v[162:163], v[182:183], 0, s[0:1]
	s_mov_b32 m0, s53
	s_mov_b64 s[0:1], 0x34000
	global_load_lds_dwordx4 v[162:163], off nt
	v_lshl_add_u64 v[162:163], v[182:183], 0, s[0:1]
	s_mov_b32 m0, s52
	s_mov_b64 s[0:1], 0x36000
	global_load_lds_dwordx4 v[162:163], off nt
	v_lshl_add_u64 v[162:163], v[182:183], 0, s[0:1]
	s_mov_b32 m0, s55
	s_mov_b64 s[0:1], 0x38000
	global_load_lds_dwordx4 v[162:163], off nt
	v_lshl_add_u64 v[162:163], v[182:183], 0, s[0:1]
	s_mov_b32 m0, s54
	s_mov_b64 s[0:1], 0x3a000
	global_load_lds_dwordx4 v[162:163], off nt
	v_lshl_add_u64 v[162:163], v[182:183], 0, s[0:1]
	s_mov_b32 m0, s57
	s_mov_b64 s[0:1], 0x3c000
	global_load_lds_dwordx4 v[162:163], off nt
	v_lshl_add_u64 v[162:163], v[182:183], 0, s[0:1]
	s_mov_b32 m0, s56
	s_mov_b64 s[0:1], 0x3e000
	global_load_lds_dwordx4 v[162:163], off nt
	v_lshl_add_u64 v[162:163], v[182:183], 0, s[0:1]
	s_mov_b32 m0, s59
	v_mfma_f32_16x16x32_bf16 v[90:93], v[34:37], v[86:89], v[74:77]
	global_load_lds_dwordx4 v[162:163], off nt
	v_mov_b32_e32 v162, v0
	v_mfma_f32_16x16x32_bf16 v[86:89], v[34:37], v[222:225], v[70:73]
	s_mov_b32 s0, 0x358637bd
	v_mfma_f32_16x16x32_bf16 v[70:73], v[34:37], v[238:241], v[170:173]
	v_add_u32_e32 v238, 0, v162
	v_mfma_f32_16x16x32_bf16 v[74:77], v[34:37], v[234:237], v[166:169]
	v_add_u32_e32 v234, v238, v192
	v_mfma_f32_16x16x32_bf16 v[82:85], v[34:37], v[226:229], v[66:69]
	v_mfma_f32_16x16x32_bf16 v[66:69], v[34:37], v[242:245], v[174:177]
	ds_read_b128 v[162:165], v234
	ds_read_b128 v[166:169], v234 offset:8192
	ds_read_b128 v[170:173], v234 offset:16384
	ds_read_b128 v[174:177], v234 offset:24576
	ds_read_b128 v[222:225], v234 offset:32768
	ds_read_b128 v[226:229], v234 offset:40960
	ds_read_b128 v[230:233], v234 offset:49152
	ds_read_b128 v[234:237], v234 offset:57344
	s_waitcnt lgkmcnt(0)
	s_waitcnt lgkmcnt(0)
	v_mfma_f32_16x16x32_bf16 v[114:117], v[62:65], v[234:237], v[114:117]
	v_add_u32_e32 v234, v238, v193
	v_mfma_f32_16x16x32_bf16 v[110:113], v[62:65], v[162:165], v[110:113]
	v_mfma_f32_16x16x32_bf16 v[106:109], v[62:65], v[166:169], v[106:109]
	v_mfma_f32_16x16x32_bf16 v[102:105], v[62:65], v[170:173], v[102:105]
	v_mfma_f32_16x16x32_bf16 v[98:101], v[62:65], v[174:177], v[98:101]
	v_mfma_f32_16x16x32_bf16 v[126:129], v[62:65], v[222:225], v[126:129]
	v_mfma_f32_16x16x32_bf16 v[122:125], v[62:65], v[226:229], v[122:125]
	v_mfma_f32_16x16x32_bf16 v[118:121], v[62:65], v[230:233], v[118:121]
	ds_read_b128 v[162:165], v234
	ds_read_b128 v[166:169], v234 offset:8192
	ds_read_b128 v[170:173], v234 offset:16384
	ds_read_b128 v[174:177], v234 offset:24576
	ds_read_b128 v[222:225], v234 offset:32768
	ds_read_b128 v[226:229], v234 offset:40960
	ds_read_b128 v[230:233], v234 offset:49152
	ds_read_b128 v[234:237], v234 offset:57344
	s_waitcnt lgkmcnt(0)
	s_waitcnt lgkmcnt(0)
	v_mfma_f32_16x16x32_bf16 v[114:117], v[58:61], v[234:237], v[114:117]
	v_add_u32_e32 v234, v238, v194
	v_mfma_f32_16x16x32_bf16 v[110:113], v[58:61], v[162:165], v[110:113]
	v_mfma_f32_16x16x32_bf16 v[106:109], v[58:61], v[166:169], v[106:109]
	v_mfma_f32_16x16x32_bf16 v[102:105], v[58:61], v[170:173], v[102:105]
	v_mfma_f32_16x16x32_bf16 v[98:101], v[58:61], v[174:177], v[98:101]
	v_mfma_f32_16x16x32_bf16 v[126:129], v[58:61], v[222:225], v[126:129]
	v_mfma_f32_16x16x32_bf16 v[122:125], v[58:61], v[226:229], v[122:125]
	v_mfma_f32_16x16x32_bf16 v[118:121], v[58:61], v[230:233], v[118:121]
	ds_read_b128 v[162:165], v234
	ds_read_b128 v[166:169], v234 offset:8192
	ds_read_b128 v[170:173], v234 offset:16384
	ds_read_b128 v[174:177], v234 offset:24576
	ds_read_b128 v[222:225], v234 offset:32768
	ds_read_b128 v[226:229], v234 offset:40960
	ds_read_b128 v[230:233], v234 offset:49152
	ds_read_b128 v[234:237], v234 offset:57344
	s_waitcnt lgkmcnt(0)
	s_waitcnt lgkmcnt(0)
	v_mfma_f32_16x16x32_bf16 v[114:117], v[54:57], v[234:237], v[114:117]
	v_add_u32_e32 v234, v238, v195
	v_mfma_f32_16x16x32_bf16 v[110:113], v[54:57], v[162:165], v[110:113]
	v_mfma_f32_16x16x32_bf16 v[106:109], v[54:57], v[166:169], v[106:109]
	v_mfma_f32_16x16x32_bf16 v[102:105], v[54:57], v[170:173], v[102:105]
	v_mfma_f32_16x16x32_bf16 v[98:101], v[54:57], v[174:177], v[98:101]
	v_mfma_f32_16x16x32_bf16 v[126:129], v[54:57], v[222:225], v[126:129]
	v_mfma_f32_16x16x32_bf16 v[122:125], v[54:57], v[226:229], v[122:125]
	v_mfma_f32_16x16x32_bf16 v[118:121], v[54:57], v[230:233], v[118:121]
	ds_read_b128 v[162:165], v234
	ds_read_b128 v[166:169], v234 offset:8192
	ds_read_b128 v[170:173], v234 offset:16384
	ds_read_b128 v[174:177], v234 offset:24576
	ds_read_b128 v[222:225], v234 offset:32768
	ds_read_b128 v[226:229], v234 offset:40960
	ds_read_b128 v[230:233], v234 offset:49152
	ds_read_b128 v[234:237], v234 offset:57344
	s_waitcnt lgkmcnt(0)
	s_waitcnt lgkmcnt(0)
	v_mfma_f32_16x16x32_bf16 v[114:117], v[50:53], v[234:237], v[114:117]
	v_add_u32_e32 v234, v238, v196
	v_mfma_f32_16x16x32_bf16 v[110:113], v[50:53], v[162:165], v[110:113]
	v_mfma_f32_16x16x32_bf16 v[106:109], v[50:53], v[166:169], v[106:109]
	v_mfma_f32_16x16x32_bf16 v[102:105], v[50:53], v[170:173], v[102:105]
	v_mfma_f32_16x16x32_bf16 v[98:101], v[50:53], v[174:177], v[98:101]
	v_mfma_f32_16x16x32_bf16 v[126:129], v[50:53], v[222:225], v[126:129]
	v_mfma_f32_16x16x32_bf16 v[122:125], v[50:53], v[226:229], v[122:125]
	v_mfma_f32_16x16x32_bf16 v[118:121], v[50:53], v[230:233], v[118:121]
	ds_read_b128 v[162:165], v234
	ds_read_b128 v[166:169], v234 offset:8192
	ds_read_b128 v[170:173], v234 offset:16384
	ds_read_b128 v[174:177], v234 offset:24576
	ds_read_b128 v[222:225], v234 offset:32768
	ds_read_b128 v[226:229], v234 offset:40960
	ds_read_b128 v[230:233], v234 offset:49152
	ds_read_b128 v[234:237], v234 offset:57344
	s_waitcnt lgkmcnt(0)
; #define LAS __attribute__((address_space(3)))
; #define MFMA16(a, b, c) __builtin_amdgcn_mfma_f32_16x16x32_bf16((a), (b), (c), 0, 0, 0)
; #define WAITV0() asm volatile("s_waitcnt vmcnt(0)" ::: "memory")
; #define LBAR() do { asm volatile("s_waitcnt lgkmcnt(0)" ::: "memory"); __builtin_amdgcn_s_barrier(); asm volatile("" ::: "memory"); } while (0)
; __device__ __forceinline__ void retc_stream(const int wv, LAS unsigned char* lds, unsigned ldsb, const float* __restrict__ gn_g, const float* __restrict__ gn_b, const bf16_t* __restrict__ qkvr, const bf16_t* __restrict__ grb, const bf16_t* __restrict__ kv, ...
;     ...
; #pragma unroll
;         for (int vc = 0; vc < 4; ++vc) {
;             WAITV0(); LBAR();
;             if (vc < 3) RETC_ISSUE(item, 5 + vc);
;             unsigned img = (vc & 1) * 65536u; asm volatile("" : "+v"(img));
; #pragma unroll
;             for (int s = 0; s < 8; ++s) {
;                 bf16x8 bfr[8];
; #pragma unroll
;                 for (int c = 0; c < 8; ++c) bfr[c] = *(const LAS bf16x8*)(lds + img + c * 8192 + koff[s]);
;                 asm volatile("s_waitcnt lgkmcnt(0)" ::: "memory");
; #pragma unroll
;                 for (int c = 0; c < 8; ++c) acc[vc * 8 + c] = MFMA16(qf[s], bfr[c], acc[vc * 8 + c]);
;             }
	s_waitcnt lgkmcnt(0)
	v_mfma_f32_16x16x32_bf16 v[114:117], v[46:49], v[234:237], v[114:117]
	v_add_u32_e32 v234, v238, v197
	v_mfma_f32_16x16x32_bf16 v[110:113], v[46:49], v[162:165], v[110:113]
	v_mfma_f32_16x16x32_bf16 v[106:109], v[46:49], v[166:169], v[106:109]
	v_mfma_f32_16x16x32_bf16 v[102:105], v[46:49], v[170:173], v[102:105]
	v_mfma_f32_16x16x32_bf16 v[98:101], v[46:49], v[174:177], v[98:101]
	v_mfma_f32_16x16x32_bf16 v[126:129], v[46:49], v[222:225], v[126:129]
	v_mfma_f32_16x16x32_bf16 v[122:125], v[46:49], v[226:229], v[122:125]
	v_mfma_f32_16x16x32_bf16 v[118:121], v[46:49], v[230:233], v[118:121]
	ds_read_b128 v[162:165], v234
	ds_read_b128 v[166:169], v234 offset:8192
	ds_read_b128 v[170:173], v234 offset:16384
	ds_read_b128 v[174:177], v234 offset:24576
	ds_read_b128 v[222:225], v234 offset:32768
	ds_read_b128 v[226:229], v234 offset:40960
	ds_read_b128 v[230:233], v234 offset:49152
	ds_read_b128 v[234:237], v234 offset:57344
	s_waitcnt lgkmcnt(0)
	s_waitcnt lgkmcnt(0)
	v_mfma_f32_16x16x32_bf16 v[114:117], v[42:45], v[234:237], v[114:117]
	v_add_u32_e32 v234, v238, v198
	v_mfma_f32_16x16x32_bf16 v[110:113], v[42:45], v[162:165], v[110:113]
	v_mfma_f32_16x16x32_bf16 v[106:109], v[42:45], v[166:169], v[106:109]
	v_mfma_f32_16x16x32_bf16 v[102:105], v[42:45], v[170:173], v[102:105]
	v_mfma_f32_16x16x32_bf16 v[98:101], v[42:45], v[174:177], v[98:101]
	v_mfma_f32_16x16x32_bf16 v[126:129], v[42:45], v[222:225], v[126:129]
	v_mfma_f32_16x16x32_bf16 v[122:125], v[42:45], v[226:229], v[122:125]
	v_mfma_f32_16x16x32_bf16 v[118:121], v[42:45], v[230:233], v[118:121]
	ds_read_b128 v[162:165], v234
	ds_read_b128 v[166:169], v234 offset:8192
	ds_read_b128 v[170:173], v234 offset:16384
	ds_read_b128 v[174:177], v234 offset:24576
	ds_read_b128 v[222:225], v234 offset:32768
	ds_read_b128 v[226:229], v234 offset:40960
	ds_read_b128 v[230:233], v234 offset:49152
	ds_read_b128 v[234:237], v234 offset:57344
	s_waitcnt lgkmcnt(0)
	s_waitcnt lgkmcnt(0)
	v_mfma_f32_16x16x32_bf16 v[110:113], v[38:41], v[162:165], v[110:113]
	v_mfma_f32_16x16x32_bf16 v[106:109], v[38:41], v[166:169], v[106:109]
	v_mfma_f32_16x16x32_bf16 v[162:165], v[38:41], v[170:173], v[102:105]
	s_nop 2
	v_add_u32_e32 v102, v238, v199
	v_mfma_f32_16x16x32_bf16 v[166:169], v[38:41], v[174:177], v[98:101]
	v_mfma_f32_16x16x32_bf16 v[170:173], v[38:41], v[222:225], v[126:129]
	v_mfma_f32_16x16x32_bf16 v[174:177], v[38:41], v[226:229], v[122:125]
	v_mfma_f32_16x16x32_bf16 v[222:225], v[38:41], v[230:233], v[118:121]
	v_mfma_f32_16x16x32_bf16 v[226:229], v[38:41], v[234:237], v[114:117]
	ds_read_b128 v[98:101], v102
	s_nop 1
	ds_read_b128 v[114:117], v102 offset:8192
	ds_read_b128 v[118:121], v102 offset:16384
	ds_read_b128 v[122:125], v102 offset:24576
	ds_read_b128 v[230:233], v102 offset:32768
	ds_read_b128 v[234:237], v102 offset:40960
	ds_read_b128 v[238:241], v102 offset:49152
	ds_read_b128 v[242:245], v102 offset:57344
	s_waitcnt lgkmcnt(0)
	s_waitcnt vmcnt(0)
	s_waitcnt lgkmcnt(0)
	v_mfma_f32_16x16x32_bf16 v[102:105], v[34:37], v[98:101], v[110:113]
	s_waitcnt lgkmcnt(0)
	s_barrier
	v_mfma_f32_16x16x32_bf16 v[98:101], v[34:37], v[114:117], v[106:109]
	v_mfma_f32_16x16x32_bf16 v[106:109], v[34:37], v[118:121], v[162:165]
	s_nop 2
	v_mov_b32_e32 v162, 0x10000
	v_mfma_f32_16x16x32_bf16 v[114:117], v[34:37], v[238:241], v[222:225]
	s_nop 0
	v_add_u32_e32 v238, 0, v162
	v_mfma_f32_16x16x32_bf16 v[118:121], v[34:37], v[234:237], v[174:177]
	v_add_u32_e32 v234, v238, v192
	v_mfma_f32_16x16x32_bf16 v[126:129], v[34:37], v[122:125], v[166:169]
	v_mfma_f32_16x16x32_bf16 v[122:125], v[34:37], v[230:233], v[170:173]
	v_mfma_f32_16x16x32_bf16 v[110:113], v[34:37], v[242:245], v[226:229]
	ds_read_b128 v[162:165], v234
	ds_read_b128 v[166:169], v234 offset:8192
	ds_read_b128 v[170:173], v234 offset:16384
	ds_read_b128 v[174:177], v234 offset:24576
	ds_read_b128 v[222:225], v234 offset:32768
	ds_read_b128 v[226:229], v234 offset:40960
	ds_read_b128 v[230:233], v234 offset:49152
	ds_read_b128 v[234:237], v234 offset:57344
	s_waitcnt lgkmcnt(0)
	s_waitcnt lgkmcnt(0)
	v_mfma_f32_16x16x32_bf16 v[150:153], v[62:65], v[230:233], v[150:153]
	v_add_u32_e32 v230, v238, v193
	v_mfma_f32_16x16x32_bf16 v[142:145], v[62:65], v[162:165], v[142:145]
	v_mfma_f32_16x16x32_bf16 v[138:141], v[62:65], v[166:169], v[138:141]
	v_mfma_f32_16x16x32_bf16 v[134:137], v[62:65], v[170:173], v[134:137]
	v_mfma_f32_16x16x32_bf16 v[130:133], v[62:65], v[174:177], v[130:133]
	v_mfma_f32_16x16x32_bf16 v[158:161], v[62:65], v[222:225], v[158:161]
	v_mfma_f32_16x16x32_bf16 v[154:157], v[62:65], v[226:229], v[154:157]
	v_mfma_f32_16x16x32_bf16 v[62:65], v[62:65], v[234:237], v[146:149]
	s_nop 2
	ds_read_b128 v[146:149], v230
	ds_read_b128 v[162:165], v230 offset:8192
	ds_read_b128 v[166:169], v230 offset:16384
	ds_read_b128 v[170:173], v230 offset:24576
	ds_read_b128 v[174:177], v230 offset:32768
	ds_read_b128 v[222:225], v230 offset:40960
	ds_read_b128 v[226:229], v230 offset:49152
	ds_read_b128 v[230:233], v230 offset:57344
	s_waitcnt lgkmcnt(0)
	s_waitcnt lgkmcnt(0)
	v_mfma_f32_16x16x32_bf16 v[150:153], v[58:61], v[226:229], v[150:153]
	v_add_u32_e32 v226, v238, v194
	v_mfma_f32_16x16x32_bf16 v[142:145], v[58:61], v[146:149], v[142:145]
	v_mfma_f32_16x16x32_bf16 v[138:141], v[58:61], v[162:165], v[138:141]
	v_mfma_f32_16x16x32_bf16 v[134:137], v[58:61], v[166:169], v[134:137]
	v_mfma_f32_16x16x32_bf16 v[130:133], v[58:61], v[170:173], v[130:133]
	v_mfma_f32_16x16x32_bf16 v[146:149], v[58:61], v[174:177], v[158:161]
	v_mfma_f32_16x16x32_bf16 v[154:157], v[58:61], v[222:225], v[154:157]
	v_mfma_f32_16x16x32_bf16 v[58:61], v[58:61], v[230:233], v[62:65]
	s_nop 2
	ds_read_b128 v[62:65], v226
	ds_read_b128 v[158:161], v226 offset:8192
	ds_read_b128 v[162:165], v226 offset:16384
	ds_read_b128 v[166:169], v226 offset:24576
	ds_read_b128 v[170:173], v226 offset:32768
	ds_read_b128 v[174:177], v226 offset:40960
	ds_read_b128 v[222:225], v226 offset:49152
	ds_read_b128 v[226:229], v226 offset:57344
	s_waitcnt lgkmcnt(0)
; #define LAS __attribute__((address_space(3)))
; #define MFMA16(a, b, c) __builtin_amdgcn_mfma_f32_16x16x32_bf16((a), (b), (c), 0, 0, 0)
; #define WAITV0() asm volatile("s_waitcnt vmcnt(0)" ::: "memory")
; #define LBAR() do { asm volatile("s_waitcnt lgkmcnt(0)" ::: "memory"); __builtin_amdgcn_s_barrier(); asm volatile("" ::: "memory"); } while (0)
; __device__ __forceinline__ void retc_stream(const int wv, LAS unsigned char* lds, unsigned ldsb, const float* __restrict__ gn_g, const float* __restrict__ gn_b, const bf16_t* __restrict__ qkvr, const bf16_t* __restrict__ grb, const bf16_t* __restrict__ kv, ...
;     ...
; #pragma unroll
;         for (int vc = 0; vc < 4; ++vc) {
;             WAITV0(); LBAR();
;             if (vc < 3) RETC_ISSUE(item, 5 + vc);
;             unsigned img = (vc & 1) * 65536u; asm volatile("" : "+v"(img));
; #pragma unroll
;             for (int s = 0; s < 8; ++s) {
;                 bf16x8 bfr[8];
; #pragma unroll
;                 for (int c = 0; c < 8; ++c) bfr[c] = *(const LAS bf16x8*)(lds + img + c * 8192 + koff[s]);
;                 asm volatile("s_waitcnt lgkmcnt(0)" ::: "memory");
; #pragma unroll
;                 for (int c = 0; c < 8; ++c) acc[vc * 8 + c] = MFMA16(qf[s], bfr[c], acc[vc * 8 + c]);
;             }
	s_waitcnt lgkmcnt(0)
	v_mfma_f32_16x16x32_bf16 v[150:153], v[54:57], v[222:225], v[150:153]
	v_add_u32_e32 v222, v238, v195
	v_mfma_f32_16x16x32_bf16 v[62:65], v[54:57], v[62:65], v[142:145]
	v_mfma_f32_16x16x32_bf16 v[138:141], v[54:57], v[158:161], v[138:141]
	v_mfma_f32_16x16x32_bf16 v[134:137], v[54:57], v[162:165], v[134:137]
	v_mfma_f32_16x16x32_bf16 v[130:133], v[54:57], v[166:169], v[130:133]
	v_mfma_f32_16x16x32_bf16 v[142:145], v[54:57], v[170:173], v[146:149]
	v_mfma_f32_16x16x32_bf16 v[146:149], v[54:57], v[174:177], v[154:157]
	v_mfma_f32_16x16x32_bf16 v[54:57], v[54:57], v[226:229], v[58:61]
	s_nop 2
	ds_read_b128 v[58:61], v222
	ds_read_b128 v[154:157], v222 offset:8192
	ds_read_b128 v[158:161], v222 offset:16384
	ds_read_b128 v[162:165], v222 offset:24576
	ds_read_b128 v[166:169], v222 offset:32768
	ds_read_b128 v[170:173], v222 offset:40960
	ds_read_b128 v[174:177], v222 offset:49152
	ds_read_b128 v[222:225], v222 offset:57344
	s_waitcnt lgkmcnt(0)
	s_waitcnt lgkmcnt(0)
	v_mfma_f32_16x16x32_bf16 v[58:61], v[50:53], v[58:61], v[62:65]
	v_mfma_f32_16x16x32_bf16 v[62:65], v[50:53], v[154:157], v[138:141]
	v_mfma_f32_16x16x32_bf16 v[138:141], v[50:53], v[166:169], v[142:145]
	v_mfma_f32_16x16x32_bf16 v[142:145], v[50:53], v[170:173], v[146:149]
	v_mfma_f32_16x16x32_bf16 v[146:149], v[50:53], v[174:177], v[150:153]
	v_add_u32_e32 v174, v238, v196
	v_mfma_f32_16x16x32_bf16 v[134:137], v[50:53], v[158:161], v[134:137]
	v_mfma_f32_16x16x32_bf16 v[130:133], v[50:53], v[162:165], v[130:133]
	v_mfma_f32_16x16x32_bf16 v[50:53], v[50:53], v[222:225], v[54:57]
	s_nop 2
	ds_read_b128 v[54:57], v174
	ds_read_b128 v[150:153], v174 offset:8192
	ds_read_b128 v[154:157], v174 offset:16384
	ds_read_b128 v[158:161], v174 offset:24576
	ds_read_b128 v[162:165], v174 offset:32768
	ds_read_b128 v[166:169], v174 offset:40960
	ds_read_b128 v[170:173], v174 offset:49152
	ds_read_b128 v[174:177], v174 offset:57344
	s_waitcnt lgkmcnt(0)
	s_waitcnt lgkmcnt(0)
	v_mfma_f32_16x16x32_bf16 v[54:57], v[46:49], v[54:57], v[58:61]
	v_mfma_f32_16x16x32_bf16 v[58:61], v[46:49], v[150:153], v[62:65]
	v_mfma_f32_16x16x32_bf16 v[62:65], v[46:49], v[154:157], v[134:137]
	v_mfma_f32_16x16x32_bf16 v[134:137], v[46:49], v[162:165], v[138:141]
	v_mfma_f32_16x16x32_bf16 v[138:141], v[46:49], v[166:169], v[142:145]
	v_mfma_f32_16x16x32_bf16 v[142:145], v[46:49], v[170:173], v[146:149]
	v_add_u32_e32 v170, v238, v197
	v_mfma_f32_16x16x32_bf16 v[130:133], v[46:49], v[158:161], v[130:133]
	v_mfma_f32_16x16x32_bf16 v[46:49], v[46:49], v[174:177], v[50:53]
	s_nop 2
	ds_read_b128 v[50:53], v170
	ds_read_b128 v[146:149], v170 offset:8192
	ds_read_b128 v[150:153], v170 offset:16384
	ds_read_b128 v[154:157], v170 offset:24576
	ds_read_b128 v[158:161], v170 offset:32768
	ds_read_b128 v[162:165], v170 offset:40960
	ds_read_b128 v[166:169], v170 offset:49152
	ds_read_b128 v[170:173], v170 offset:57344
	s_waitcnt lgkmcnt(0)
	s_waitcnt lgkmcnt(0)
	v_mfma_f32_16x16x32_bf16 v[50:53], v[42:45], v[50:53], v[54:57]
	v_mfma_f32_16x16x32_bf16 v[54:57], v[42:45], v[146:149], v[58:61]
	v_mfma_f32_16x16x32_bf16 v[58:61], v[42:45], v[150:153], v[62:65]
	v_mfma_f32_16x16x32_bf16 v[62:65], v[42:45], v[154:157], v[130:133]
	v_mfma_f32_16x16x32_bf16 v[130:133], v[42:45], v[158:161], v[134:137]
	v_mfma_f32_16x16x32_bf16 v[134:137], v[42:45], v[162:165], v[138:141]
	v_mfma_f32_16x16x32_bf16 v[138:141], v[42:45], v[166:169], v[142:145]
	v_add_u32_e32 v166, v238, v198
	v_mfma_f32_16x16x32_bf16 v[42:45], v[42:45], v[170:173], v[46:49]
	s_nop 2
	ds_read_b128 v[46:49], v166
	ds_read_b128 v[142:145], v166 offset:8192
	ds_read_b128 v[146:149], v166 offset:16384
	ds_read_b128 v[150:153], v166 offset:24576
	ds_read_b128 v[154:157], v166 offset:32768
	ds_read_b128 v[158:161], v166 offset:40960
	ds_read_b128 v[162:165], v166 offset:49152
	ds_read_b128 v[166:169], v166 offset:57344
	s_waitcnt lgkmcnt(0)
	s_waitcnt lgkmcnt(0)
	v_mfma_f32_16x16x32_bf16 v[46:49], v[38:41], v[46:49], v[50:53]
	v_mfma_f32_16x16x32_bf16 v[50:53], v[38:41], v[142:145], v[54:57]
	v_mfma_f32_16x16x32_bf16 v[54:57], v[38:41], v[146:149], v[58:61]
	v_mfma_f32_16x16x32_bf16 v[58:61], v[38:41], v[150:153], v[62:65]
	v_mfma_f32_16x16x32_bf16 v[62:65], v[38:41], v[154:157], v[130:133]
	v_mfma_f32_16x16x32_bf16 v[130:133], v[38:41], v[158:161], v[134:137]
	v_mfma_f32_16x16x32_bf16 v[134:137], v[38:41], v[162:165], v[138:141]
	v_add_u32_e32 v162, v238, v199
	v_mfma_f32_16x16x32_bf16 v[138:141], v[38:41], v[166:169], v[42:45]
	ds_read_b128 v[38:41], v162
	s_nop 1
	ds_read_b128 v[42:45], v162 offset:8192
	ds_read_b128 v[142:145], v162 offset:16384
	ds_read_b128 v[146:149], v162 offset:24576
	ds_read_b128 v[150:153], v162 offset:32768
	ds_read_b128 v[154:157], v162 offset:40960
	ds_read_b128 v[158:161], v162 offset:49152
	ds_read_b128 v[162:165], v162 offset:57344
	s_waitcnt lgkmcnt(0)
	s_waitcnt lgkmcnt(0)
	s_waitcnt lgkmcnt(0)
	v_mfma_f32_16x16x32_bf16 v[46:49], v[34:37], v[38:41], v[46:49]
	s_barrier
; __device__ __forceinline__ float shx(float v, int lane, int mask) { return __int_as_float(__builtin_amdgcn_ds_bpermute((lane ^ mask) << 2, __float_as_int(v))); }
; #define MFMA16(a, b, c) __builtin_amdgcn_mfma_f32_16x16x32_bf16((a), (b), (c), 0, 0, 0)
; __device__ __forceinline__ void retc_stream(const int wv, LAS unsigned char* lds, unsigned ldsb, const float* __restrict__ gn_g, const float* __restrict__ gn_b, const bf16_t* __restrict__ qkvr, const bf16_t* __restrict__ grb, const bf16_t* __restrict__ kv, ...
;     ...
;                 for (int c = 0; c < 8; ++c) acc[vc * 8 + c] = MFMA16(qf[s], bfr[c], acc[vc * 8 + c]);
;             }
;         }
;         const float* gng = gn_g + h * 512; const float* gnb = gn_b + h * 512;
;         float mu4[4], rs4[4];
; #pragma unroll
;         for (int e = 0; e < 4; ++e) {
;             const int q = 16 * w + 4 * g + e;
;             const float xi = exp2f(lg2 * (float)(q - 127));
;             float sum = 0.f;
; #pragma unroll
;             for (int c = 0; c < 32; ++c) { acc[c][e] *= xi; sum += acc[c][e]; }
;             sum += shx(sum, lane, 1); sum += shx(sum, lane, 2); sum += shx(sum, lane, 4); sum += shx(sum, lane, 8);
	v_mfma_f32_16x16x32_bf16 v[42:45], v[34:37], v[42:45], v[50:53]
	v_mfma_f32_16x16x32_bf16 v[38:41], v[34:37], v[142:145], v[54:57]
	v_mfma_f32_16x16x32_bf16 v[58:61], v[34:37], v[146:149], v[58:61]
	v_mfma_f32_16x16x32_bf16 v[50:53], v[34:37], v[150:153], v[62:65]
	v_mfma_f32_16x16x32_bf16 v[62:65], v[34:37], v[154:157], v[130:133]
	v_mfma_f32_16x16x32_bf16 v[54:57], v[34:37], v[158:161], v[134:137]
	s_nop 1
	v_mul_f32_e32 v130, v1, v213
	v_cmp_gt_f32_e32 vcc, s41, v130
	v_mfma_f32_16x16x32_bf16 v[34:37], v[34:37], v[162:165], v[138:141]
	s_nop 0
	v_cndmask_b32_e32 v130, 0, v187, vcc
	v_cndmask_b32_e32 v131, 0, v189, vcc
	v_fmac_f32_e32 v130, v1, v213
	v_exp_f32_e32 v130, v130
	v_mov_b32_e32 v133, v54
	s_nop 1
	v_mov_b32_e32 v132, v34
	v_mul_f32_e32 v34, v1, v214
	v_cmp_gt_f32_e32 vcc, s41, v34
	v_ldexp_f32 v130, v130, v131
	v_mov_b32_e32 v134, v62
	v_cndmask_b32_e32 v34, 0, v187, vcc
	v_fmac_f32_e32 v34, v1, v214
	v_exp_f32_e32 v34, v34
	v_mov_b32_e32 v135, v50
	v_mov_b32_e32 v136, v58
	v_mov_b32_e32 v137, v38
	v_cndmask_b32_e32 v38, 0, v189, vcc
	v_pk_mul_f32 v[138:139], v[130:131], v[132:133] op_sel_hi:[0,1]
	v_pk_mul_f32 v[140:141], v[130:131], v[134:135] op_sel_hi:[0,1]
	v_pk_mul_f32 v[142:143], v[130:131], v[136:137] op_sel_hi:[0,1]
	v_ldexp_f32 v131, v34, v38
	v_mov_b32_e32 v158, v131
	v_mov_b32_e32 v54, v35
	v_mov_b32_e32 v50, v63
	v_mov_b32_e32 v38, v59
	v_pk_mul_f32 v[34:35], v[158:159], v[54:55] op_sel_hi:[0,1]
	v_pk_mul_f32 v[62:63], v[158:159], v[50:51] op_sel_hi:[0,1]
	v_pk_mul_f32 v[58:59], v[158:159], v[38:39] op_sel_hi:[0,1]
	v_mov_b32_e32 v144, v139
	v_mov_b32_e32 v145, v35
	v_mov_b32_e32 v139, v34
	v_mov_b32_e32 v34, v143
	v_mov_b32_e32 v35, v59
	v_mov_b32_e32 v143, v58
	v_mov_b32_e32 v58, v141
	v_mov_b32_e32 v59, v63
	v_mov_b32_e32 v141, v62
	v_pk_fma_f32 v[62:63], v[130:131], v[26:27], 0 op_sel_hi:[1,1,0]
	s_nop 0
	v_pk_fma_f32 v[62:63], v[130:131], v[30:31], v[62:63]
	s_nop 0
	v_pk_fma_f32 v[62:63], v[130:131], v[22:23], v[62:63]
	s_nop 0
	v_pk_fma_f32 v[62:63], v[130:131], v[18:19], v[62:63]
	s_nop 0
	v_pk_fma_f32 v[62:63], v[130:131], v[14:15], v[62:63]
	s_nop 0
	v_pk_fma_f32 v[62:63], v[130:131], v[10:11], v[62:63]
	s_nop 0
	v_pk_fma_f32 v[62:63], v[130:131], v[6:7], v[62:63]
	s_nop 0
	v_pk_fma_f32 v[62:63], v[130:131], v[2:3], v[62:63]
	s_nop 0
	v_pk_fma_f32 v[62:63], v[130:131], v[94:95], v[62:63]
	s_nop 0
	v_pk_fma_f32 v[62:63], v[130:131], v[90:91], v[62:63]
	s_nop 0
	v_pk_fma_f32 v[62:63], v[130:131], v[86:87], v[62:63]
	s_nop 0
	v_pk_fma_f32 v[62:63], v[130:131], v[82:83], v[62:63]
	s_nop 0
	v_pk_fma_f32 v[62:63], v[130:131], v[78:79], v[62:63]
	s_nop 0
	v_pk_fma_f32 v[62:63], v[130:131], v[74:75], v[62:63]
	s_nop 0
	v_pk_fma_f32 v[62:63], v[130:131], v[70:71], v[62:63]
	s_nop 0
	v_pk_fma_f32 v[62:63], v[130:131], v[66:67], v[62:63]
	s_nop 0
	v_pk_fma_f32 v[62:63], v[130:131], v[102:103], v[62:63]
	s_nop 0
	v_pk_fma_f32 v[62:63], v[130:131], v[98:99], v[62:63]
	s_nop 0
	v_pk_fma_f32 v[62:63], v[130:131], v[106:107], v[62:63]
	s_nop 0
	v_pk_fma_f32 v[62:63], v[130:131], v[126:127], v[62:63]
	s_nop 0
	v_pk_fma_f32 v[62:63], v[130:131], v[122:123], v[62:63]
	s_nop 0
	v_pk_fma_f32 v[62:63], v[130:131], v[118:119], v[62:63]
	s_nop 0
	v_pk_fma_f32 v[62:63], v[130:131], v[114:115], v[62:63]
	s_nop 0
	v_pk_fma_f32 v[62:63], v[130:131], v[110:111], v[62:63]
	s_nop 0
	v_pk_fma_f32 v[62:63], v[130:131], v[46:47], v[62:63]
	s_nop 0
	v_pk_fma_f32 v[62:63], v[130:131], v[42:43], v[62:63]
	s_nop 0
	v_pk_add_f32 v[34:35], v[62:63], v[34:35]
	s_nop 0
	v_pk_add_f32 v[34:35], v[34:35], v[142:143]
	s_nop 0
	v_pk_add_f32 v[34:35], v[34:35], v[58:59]
	s_nop 0
	v_pk_add_f32 v[34:35], v[34:35], v[140:141]
	s_nop 0
	v_pk_add_f32 v[34:35], v[34:35], v[144:145]
	s_nop 0
	v_pk_add_f32 v[34:35], v[34:35], v[138:139]
	ds_bpermute_b32 v58, v208, v34
	ds_bpermute_b32 v59, v208, v35
	s_waitcnt lgkmcnt(0)
	v_pk_add_f32 v[34:35], v[34:35], v[58:59]
	ds_bpermute_b32 v58, v209, v34
	ds_bpermute_b32 v59, v209, v35
	s_waitcnt lgkmcnt(0)
	v_pk_add_f32 v[34:35], v[34:35], v[58:59]
	ds_bpermute_b32 v58, v210, v34
	ds_bpermute_b32 v59, v210, v35
	s_waitcnt lgkmcnt(0)
	v_pk_add_f32 v[34:35], v[34:35], v[58:59]
	ds_bpermute_b32 v58, v211, v34
	ds_bpermute_b32 v59, v211, v35
	s_waitcnt lgkmcnt(0)
; __device__ __forceinline__ float shx(float v, int lane, int mask) { return __int_as_float(__builtin_amdgcn_ds_bpermute((lane ^ mask) << 2, __float_as_int(v))); }
; __device__ __forceinline__ void retc_stream(const int wv, LAS unsigned char* lds, unsigned ldsb, const float* __restrict__ gn_g, const float* __restrict__ gn_b, const bf16_t* __restrict__ qkvr, const bf16_t* __restrict__ grb, const bf16_t* __restrict__ kv, ...
;     ...
;             for (int c = 0; c < 32; ++c) { acc[c][e] *= xi; sum += acc[c][e]; }
;             sum += shx(sum, lane, 1); sum += shx(sum, lane, 2); sum += shx(sum, lane, 4); sum += shx(sum, lane, 8);
;             const float mu = sum * (1.0f / 512.0f);
;             float var = 0.f;
; #pragma unroll
;             for (int c = 0; c < 32; ++c) { const float d = acc[c][e] - mu; var += d * d; }
;             var += shx(var, lane, 1); var += shx(var, lane, 2); var += shx(var, lane, 4); var += shx(var, lane, 8);
;             mu4[e] = mu; rs4[e] = rsqrtf(var * (1.0f / 512.0f) + EPS);
	v_pk_add_f32 v[34:35], v[34:35], v[58:59]
	s_nop 0
	v_pk_mul_f32 v[160:161], v[34:35], s[40:41] op_sel_hi:[1,0]
	s_nop 0
	v_pk_fma_f32 v[154:155], v[130:131], v[30:31], v[160:161] neg_lo:[0,0,1] neg_hi:[0,0,1]
	v_pk_fma_f32 v[156:157], v[130:131], v[26:27], v[160:161] neg_lo:[0,0,1] neg_hi:[0,0,1]
	v_pk_mul_f32 v[26:27], v[154:155], v[154:155]
	v_pk_fma_f32 v[152:153], v[130:131], v[22:23], v[160:161] neg_lo:[0,0,1] neg_hi:[0,0,1]
	v_pk_fma_f32 v[26:27], v[156:157], v[156:157], v[26:27]
	v_pk_fma_f32 v[150:151], v[130:131], v[18:19], v[160:161] neg_lo:[0,0,1] neg_hi:[0,0,1]
	v_pk_fma_f32 v[22:23], v[152:153], v[152:153], v[26:27]
	v_pk_fma_f32 v[148:149], v[130:131], v[14:15], v[160:161] neg_lo:[0,0,1] neg_hi:[0,0,1]
	v_pk_fma_f32 v[18:19], v[150:151], v[150:151], v[22:23]
	v_pk_fma_f32 v[146:147], v[130:131], v[10:11], v[160:161] neg_lo:[0,0,1] neg_hi:[0,0,1]
	v_pk_fma_f32 v[14:15], v[148:149], v[148:149], v[18:19]
	v_pk_fma_f32 v[144:145], v[130:131], v[6:7], v[160:161] neg_lo:[0,0,1] neg_hi:[0,0,1]
	v_pk_fma_f32 v[10:11], v[146:147], v[146:147], v[14:15]
	v_pk_fma_f32 v[142:143], v[130:131], v[2:3], v[160:161] neg_lo:[0,0,1] neg_hi:[0,0,1]
	v_pk_fma_f32 v[6:7], v[144:145], v[144:145], v[10:11]
	v_pk_fma_f32 v[140:141], v[130:131], v[94:95], v[160:161] neg_lo:[0,0,1] neg_hi:[0,0,1]
	v_pk_fma_f32 v[2:3], v[142:143], v[142:143], v[6:7]
	v_pk_fma_f32 v[138:139], v[130:131], v[90:91], v[160:161] neg_lo:[0,0,1] neg_hi:[0,0,1]
	v_pk_fma_f32 v[2:3], v[140:141], v[140:141], v[2:3]
	v_pk_fma_f32 v[62:63], v[130:131], v[136:137], v[160:161] op_sel_hi:[0,1,0] neg_lo:[0,0,1] neg_hi:[0,0,1]
	v_pk_fma_f32 v[2:3], v[138:139], v[138:139], v[2:3]
	v_pk_fma_f32 v[136:137], v[130:131], v[86:87], v[160:161] neg_lo:[0,0,1] neg_hi:[0,0,1]
	v_pk_fma_f32 v[58:59], v[130:131], v[134:135], v[160:161] op_sel_hi:[0,1,0] neg_lo:[0,0,1] neg_hi:[0,0,1]
	v_pk_fma_f32 v[2:3], v[136:137], v[136:137], v[2:3]
	v_pk_fma_f32 v[134:135], v[130:131], v[82:83], v[160:161] neg_lo:[0,0,1] neg_hi:[0,0,1]
	v_pk_fma_f32 v[34:35], v[130:131], v[132:133], v[160:161] op_sel_hi:[0,1,0] neg_lo:[0,0,1] neg_hi:[0,0,1]
	v_pk_fma_f32 v[2:3], v[134:135], v[134:135], v[2:3]
	v_pk_fma_f32 v[132:133], v[130:131], v[78:79], v[160:161] neg_lo:[0,0,1] neg_hi:[0,0,1]
	v_pk_fma_f32 v[94:95], v[130:131], v[74:75], v[160:161] neg_lo:[0,0,1] neg_hi:[0,0,1]
	v_pk_fma_f32 v[2:3], v[132:133], v[132:133], v[2:3]
	v_pk_fma_f32 v[90:91], v[130:131], v[70:71], v[160:161] neg_lo:[0,0,1] neg_hi:[0,0,1]
	v_pk_fma_f32 v[2:3], v[94:95], v[94:95], v[2:3]
	v_pk_fma_f32 v[86:87], v[130:131], v[66:67], v[160:161] neg_lo:[0,0,1] neg_hi:[0,0,1]
	v_pk_fma_f32 v[2:3], v[90:91], v[90:91], v[2:3]
	v_pk_fma_f32 v[82:83], v[130:131], v[102:103], v[160:161] neg_lo:[0,0,1] neg_hi:[0,0,1]
	v_pk_fma_f32 v[2:3], v[86:87], v[86:87], v[2:3]
	v_pk_fma_f32 v[78:79], v[130:131], v[98:99], v[160:161] neg_lo:[0,0,1] neg_hi:[0,0,1]
	v_pk_fma_f32 v[2:3], v[82:83], v[82:83], v[2:3]
	v_pk_fma_f32 v[74:75], v[130:131], v[106:107], v[160:161] neg_lo:[0,0,1] neg_hi:[0,0,1]
	v_pk_fma_f32 v[2:3], v[78:79], v[78:79], v[2:3]
	v_pk_fma_f32 v[70:71], v[130:131], v[126:127], v[160:161] neg_lo:[0,0,1] neg_hi:[0,0,1]
	v_pk_fma_f32 v[2:3], v[74:75], v[74:75], v[2:3]
	v_pk_fma_f32 v[66:67], v[130:131], v[122:123], v[160:161] neg_lo:[0,0,1] neg_hi:[0,0,1]
	v_pk_fma_f32 v[2:3], v[70:71], v[70:71], v[2:3]
	v_pk_fma_f32 v[30:31], v[130:131], v[118:119], v[160:161] neg_lo:[0,0,1] neg_hi:[0,0,1]
	v_pk_fma_f32 v[2:3], v[66:67], v[66:67], v[2:3]
	v_pk_fma_f32 v[26:27], v[130:131], v[114:115], v[160:161] neg_lo:[0,0,1] neg_hi:[0,0,1]
	v_pk_fma_f32 v[2:3], v[30:31], v[30:31], v[2:3]
	v_pk_fma_f32 v[22:23], v[130:131], v[110:111], v[160:161] neg_lo:[0,0,1] neg_hi:[0,0,1]
	v_pk_fma_f32 v[2:3], v[26:27], v[26:27], v[2:3]
	v_pk_fma_f32 v[18:19], v[130:131], v[46:47], v[160:161] neg_lo:[0,0,1] neg_hi:[0,0,1]
	v_pk_fma_f32 v[2:3], v[22:23], v[22:23], v[2:3]
	v_pk_fma_f32 v[10:11], v[158:159], v[38:39], v[160:161] op_sel:[0,0,1] op_sel_hi:[0,1,1] neg_lo:[0,0,1] neg_hi:[0,0,1]
	v_pk_mul_f32 v[162:163], v[62:63], v[62:63]
	v_pk_fma_f32 v[2:3], v[18:19], v[18:19], v[2:3]
	v_pk_fma_f32 v[14:15], v[130:131], v[42:43], v[160:161] neg_lo:[0,0,1] neg_hi:[0,0,1]
	v_pk_mul_f32 v[38:39], v[10:11], v[10:11]
	v_pk_fma_f32 v[42:43], v[14:15], v[14:15], v[2:3]
	v_pk_fma_f32 v[6:7], v[158:159], v[50:51], v[160:161] op_sel:[0,0,1] op_sel_hi:[0,1,1] neg_lo:[0,0,1] neg_hi:[0,0,1]
	v_pk_fma_f32 v[2:3], v[158:159], v[54:55], v[160:161] op_sel:[0,0,1] op_sel_hi:[0,1,1] neg_lo:[0,0,1] neg_hi:[0,0,1]
	v_mov_b32_e32 v55, v162
	v_mov_b32_e32 v162, v39
	v_pk_mul_f32 v[164:165], v[58:59], v[58:59]
	v_pk_mul_f32 v[46:47], v[6:7], v[6:7]
	v_mov_b32_e32 v54, v38
	v_pk_add_f32 v[38:39], v[162:163], v[42:43] op_sel:[0,1] op_sel_hi:[1,0]
	v_mov_b32_e32 v42, v47
	v_pk_add_f32 v[38:39], v[54:55], v[38:39]
	v_mov_b32_e32 v43, v165
	v_pk_mul_f32 v[166:167], v[34:35], v[34:35]
	v_pk_mul_f32 v[50:51], v[2:3], v[2:3]
	v_pk_add_f32 v[38:39], v[42:43], v[38:39]
	v_mov_b32_e32 v47, v164
	v_pk_add_f32 v[38:39], v[46:47], v[38:39]
	v_mov_b32_e32 v42, v51
	v_mov_b32_e32 v43, v167
	v_pk_add_f32 v[38:39], v[42:43], v[38:39]
	v_mov_b32_e32 v51, v166
	v_pk_add_f32 v[38:39], v[50:51], v[38:39]
	ds_bpermute_b32 v43, v208, v39
	ds_bpermute_b32 v42, v208, v38
	v_mov_b64_e32 v[46:47], s[0:1]
	v_mov_b32_e32 v50, v36
	v_mul_f32_e32 v36, v1, v216
	v_mov_b32_e32 v51, v56
	s_waitcnt lgkmcnt(0)
	v_pk_add_f32 v[38:39], v[38:39], v[42:43]
	ds_bpermute_b32 v43, v209, v39
	ds_bpermute_b32 v42, v209, v38
	v_mov_b32_e32 v102, v60
	v_mov_b32_e32 v103, v40
	v_mov_b32_e32 v56, v37
	v_mov_b32_e32 v40, v61
	s_waitcnt lgkmcnt(0)
; __device__ __forceinline__ float shx(float v, int lane, int mask) { return __int_as_float(__builtin_amdgcn_ds_bpermute((lane ^ mask) << 2, __float_as_int(v))); }
; __device__ __forceinline__ void retc_stream(const int wv, LAS unsigned char* lds, unsigned ldsb, const float* __restrict__ gn_g, const float* __restrict__ gn_b, const bf16_t* __restrict__ qkvr, const bf16_t* __restrict__ grb, const bf16_t* __restrict__ kv, ...
;     ...
;         for (int e = 0; e < 4; ++e) {
;             const int q = 16 * w + 4 * g + e;
;             const float xi = exp2f(lg2 * (float)(q - 127));
;             float sum = 0.f;
; #pragma unroll
;             for (int c = 0; c < 32; ++c) { acc[c][e] *= xi; sum += acc[c][e]; }
;             sum += shx(sum, lane, 1); sum += shx(sum, lane, 2); sum += shx(sum, lane, 4); sum += shx(sum, lane, 8);
;             const float mu = sum * (1.0f / 512.0f);
;             float var = 0.f;
; #pragma unroll
;             for (int c = 0; c < 32; ++c) { const float d = acc[c][e] - mu; var += d * d; }
;             var += shx(var, lane, 1); var += shx(var, lane, 2); var += shx(var, lane, 4); var += shx(var, lane, 8);
;             mu4[e] = mu; rs4[e] = rsqrtf(var * (1.0f / 512.0f) + EPS);
	v_pk_add_f32 v[38:39], v[38:39], v[42:43]
	ds_bpermute_b32 v43, v210, v39
	ds_bpermute_b32 v42, v210, v38
	s_waitcnt lgkmcnt(0)
	v_pk_add_f32 v[38:39], v[38:39], v[42:43]
	ds_bpermute_b32 v43, v211, v39
	ds_bpermute_b32 v42, v211, v38
	s_waitcnt lgkmcnt(0)
	v_pk_add_f32 v[38:39], v[38:39], v[42:43]
	s_nop 0
	v_pk_fma_f32 v[38:39], v[38:39], s[40:41], v[46:47] op_sel_hi:[1,0,0]
	s_nop 0
	v_mul_f32_e32 v42, 0x4b800000, v39
	v_cmp_gt_f32_e64 s[0:1], s36, v39
	v_cmp_gt_f32_e32 vcc, s36, v38
	s_nop 0
	v_cndmask_b32_e64 v39, v39, v42, s[0:1]
	v_rsq_f32_e32 v39, v39
	s_nop 0
	v_mul_f32_e32 v42, 0x45800000, v39
	v_cndmask_b32_e64 v110, v39, v42, s[0:1]
	v_mul_f32_e32 v39, 0x4b800000, v38
	v_cndmask_b32_e32 v38, v38, v39, vcc
	v_rsq_f32_e32 v38, v38
	v_mul_f32_e32 v30, v30, v110
	v_mul_f32_e32 v26, v26, v110
	v_mul_f32_e32 v22, v22, v110
	v_mul_f32_e32 v39, 0x45800000, v38
	v_cndmask_b32_e32 v111, v38, v39, vcc
	v_mul_f32_e32 v38, v1, v215
	v_cmp_gt_f32_e32 vcc, s41, v38
	v_mul_f32_e32 v18, v18, v110
	v_mul_f32_e32 v14, v14, v110
	v_cndmask_b32_e32 v38, 0, v187, vcc
	v_cndmask_b32_e32 v39, 0, v189, vcc
	v_cmp_gt_f32_e32 vcc, s41, v36
	v_fmac_f32_e32 v38, v1, v215
	v_exp_f32_e32 v38, v38
	v_cndmask_b32_e32 v36, 0, v187, vcc
	v_fmac_f32_e32 v36, v1, v216
	v_exp_f32_e32 v1, v36
	v_ldexp_f32 v98, v38, v39
	v_mov_b32_e32 v38, v64
	v_mov_b32_e32 v39, v52
	v_cndmask_b32_e32 v36, 0, v189, vcc
	v_pk_mul_f32 v[42:43], v[98:99], v[50:51] op_sel_hi:[0,1]
	v_pk_mul_f32 v[54:55], v[98:99], v[38:39] op_sel_hi:[0,1]
	v_pk_mul_f32 v[106:107], v[98:99], v[102:103] op_sel_hi:[0,1]
	v_ldexp_f32 v99, v1, v36
	v_mov_b32_e32 v114, v99
	v_mov_b32_e32 v52, v65
	v_pk_mul_f32 v[36:37], v[114:115], v[56:57] op_sel_hi:[0,1]
	v_pk_mul_f32 v[64:65], v[114:115], v[52:53] op_sel_hi:[0,1]
	v_pk_mul_f32 v[60:61], v[114:115], v[40:41] op_sel_hi:[0,1]
	v_mov_b32_e32 v118, v43
	v_mov_b32_e32 v119, v37
	v_mov_b32_e32 v43, v36
	v_mov_b32_e32 v36, v107
	v_mov_b32_e32 v37, v61
	v_mov_b32_e32 v107, v60
	v_mov_b32_e32 v60, v55
	v_mov_b32_e32 v61, v65
	v_mov_b32_e32 v55, v64
	v_pk_fma_f32 v[64:65], v[98:99], v[28:29], 0 op_sel_hi:[1,1,0]
	v_mul_f32_e32 v11, v11, v111
	v_pk_fma_f32 v[64:65], v[98:99], v[32:33], v[64:65]
	v_mul_f32_e32 v10, v10, v111
	v_pk_fma_f32 v[64:65], v[98:99], v[24:25], v[64:65]
	v_mul_f32_e32 v7, v7, v111
	v_pk_fma_f32 v[64:65], v[98:99], v[20:21], v[64:65]
	v_mul_f32_e32 v6, v6, v111
	v_pk_fma_f32 v[64:65], v[98:99], v[16:17], v[64:65]
	v_mul_f32_e32 v3, v3, v111
	v_pk_fma_f32 v[64:65], v[98:99], v[12:13], v[64:65]
	v_mul_f32_e32 v2, v2, v111
	v_pk_fma_f32 v[64:65], v[98:99], v[8:9], v[64:65]
	s_nop 0
	v_pk_fma_f32 v[64:65], v[98:99], v[4:5], v[64:65]
	s_nop 0
	v_pk_fma_f32 v[64:65], v[98:99], v[96:97], v[64:65]
	s_nop 0
	v_pk_fma_f32 v[64:65], v[98:99], v[92:93], v[64:65]
	s_nop 0
	v_pk_fma_f32 v[64:65], v[98:99], v[88:89], v[64:65]
	s_nop 0
	v_pk_fma_f32 v[64:65], v[98:99], v[84:85], v[64:65]
	s_nop 0
	v_pk_fma_f32 v[64:65], v[98:99], v[80:81], v[64:65]
	s_nop 0
	v_pk_fma_f32 v[64:65], v[98:99], v[76:77], v[64:65]
	s_nop 0
	v_pk_fma_f32 v[64:65], v[98:99], v[72:73], v[64:65]
	s_nop 0
	v_pk_fma_f32 v[64:65], v[98:99], v[68:69], v[64:65]
	s_nop 0
	v_pk_fma_f32 v[64:65], v[98:99], v[104:105], v[64:65]
	s_nop 0
	v_pk_fma_f32 v[64:65], v[98:99], v[100:101], v[64:65]
	s_nop 0
	v_pk_fma_f32 v[64:65], v[98:99], v[108:109], v[64:65]
	s_nop 0
	v_pk_fma_f32 v[64:65], v[98:99], v[128:129], v[64:65]
	s_nop 0
	v_pk_fma_f32 v[64:65], v[98:99], v[124:125], v[64:65]
	s_nop 0
	v_pk_fma_f32 v[64:65], v[98:99], v[120:121], v[64:65]
	s_nop 0
	v_pk_fma_f32 v[64:65], v[98:99], v[116:117], v[64:65]
	s_nop 0
	v_pk_fma_f32 v[64:65], v[98:99], v[112:113], v[64:65]
	s_nop 0
	v_pk_fma_f32 v[64:65], v[98:99], v[48:49], v[64:65]
	s_nop 0
	v_pk_fma_f32 v[64:65], v[98:99], v[44:45], v[64:65]
	s_nop 0
	v_pk_add_f32 v[36:37], v[64:65], v[36:37]
	s_nop 0
	v_pk_add_f32 v[36:37], v[36:37], v[106:107]
	s_nop 0
	v_pk_add_f32 v[36:37], v[36:37], v[60:61]
	s_nop 0
	v_pk_add_f32 v[36:37], v[36:37], v[54:55]
	s_nop 0
	v_pk_add_f32 v[36:37], v[36:37], v[118:119]
	s_nop 0
	v_pk_add_f32 v[36:37], v[36:37], v[42:43]
	ds_bpermute_b32 v42, v208, v36
	ds_bpermute_b32 v43, v208, v37
	s_waitcnt lgkmcnt(0)
	v_pk_add_f32 v[36:37], v[36:37], v[42:43]
	ds_bpermute_b32 v42, v209, v36
	ds_bpermute_b32 v43, v209, v37
	s_waitcnt lgkmcnt(0)
	v_pk_add_f32 v[36:37], v[36:37], v[42:43]
	ds_bpermute_b32 v42, v210, v36
	ds_bpermute_b32 v43, v210, v37
	s_waitcnt lgkmcnt(0)
	v_pk_add_f32 v[36:37], v[36:37], v[42:43]
	ds_bpermute_b32 v42, v211, v36
	ds_bpermute_b32 v43, v211, v37
	s_waitcnt lgkmcnt(0)
; __device__ __forceinline__ float shx(float v, int lane, int mask) { return __int_as_float(__builtin_amdgcn_ds_bpermute((lane ^ mask) << 2, __float_as_int(v))); }
; __device__ __forceinline__ void retc_stream(const int wv, LAS unsigned char* lds, unsigned ldsb, const float* __restrict__ gn_g, const float* __restrict__ gn_b, const bf16_t* __restrict__ qkvr, const bf16_t* __restrict__ grb, const bf16_t* __restrict__ kv, ...
;     ...
;             for (int c = 0; c < 32; ++c) { acc[c][e] *= xi; sum += acc[c][e]; }
;             sum += shx(sum, lane, 1); sum += shx(sum, lane, 2); sum += shx(sum, lane, 4); sum += shx(sum, lane, 8);
;             const float mu = sum * (1.0f / 512.0f);
;             float var = 0.f;
; #pragma unroll
;             for (int c = 0; c < 32; ++c) { const float d = acc[c][e] - mu; var += d * d; }
;             var += shx(var, lane, 1); var += shx(var, lane, 2); var += shx(var, lane, 4); var += shx(var, lane, 8);
	v_pk_add_f32 v[36:37], v[36:37], v[42:43]
	s_nop 0
	v_pk_mul_f32 v[118:119], v[36:37], s[40:41] op_sel_hi:[1,0]
	s_nop 0
	v_pk_fma_f32 v[160:161], v[98:99], v[32:33], v[118:119] neg_lo:[0,0,1] neg_hi:[0,0,1]
	v_pk_fma_f32 v[158:159], v[98:99], v[28:29], v[118:119] neg_lo:[0,0,1] neg_hi:[0,0,1]
	v_pk_mul_f32 v[28:29], v[160:161], v[160:161]
	v_pk_fma_f32 v[162:163], v[98:99], v[24:25], v[118:119] neg_lo:[0,0,1] neg_hi:[0,0,1]
	v_pk_fma_f32 v[28:29], v[158:159], v[158:159], v[28:29]
	v_pk_fma_f32 v[164:165], v[98:99], v[20:21], v[118:119] neg_lo:[0,0,1] neg_hi:[0,0,1]
	v_pk_fma_f32 v[24:25], v[162:163], v[162:163], v[28:29]
	v_pk_fma_f32 v[166:167], v[98:99], v[16:17], v[118:119] neg_lo:[0,0,1] neg_hi:[0,0,1]
	v_pk_fma_f32 v[20:21], v[164:165], v[164:165], v[24:25]
	v_pk_fma_f32 v[168:169], v[98:99], v[12:13], v[118:119] neg_lo:[0,0,1] neg_hi:[0,0,1]
	v_pk_fma_f32 v[16:17], v[166:167], v[166:167], v[20:21]
	v_pk_fma_f32 v[170:171], v[98:99], v[8:9], v[118:119] neg_lo:[0,0,1] neg_hi:[0,0,1]
	v_pk_fma_f32 v[12:13], v[168:169], v[168:169], v[16:17]
	v_pk_fma_f32 v[106:107], v[98:99], v[4:5], v[118:119] neg_lo:[0,0,1] neg_hi:[0,0,1]
	v_pk_fma_f32 v[8:9], v[170:171], v[170:171], v[12:13]
	v_pk_fma_f32 v[42:43], v[98:99], v[102:103], v[118:119] op_sel_hi:[0,1,0] neg_lo:[0,0,1] neg_hi:[0,0,1]
	v_pk_fma_f32 v[4:5], v[106:107], v[106:107], v[8:9]
	v_pk_fma_f32 v[102:103], v[98:99], v[96:97], v[118:119] neg_lo:[0,0,1] neg_hi:[0,0,1]
	v_pk_fma_f32 v[96:97], v[98:99], v[92:93], v[118:119] neg_lo:[0,0,1] neg_hi:[0,0,1]
	v_pk_fma_f32 v[4:5], v[102:103], v[102:103], v[4:5]
	v_pk_fma_f32 v[92:93], v[98:99], v[88:89], v[118:119] neg_lo:[0,0,1] neg_hi:[0,0,1]
	v_pk_fma_f32 v[4:5], v[96:97], v[96:97], v[4:5]
	v_pk_fma_f32 v[88:89], v[98:99], v[84:85], v[118:119] neg_lo:[0,0,1] neg_hi:[0,0,1]
	v_pk_fma_f32 v[4:5], v[92:93], v[92:93], v[4:5]
	v_pk_fma_f32 v[84:85], v[98:99], v[80:81], v[118:119] neg_lo:[0,0,1] neg_hi:[0,0,1]
	v_pk_fma_f32 v[4:5], v[88:89], v[88:89], v[4:5]
	v_pk_fma_f32 v[80:81], v[98:99], v[76:77], v[118:119] neg_lo:[0,0,1] neg_hi:[0,0,1]
	v_pk_fma_f32 v[4:5], v[84:85], v[84:85], v[4:5]
	v_pk_fma_f32 v[76:77], v[98:99], v[72:73], v[118:119] neg_lo:[0,0,1] neg_hi:[0,0,1]
	v_pk_fma_f32 v[4:5], v[80:81], v[80:81], v[4:5]
	v_pk_fma_f32 v[72:73], v[98:99], v[68:69], v[118:119] neg_lo:[0,0,1] neg_hi:[0,0,1]
	v_pk_fma_f32 v[4:5], v[76:77], v[76:77], v[4:5]
	v_pk_fma_f32 v[68:69], v[98:99], v[104:105], v[118:119] neg_lo:[0,0,1] neg_hi:[0,0,1]
	v_pk_fma_f32 v[4:5], v[72:73], v[72:73], v[4:5]
	v_pk_fma_f32 v[64:65], v[98:99], v[100:101], v[118:119] neg_lo:[0,0,1] neg_hi:[0,0,1]
	v_pk_fma_f32 v[4:5], v[68:69], v[68:69], v[4:5]
	v_pk_fma_f32 v[60:61], v[98:99], v[108:109], v[118:119] neg_lo:[0,0,1] neg_hi:[0,0,1]
	v_pk_fma_f32 v[4:5], v[64:65], v[64:65], v[4:5]
	v_pk_fma_f32 v[54:55], v[98:99], v[128:129], v[118:119] neg_lo:[0,0,1] neg_hi:[0,0,1]
	v_pk_fma_f32 v[4:5], v[60:61], v[60:61], v[4:5]
	v_pk_fma_f32 v[36:37], v[98:99], v[50:51], v[118:119] op_sel_hi:[0,1,0] neg_lo:[0,0,1] neg_hi:[0,0,1]
	v_pk_fma_f32 v[4:5], v[54:55], v[54:55], v[4:5]
	v_pk_fma_f32 v[50:51], v[98:99], v[124:125], v[118:119] neg_lo:[0,0,1] neg_hi:[0,0,1]
	v_pk_fma_f32 v[32:33], v[98:99], v[120:121], v[118:119] neg_lo:[0,0,1] neg_hi:[0,0,1]
	v_pk_fma_f32 v[4:5], v[50:51], v[50:51], v[4:5]
	v_pk_fma_f32 v[28:29], v[98:99], v[116:117], v[118:119] neg_lo:[0,0,1] neg_hi:[0,0,1]
	v_pk_fma_f32 v[4:5], v[32:33], v[32:33], v[4:5]
	v_pk_fma_f32 v[24:25], v[98:99], v[112:113], v[118:119] neg_lo:[0,0,1] neg_hi:[0,0,1]
	v_pk_fma_f32 v[4:5], v[28:29], v[28:29], v[4:5]
	v_pk_fma_f32 v[20:21], v[98:99], v[48:49], v[118:119] neg_lo:[0,0,1] neg_hi:[0,0,1]
	v_pk_fma_f32 v[4:5], v[24:25], v[24:25], v[4:5]
	v_pk_fma_f32 v[12:13], v[114:115], v[40:41], v[118:119] op_sel:[0,0,1] op_sel_hi:[0,1,1] neg_lo:[0,0,1] neg_hi:[0,0,1]
	v_pk_mul_f32 v[122:123], v[42:43], v[42:43]
	v_pk_fma_f32 v[4:5], v[20:21], v[20:21], v[4:5]
	v_pk_fma_f32 v[16:17], v[98:99], v[44:45], v[118:119] neg_lo:[0,0,1] neg_hi:[0,0,1]
	v_pk_mul_f32 v[40:41], v[12:13], v[12:13]
	v_pk_fma_f32 v[38:39], v[98:99], v[38:39], v[118:119] op_sel_hi:[0,1,0] neg_lo:[0,0,1] neg_hi:[0,0,1]
	v_pk_fma_f32 v[44:45], v[16:17], v[16:17], v[4:5]
	v_pk_fma_f32 v[8:9], v[114:115], v[52:53], v[118:119] op_sel:[0,0,1] op_sel_hi:[0,1,1] neg_lo:[0,0,1] neg_hi:[0,0,1]
	v_pk_fma_f32 v[4:5], v[114:115], v[56:57], v[118:119] op_sel:[0,0,1] op_sel_hi:[0,1,1] neg_lo:[0,0,1] neg_hi:[0,0,1]
	v_mov_b32_e32 v57, v122
	v_mov_b32_e32 v122, v41
	v_pk_mul_f32 v[126:127], v[38:39], v[38:39]
	v_pk_mul_f32 v[48:49], v[8:9], v[8:9]
	v_mov_b32_e32 v56, v40
	v_pk_add_f32 v[40:41], v[122:123], v[44:45] op_sel:[0,1] op_sel_hi:[1,0]
	v_mov_b32_e32 v44, v49
	v_pk_add_f32 v[40:41], v[56:57], v[40:41]
	v_mov_b32_e32 v45, v127
	v_pk_mul_f32 v[130:131], v[36:37], v[36:37]
	v_pk_mul_f32 v[52:53], v[4:5], v[4:5]
	v_pk_add_f32 v[40:41], v[44:45], v[40:41]
	v_mov_b32_e32 v49, v126
	v_pk_add_f32 v[40:41], v[48:49], v[40:41]
	v_mov_b32_e32 v44, v53
	v_mov_b32_e32 v45, v131
	v_pk_add_f32 v[40:41], v[44:45], v[40:41]
	v_mov_b32_e32 v53, v130
	v_pk_add_f32 v[40:41], v[52:53], v[40:41]
	ds_bpermute_b32 v45, v208, v41
	ds_bpermute_b32 v44, v208, v40
	s_waitcnt lgkmcnt(0)
	v_pk_add_f32 v[40:41], v[40:41], v[44:45]
	ds_bpermute_b32 v45, v209, v41
	ds_bpermute_b32 v44, v209, v40
	s_waitcnt lgkmcnt(0)
	v_pk_add_f32 v[40:41], v[40:41], v[44:45]
	ds_bpermute_b32 v45, v210, v41
	ds_bpermute_b32 v44, v210, v40
	s_waitcnt lgkmcnt(0)
	v_pk_add_f32 v[40:41], v[40:41], v[44:45]
	ds_bpermute_b32 v45, v211, v41
	ds_bpermute_b32 v44, v211, v40
	s_waitcnt lgkmcnt(0)
; #define LAS __attribute__((address_space(3)))
; __device__ __forceinline__ bf16_t f2bf(float f) { return (bf16_t)(cvt_pk_bf16(f, 0.f) & 0xffffu); }
; #define LBAR() do { asm volatile("s_waitcnt lgkmcnt(0)" ::: "memory"); __builtin_amdgcn_s_barrier(); asm volatile("" ::: "memory"); } while (0)
; __device__ __forceinline__ void retc_stream(const int wv, LAS unsigned char* lds, unsigned ldsb, const float* __restrict__ gn_g, const float* __restrict__ gn_b, const bf16_t* __restrict__ qkvr, const bf16_t* __restrict__ grb, const bf16_t* __restrict__ kv, ...
;     ...
;             mu4[e] = mu; rs4[e] = rsqrtf(var * (1.0f / 512.0f) + EPS);
;         }
;         LBAR();
;         {
;             unsigned wb = (unsigned)(16 * w + 4 * g) * 1024u + (unsigned)li * 2u; asm volatile("" : "+v"(wb));
; #pragma unroll
;             for (int c = 0; c < 32; ++c) {
;                 const unsigned co = (unsigned)(((2 * c) ^ (2 * g)) * 16);
; #pragma unroll
;                 for (int e = 0; e < 4; ++e)
;                     *(LAS bf16_t*)(lds + wb + e * 1024 + co) = f2bf((acc[c][e] - mu4[e]) * rs4[e]);
;             }
	v_pk_add_f32 v[40:41], v[40:41], v[44:45]
	s_nop 0
	v_pk_fma_f32 v[40:41], v[40:41], s[40:41], v[46:47] op_sel_hi:[1,0,0]
	v_mul_f32_e32 v45, v156, v110
	v_mul_f32_e32 v1, 0x4b800000, v41
	v_cmp_gt_f32_e64 s[0:1], s36, v41
	v_cmp_gt_f32_e32 vcc, s36, v40
	v_mul_f32_e32 v46, v154, v110
	v_cndmask_b32_e64 v1, v41, v1, s[0:1]
	v_rsq_f32_e32 v1, v1
	v_mul_f32_e32 v47, v152, v110
	v_mul_f32_e32 v41, 0x45800000, v1
	v_cndmask_b32_e64 v1, v1, v41, s[0:1]
	v_mul_f32_e32 v41, 0x4b800000, v40
	v_cndmask_b32_e32 v40, v40, v41, vcc
	v_rsq_f32_e32 v40, v40
	s_add_u32 s0, s18, s12
	s_addc_u32 s1, s19, s13
	v_mul_f32_e32 v41, 0x45800000, v40
	v_cndmask_b32_e32 v40, v40, v41, vcc
	v_mov_b32_e32 v41, v212
	v_cvt_pk_bf16_f32 v45, v45, v0
	s_nop 0
	v_add_u32_e32 v41, 0, v41
	v_add_u32_e32 v44, v41, v217
	ds_write_b16 v44, v45
	v_mul_f32_e32 v45, v157, v111
	v_cvt_pk_bf16_f32 v45, v45, v0
	ds_write_b16 v44, v45 offset:1024
	v_mul_f32_e32 v45, v158, v1
	v_cvt_pk_bf16_f32 v45, v45, v0
	ds_write_b16 v44, v45 offset:2048
	v_mul_f32_e32 v45, v159, v40
	v_cvt_pk_bf16_f32 v45, v45, v0
	ds_write_b16 v44, v45 offset:3072
	v_add_u32_e32 v45, v41, v218
	v_cvt_pk_bf16_f32 v46, v46, v0
	ds_write_b16 v45, v46
	v_mul_f32_e32 v46, v155, v111
	v_cvt_pk_bf16_f32 v46, v46, v0
	ds_write_b16 v45, v46 offset:1024
	v_mul_f32_e32 v46, v160, v1
	v_cvt_pk_bf16_f32 v46, v46, v0
	ds_write_b16 v45, v46 offset:2048
	v_mul_f32_e32 v46, v161, v40
	v_cvt_pk_bf16_f32 v46, v46, v0
	ds_write_b16 v45, v46 offset:3072
	v_add_u32_e32 v46, v41, v219
	v_cvt_pk_bf16_f32 v47, v47, v0
	ds_write_b16 v46, v47
	v_mul_f32_e32 v47, v153, v111
	v_cvt_pk_bf16_f32 v47, v47, v0
	ds_write_b16 v46, v47 offset:1024
	v_mul_f32_e32 v47, v162, v1
	v_cvt_pk_bf16_f32 v47, v47, v0
	ds_write_b16 v46, v47 offset:2048
	v_mul_f32_e32 v47, v163, v40
	v_cvt_pk_bf16_f32 v47, v47, v0
	ds_write_b16 v46, v47 offset:3072
	v_mul_f32_e32 v47, v150, v110
	v_add_u32_e32 v41, v41, v220
	v_cvt_pk_bf16_f32 v47, v47, v0
	ds_write_b16 v41, v47
	v_mul_f32_e32 v47, v151, v111
	v_cvt_pk_bf16_f32 v47, v47, v0
	ds_write_b16 v41, v47 offset:1024
	v_mul_f32_e32 v47, v164, v1
	v_cvt_pk_bf16_f32 v47, v47, v0
	ds_write_b16 v41, v47 offset:2048
	v_mul_f32_e32 v47, v165, v40
	v_cvt_pk_bf16_f32 v47, v47, v0
	ds_write_b16 v41, v47 offset:3072
	v_mul_f32_e32 v47, v148, v110
	v_cvt_pk_bf16_f32 v47, v47, v0
	ds_write_b16 v44, v47 offset:128
	v_mul_f32_e32 v47, v149, v111
	v_cvt_pk_bf16_f32 v47, v47, v0
	ds_write_b16 v44, v47 offset:1152
	v_mul_f32_e32 v47, v166, v1
	v_cvt_pk_bf16_f32 v47, v47, v0
	ds_write_b16 v44, v47 offset:2176
	v_mul_f32_e32 v47, v167, v40
	v_cvt_pk_bf16_f32 v47, v47, v0
	ds_write_b16 v44, v47 offset:3200
	v_mul_f32_e32 v47, v146, v110
	v_cvt_pk_bf16_f32 v47, v47, v0
	ds_write_b16 v45, v47 offset:128
	v_mul_f32_e32 v47, v147, v111
	v_cvt_pk_bf16_f32 v47, v47, v0
	ds_write_b16 v45, v47 offset:1152
	v_mul_f32_e32 v47, v168, v1
	v_cvt_pk_bf16_f32 v47, v47, v0
	ds_write_b16 v45, v47 offset:2176
	v_mul_f32_e32 v47, v169, v40
	v_cvt_pk_bf16_f32 v47, v47, v0
	ds_write_b16 v45, v47 offset:3200
	v_mul_f32_e32 v47, v144, v110
	v_cvt_pk_bf16_f32 v47, v47, v0
	ds_write_b16 v46, v47 offset:128
	v_mul_f32_e32 v47, v145, v111
	v_cvt_pk_bf16_f32 v47, v47, v0
	ds_write_b16 v46, v47 offset:1152
	v_mul_f32_e32 v47, v170, v1
	v_cvt_pk_bf16_f32 v47, v47, v0
	ds_write_b16 v46, v47 offset:2176
	v_mul_f32_e32 v47, v171, v40
	v_cvt_pk_bf16_f32 v47, v47, v0
	ds_write_b16 v46, v47 offset:3200
	v_mul_f32_e32 v47, v142, v110
	v_cvt_pk_bf16_f32 v47, v47, v0
	ds_write_b16 v41, v47 offset:128
	v_mul_f32_e32 v47, v143, v111
	v_cvt_pk_bf16_f32 v47, v47, v0
	ds_write_b16 v41, v47 offset:1152
	v_mul_f32_e32 v47, v106, v1
	v_cvt_pk_bf16_f32 v47, v47, v0
	ds_write_b16 v41, v47 offset:2176
	v_mul_f32_e32 v47, v107, v40
	v_cvt_pk_bf16_f32 v47, v47, v0
	ds_write_b16 v41, v47 offset:3200
	v_mul_f32_e32 v47, v140, v110
	v_cvt_pk_bf16_f32 v47, v47, v0
	ds_write_b16 v44, v47 offset:256
	v_mul_f32_e32 v47, v141, v111
	v_cvt_pk_bf16_f32 v47, v47, v0
	ds_write_b16 v44, v47 offset:1280
	v_mul_f32_e32 v47, v102, v1
	v_cvt_pk_bf16_f32 v47, v47, v0
	ds_write_b16 v44, v47 offset:2304
	v_mul_f32_e32 v47, v103, v40
	v_cvt_pk_bf16_f32 v47, v47, v0
	ds_write_b16 v44, v47 offset:3328
	v_mul_f32_e32 v47, v138, v110
	v_cvt_pk_bf16_f32 v47, v47, v0
	ds_write_b16 v45, v47 offset:256
	v_mul_f32_e32 v47, v139, v111
	v_cvt_pk_bf16_f32 v47, v47, v0
	ds_write_b16 v45, v47 offset:1280
	v_mul_f32_e32 v47, v96, v1
	v_cvt_pk_bf16_f32 v47, v47, v0
	ds_write_b16 v45, v47 offset:2304
	v_mul_f32_e32 v47, v97, v40
	v_cvt_pk_bf16_f32 v47, v47, v0
	ds_write_b16 v45, v47 offset:3328
	v_mul_f32_e32 v47, v136, v110
	v_cvt_pk_bf16_f32 v47, v47, v0
	ds_write_b16 v46, v47 offset:256
	v_mul_f32_e32 v47, v137, v111
	v_cvt_pk_bf16_f32 v47, v47, v0
	ds_write_b16 v46, v47 offset:1280
	v_mul_f32_e32 v47, v92, v1
	v_cvt_pk_bf16_f32 v47, v47, v0
	ds_write_b16 v46, v47 offset:2304
	v_mul_f32_e32 v47, v93, v40
	v_cvt_pk_bf16_f32 v47, v47, v0
	ds_write_b16 v46, v47 offset:3328
	v_mul_f32_e32 v47, v134, v110
	v_cvt_pk_bf16_f32 v47, v47, v0
	ds_write_b16 v41, v47 offset:256
	v_mul_f32_e32 v47, v135, v111
	v_cvt_pk_bf16_f32 v47, v47, v0
	ds_write_b16 v41, v47 offset:1280
	v_mul_f32_e32 v47, v88, v1
	v_cvt_pk_bf16_f32 v47, v47, v0
	ds_write_b16 v41, v47 offset:2304
	v_mul_f32_e32 v47, v89, v40
	v_cvt_pk_bf16_f32 v47, v47, v0
	ds_write_b16 v41, v47 offset:3328
	v_mul_f32_e32 v47, v132, v110
	v_cvt_pk_bf16_f32 v47, v47, v0
	ds_write_b16 v44, v47 offset:384
	v_mul_f32_e32 v47, v133, v111
	v_cvt_pk_bf16_f32 v47, v47, v0
	ds_write_b16 v44, v47 offset:1408
	v_mul_f32_e32 v47, v84, v1
	v_cvt_pk_bf16_f32 v47, v47, v0
; #define LAS __attribute__((address_space(3)))
; __device__ __forceinline__ bf16_t f2bf(float f) { return (bf16_t)(cvt_pk_bf16(f, 0.f) & 0xffffu); }
; __device__ __forceinline__ void retc_stream(const int wv, LAS unsigned char* lds, unsigned ldsb, const float* __restrict__ gn_g, const float* __restrict__ gn_b, const bf16_t* __restrict__ qkvr, const bf16_t* __restrict__ grb, const bf16_t* __restrict__ kv, ...
;     ...
;             unsigned wb = (unsigned)(16 * w + 4 * g) * 1024u + (unsigned)li * 2u; asm volatile("" : "+v"(wb));
; #pragma unroll
;             for (int c = 0; c < 32; ++c) {
;                 const unsigned co = (unsigned)(((2 * c) ^ (2 * g)) * 16);
; #pragma unroll
;                 for (int e = 0; e < 4; ++e)
;                     *(LAS bf16_t*)(lds + wb + e * 1024 + co) = f2bf((acc[c][e] - mu4[e]) * rs4[e]);
;             }
	ds_write_b16 v44, v47 offset:2432
	v_mul_f32_e32 v47, v85, v40
	v_cvt_pk_bf16_f32 v47, v47, v0
	ds_write_b16 v44, v47 offset:3456
	v_mul_f32_e32 v47, v94, v110
	v_cvt_pk_bf16_f32 v47, v47, v0
	ds_write_b16 v45, v47 offset:384
	v_mul_f32_e32 v47, v95, v111
	v_cvt_pk_bf16_f32 v47, v47, v0
	ds_write_b16 v45, v47 offset:1408
	v_mul_f32_e32 v47, v80, v1
	v_cvt_pk_bf16_f32 v47, v47, v0
	ds_write_b16 v45, v47 offset:2432
	v_mul_f32_e32 v47, v81, v40
	v_cvt_pk_bf16_f32 v47, v47, v0
	ds_write_b16 v45, v47 offset:3456
	v_mul_f32_e32 v47, v90, v110
	v_cvt_pk_bf16_f32 v47, v47, v0
	ds_write_b16 v46, v47 offset:384
	v_mul_f32_e32 v47, v91, v111
	v_cvt_pk_bf16_f32 v47, v47, v0
	ds_write_b16 v46, v47 offset:1408
	v_mul_f32_e32 v47, v76, v1
	v_cvt_pk_bf16_f32 v47, v47, v0
	ds_write_b16 v46, v47 offset:2432
	v_mul_f32_e32 v47, v77, v40
	v_cvt_pk_bf16_f32 v47, v47, v0
	ds_write_b16 v46, v47 offset:3456
	v_mul_f32_e32 v47, v86, v110
	v_cvt_pk_bf16_f32 v47, v47, v0
	ds_write_b16 v41, v47 offset:384
	v_mul_f32_e32 v47, v87, v111
	v_cvt_pk_bf16_f32 v47, v47, v0
	ds_write_b16 v41, v47 offset:1408
	v_mul_f32_e32 v47, v72, v1
	v_cvt_pk_bf16_f32 v47, v47, v0
	ds_write_b16 v41, v47 offset:2432
	v_mul_f32_e32 v47, v73, v40
	v_cvt_pk_bf16_f32 v47, v47, v0
	ds_write_b16 v41, v47 offset:3456
	v_mul_f32_e32 v47, v82, v110
	v_cvt_pk_bf16_f32 v47, v47, v0
	ds_write_b16 v44, v47 offset:512
	v_mul_f32_e32 v47, v83, v111
	v_cvt_pk_bf16_f32 v47, v47, v0
	ds_write_b16 v44, v47 offset:1536
	v_mul_f32_e32 v47, v68, v1
	v_cvt_pk_bf16_f32 v47, v47, v0
	ds_write_b16 v44, v47 offset:2560
	v_mul_f32_e32 v47, v69, v40
	v_cvt_pk_bf16_f32 v47, v47, v0
	ds_write_b16 v44, v47 offset:3584
	v_mul_f32_e32 v47, v78, v110
	v_cvt_pk_bf16_f32 v47, v47, v0
	ds_write_b16 v45, v47 offset:512
	v_mul_f32_e32 v47, v79, v111
	v_cvt_pk_bf16_f32 v47, v47, v0
	ds_write_b16 v45, v47 offset:1536
	v_mul_f32_e32 v47, v64, v1
	v_cvt_pk_bf16_f32 v47, v47, v0
	ds_write_b16 v45, v47 offset:2560
	v_mul_f32_e32 v47, v65, v40
	v_cvt_pk_bf16_f32 v47, v47, v0
	ds_write_b16 v45, v47 offset:3584
	v_mul_f32_e32 v47, v74, v110
	v_cvt_pk_bf16_f32 v47, v47, v0
	ds_write_b16 v46, v47 offset:512
	v_mul_f32_e32 v47, v75, v111
	v_cvt_pk_bf16_f32 v47, v47, v0
	ds_write_b16 v46, v47 offset:1536
	v_mul_f32_e32 v47, v60, v1
	v_cvt_pk_bf16_f32 v47, v47, v0
	ds_write_b16 v46, v47 offset:2560
	v_mul_f32_e32 v47, v61, v40
	v_cvt_pk_bf16_f32 v47, v47, v0
	ds_write_b16 v46, v47 offset:3584
	v_mul_f32_e32 v47, v70, v110
	v_cvt_pk_bf16_f32 v47, v47, v0
	ds_write_b16 v41, v47 offset:512
	v_mul_f32_e32 v47, v71, v111
	v_cvt_pk_bf16_f32 v47, v47, v0
	ds_write_b16 v41, v47 offset:1536
	v_mul_f32_e32 v47, v54, v1
	v_cvt_pk_bf16_f32 v47, v47, v0
	ds_write_b16 v41, v47 offset:2560
	v_mul_f32_e32 v47, v55, v40
	v_cvt_pk_bf16_f32 v47, v47, v0
	ds_write_b16 v41, v47 offset:3584
	v_mul_f32_e32 v47, v66, v110
	v_cvt_pk_bf16_f32 v47, v47, v0
	ds_write_b16 v44, v47 offset:640
	v_mul_f32_e32 v47, v67, v111
	v_cvt_pk_bf16_f32 v47, v47, v0
	ds_write_b16 v44, v47 offset:1664
	v_mul_f32_e32 v47, v50, v1
	v_cvt_pk_bf16_f32 v47, v47, v0
	ds_write_b16 v44, v47 offset:2688
	v_mul_f32_e32 v47, v51, v40
	v_cvt_pk_bf16_f32 v47, v47, v0
	ds_write_b16 v44, v47 offset:3712
	v_cvt_pk_bf16_f32 v30, v30, v0
	ds_write_b16 v45, v30 offset:640
	v_mul_f32_e32 v30, v31, v111
	v_cvt_pk_bf16_f32 v30, v30, v0
	ds_write_b16 v45, v30 offset:1664
	v_mul_f32_e32 v30, v32, v1
	v_cvt_pk_bf16_f32 v30, v30, v0
	ds_write_b16 v45, v30 offset:2688
	v_mul_f32_e32 v30, v33, v40
	v_cvt_pk_bf16_f32 v30, v30, v0
	ds_write_b16 v45, v30 offset:3712
	v_cvt_pk_bf16_f32 v26, v26, v0
	ds_write_b16 v46, v26 offset:640
	v_mul_f32_e32 v26, v27, v111
	v_cvt_pk_bf16_f32 v26, v26, v0
	ds_write_b16 v46, v26 offset:1664
	v_mul_f32_e32 v26, v28, v1
	v_cvt_pk_bf16_f32 v26, v26, v0
	ds_write_b16 v46, v26 offset:2688
	v_mul_f32_e32 v26, v29, v40
	v_cvt_pk_bf16_f32 v26, v26, v0
	ds_write_b16 v46, v26 offset:3712
	v_cvt_pk_bf16_f32 v22, v22, v0
	ds_write_b16 v41, v22 offset:640
	v_mul_f32_e32 v22, v23, v111
	v_cvt_pk_bf16_f32 v22, v22, v0
	ds_write_b16 v41, v22 offset:1664
	v_mul_f32_e32 v22, v24, v1
	v_cvt_pk_bf16_f32 v22, v22, v0
	ds_write_b16 v41, v22 offset:2688
	v_mul_f32_e32 v22, v25, v40
	v_cvt_pk_bf16_f32 v22, v22, v0
	ds_write_b16 v41, v22 offset:3712
	v_cvt_pk_bf16_f32 v18, v18, v0
	ds_write_b16 v44, v18 offset:768
	v_mul_f32_e32 v18, v19, v111
	v_cvt_pk_bf16_f32 v18, v18, v0
	ds_write_b16 v44, v18 offset:1792
	v_mul_f32_e32 v18, v20, v1
	v_cvt_pk_bf16_f32 v18, v18, v0
	ds_write_b16 v44, v18 offset:2816
	v_mul_f32_e32 v18, v21, v40
	v_cvt_pk_bf16_f32 v18, v18, v0
	ds_write_b16 v44, v18 offset:3840
	v_cvt_pk_bf16_f32 v14, v14, v0
	ds_write_b16 v45, v14 offset:768
	v_mul_f32_e32 v14, v15, v111
	v_cvt_pk_bf16_f32 v14, v14, v0
	ds_write_b16 v45, v14 offset:1792
	v_mul_f32_e32 v14, v16, v1
	v_cvt_pk_bf16_f32 v14, v14, v0
	ds_write_b16 v45, v14 offset:2816
	v_mul_f32_e32 v14, v17, v40
	v_cvt_pk_bf16_f32 v14, v14, v0
	ds_write_b16 v45, v14 offset:3840
	v_mul_f32_e32 v14, v63, v110
	v_cvt_pk_bf16_f32 v14, v14, v0
	ds_write_b16 v46, v14 offset:768
	v_cvt_pk_bf16_f32 v11, v11, v0
	ds_write_b16 v46, v11 offset:1792
	v_mul_f32_e32 v11, v43, v1
	v_cvt_pk_bf16_f32 v11, v11, v0
	ds_write_b16 v46, v11 offset:2816
	v_mul_f32_e32 v11, v13, v40
	v_cvt_pk_bf16_f32 v11, v11, v0
	ds_write_b16 v46, v11 offset:3840
	v_mul_f32_e32 v11, v62, v110
	v_cvt_pk_bf16_f32 v11, v11, v0
	ds_write_b16 v41, v11 offset:768
	v_cvt_pk_bf16_f32 v10, v10, v0
	ds_write_b16 v41, v10 offset:1792
	v_mul_f32_e32 v10, v42, v1
	v_cvt_pk_bf16_f32 v10, v10, v0
	ds_write_b16 v41, v10 offset:2816
	v_mul_f32_e32 v10, v12, v40
	v_cvt_pk_bf16_f32 v10, v10, v0
; #define LAS __attribute__((address_space(3)))
; __device__ __forceinline__ bf16_t f2bf(float f) { return (bf16_t)(cvt_pk_bf16(f, 0.f) & 0xffffu); }
; #define LBAR() do { asm volatile("s_waitcnt lgkmcnt(0)" ::: "memory"); __builtin_amdgcn_s_barrier(); asm volatile("" ::: "memory"); } while (0)
; __device__ __forceinline__ void retc_stream(const int wv, LAS unsigned char* lds, unsigned ldsb, const float* __restrict__ gn_g, const float* __restrict__ gn_b, const bf16_t* __restrict__ qkvr, const bf16_t* __restrict__ grb, const bf16_t* __restrict__ kv, ...
;     ...
;                     *(LAS bf16_t*)(lds + wb + e * 1024 + co) = f2bf((acc[c][e] - mu4[e]) * rs4[e]);
;             }
;         }
;         {
;             int tq = t; asm volatile("" : "+v"(tq));
;             const int ch = tq & 63, r0 = tq >> 6;
;             const f32x4 g0 = *(const f32x4*)(gng + ch * 8), g1 = *(const f32x4*)(gng + ch * 8 + 4), b0 = *(const f32x4*)(gnb + ch * 8), b1 = *(const f32x4*)(gnb + ch * 8 + 4);
;             u32x4 gv[16];
; #pragma unroll
;             for (int k = 0; k < 16; ++k) gv[k] = *(const u32x4*)(grb + (size_t)(n * 128 + r0 + 8 * k) * 2048 + h * 512 + ch * 8);
;             LBAR();
	ds_write_b16 v41, v10 offset:3840
	v_mul_f32_e32 v10, v59, v110
	v_cvt_pk_bf16_f32 v10, v10, v0
	ds_write_b16 v44, v10 offset:896
	v_cvt_pk_bf16_f32 v7, v7, v0
	ds_write_b16 v44, v7 offset:1920
	v_mul_f32_e32 v7, v39, v1
	v_cvt_pk_bf16_f32 v7, v7, v0
	ds_write_b16 v44, v7 offset:2944
	v_mul_f32_e32 v7, v9, v40
	v_cvt_pk_bf16_f32 v7, v7, v0
	ds_write_b16 v44, v7 offset:3968
	v_mul_f32_e32 v7, v58, v110
	v_cvt_pk_bf16_f32 v7, v7, v0
	ds_write_b16 v45, v7 offset:896
	v_cvt_pk_bf16_f32 v6, v6, v0
	ds_write_b16 v45, v6 offset:1920
	v_mul_f32_e32 v6, v38, v1
	v_cvt_pk_bf16_f32 v6, v6, v0
	ds_write_b16 v45, v6 offset:2944
	v_mul_f32_e32 v6, v8, v40
	v_cvt_pk_bf16_f32 v6, v6, v0
	ds_write_b16 v45, v6 offset:3968
	v_mul_f32_e32 v6, v35, v110
	v_cvt_pk_bf16_f32 v6, v6, v0
	ds_write_b16 v46, v6 offset:896
	v_cvt_pk_bf16_f32 v3, v3, v0
	ds_write_b16 v46, v3 offset:1920
	v_mul_f32_e32 v3, v37, v1
	v_cvt_pk_bf16_f32 v3, v3, v0
	ds_write_b16 v46, v3 offset:2944
	v_mul_f32_e32 v3, v5, v40
	v_cvt_pk_bf16_f32 v3, v3, v0
	ds_write_b16 v46, v3 offset:3968
	v_mul_f32_e32 v3, v34, v110
	v_mul_f32_e32 v1, v36, v1
	v_cvt_pk_bf16_f32 v3, v3, v0
	ds_write_b16 v41, v3 offset:896
	v_cvt_pk_bf16_f32 v2, v2, v0
	ds_write_b16 v41, v2 offset:1920
	v_cvt_pk_bf16_f32 v1, v1, v0
	ds_write_b16 v41, v1 offset:2944
	v_mul_f32_e32 v1, v4, v40
	v_cvt_pk_bf16_f32 v1, v1, v0
	v_mov_b32_e32 v2, v191
	ds_write_b16 v41, v1 offset:3968
	v_mov_b32_e32 v79, v0
	v_and_b32_e32 v1, 63, v2
	v_lshlrev_b32_e32 v14, 5, v1
	v_ashrrev_i32_e32 v80, 6, v2
	global_load_dwordx4 v[2:5], v14, s[10:11] offset:16
	global_load_dwordx4 v[10:13], v14, s[10:11]
	global_load_dwordx4 v[6:9], v14, s[0:1] offset:16
	s_nop 0
	global_load_dwordx4 v[14:17], v14, s[0:1]
	s_lshl_b64 s[0:1], s[2:3], 1
	v_readlane_b32 s2, v254, 31
	v_add_u32_e32 v18, s29, v80
	s_add_u32 s2, s2, s0
	v_readlane_b32 s3, v254, 33
	s_addc_u32 s3, s3, s1
	v_lshlrev_b32_e32 v78, 4, v1
	v_ashrrev_i32_e32 v19, 31, v18
	v_lshl_add_u64 v[20:21], s[2:3], 0, v[78:79]
	v_lshlrev_b64 v[90:91], 12, v[18:19]
	v_lshl_add_u64 v[18:19], v[20:21], 0, v[90:91]
	global_load_dwordx4 v[82:85], v[18:19], off
	s_mov_b32 s2, 0x8000
	v_add_co_u32_e32 v20, vcc, s2, v18
	s_mov_b32 s2, 0x10000
	s_nop 0
	v_addc_co_u32_e32 v21, vcc, 0, v19, vcc
	global_load_dwordx4 v[74:77], v[20:21], off
	v_add_co_u32_e32 v20, vcc, s2, v18
	s_mov_b32 s2, 0x18000
	s_nop 0
	v_addc_co_u32_e32 v21, vcc, 0, v19, vcc
	global_load_dwordx4 v[70:73], v[20:21], off
	v_add_co_u32_e32 v20, vcc, s2, v18
	s_mov_b32 s2, 0x20000
	s_nop 0
	v_addc_co_u32_e32 v21, vcc, 0, v19, vcc
	global_load_dwordx4 v[66:69], v[20:21], off
	v_add_co_u32_e32 v20, vcc, s2, v18
	s_mov_b32 s2, 0x28000
	s_nop 0
	v_addc_co_u32_e32 v21, vcc, 0, v19, vcc
	global_load_dwordx4 v[62:65], v[20:21], off
	v_add_co_u32_e32 v20, vcc, s2, v18
	s_mov_b32 s2, 0x30000
	s_nop 0
	v_addc_co_u32_e32 v21, vcc, 0, v19, vcc
	global_load_dwordx4 v[58:61], v[20:21], off
	v_add_co_u32_e32 v20, vcc, s2, v18
	s_mov_b32 s2, 0x38000
	s_nop 0
	v_addc_co_u32_e32 v21, vcc, 0, v19, vcc
	global_load_dwordx4 v[54:57], v[20:21], off
	v_add_co_u32_e32 v20, vcc, s2, v18
	s_mov_b32 s2, 0x40000
	s_nop 0
	v_addc_co_u32_e32 v21, vcc, 0, v19, vcc
	global_load_dwordx4 v[50:53], v[20:21], off
	v_add_co_u32_e32 v20, vcc, s2, v18
	s_mov_b32 s2, 0x48000
	s_nop 0
	v_addc_co_u32_e32 v21, vcc, 0, v19, vcc
	global_load_dwordx4 v[46:49], v[20:21], off
	v_add_co_u32_e32 v20, vcc, s2, v18
	s_mov_b32 s2, 0x50000
	s_nop 0
	v_addc_co_u32_e32 v21, vcc, 0, v19, vcc
	global_load_dwordx4 v[42:45], v[20:21], off
	v_add_co_u32_e32 v20, vcc, s2, v18
	s_mov_b32 s2, 0x58000
	s_nop 0
	v_addc_co_u32_e32 v21, vcc, 0, v19, vcc
	global_load_dwordx4 v[38:41], v[20:21], off
	v_add_co_u32_e32 v20, vcc, s2, v18
	s_mov_b32 s2, 0x60000
	s_nop 0
	v_addc_co_u32_e32 v21, vcc, 0, v19, vcc
	global_load_dwordx4 v[34:37], v[20:21], off
	v_add_co_u32_e32 v20, vcc, s2, v18
	s_mov_b32 s2, 0x68000
	s_nop 0
	v_addc_co_u32_e32 v21, vcc, 0, v19, vcc
	global_load_dwordx4 v[30:33], v[20:21], off
	v_add_co_u32_e32 v20, vcc, s2, v18
	s_mov_b32 s2, 0x70000
	s_nop 0
	v_addc_co_u32_e32 v21, vcc, 0, v19, vcc
	global_load_dwordx4 v[26:29], v[20:21], off
	v_add_co_u32_e32 v20, vcc, s2, v18
	s_mov_b32 s2, 0x78000
	s_nop 0
	v_addc_co_u32_e32 v21, vcc, 0, v19, vcc
	v_lshrrev_b32_e32 v81, 1, v80
	v_add_co_u32_e32 v18, vcc, s2, v18
	v_bitop3_b32 v81, v81, v1, 6 bitop3:0x6c
	s_nop 0
	v_addc_co_u32_e32 v19, vcc, 0, v19, vcc
	v_lshlrev_b32_e32 v86, 10, v80
	v_lshlrev_b32_e32 v81, 4, v81
	global_load_dwordx4 v[22:25], v[20:21], off
	v_add3_u32 v86, 0, v86, v81
	global_load_dwordx4 v[18:21], v[18:19], off
	s_waitcnt lgkmcnt(0)
	s_barrier
; #define LAS __attribute__((address_space(3)))
; __device__ __forceinline__ unsigned cvt_pk_bf16(float lo, float hi) { unsigned r; asm volatile("v_cvt_pk_bf16_f32 %0, %1, %2" : "=v"(r) : "v"(lo), "v"(hi)); return r; }
; __device__ __forceinline__ float bflo(unsigned u) { return __uint_as_float(u << 16); }
; __device__ __forceinline__ float bfhi(unsigned u) { return __uint_as_float(u & 0xffff0000u); }
; __device__ __forceinline__ void retc_stream(const int wv, LAS unsigned char* lds, unsigned ldsb, const float* __restrict__ gn_g, const float* __restrict__ gn_b, const bf16_t* __restrict__ qkvr, const bf16_t* __restrict__ grb, const bf16_t* __restrict__ kv, ...
;     ...
; #pragma unroll
;             for (int k = 0; k < 16; ++k) {
;                 const int row = r0 + 8 * k;
;                 const u32x4 yv = *(const LAS u32x4*)(lds + row * 1024 + ((ch ^ (2 * ((row >> 2) & 3))) << 4));
;                 const u32x4 q = gv[k];
;                 u32x4 o;
;                 o.x = cvt_pk_bf16((bflo(yv.x) * g0[0] + b0[0]) * bflo(q.x), (bfhi(yv.x) * g0[1] + b0[1]) * bfhi(q.x));
;                 o.y = cvt_pk_bf16((bflo(yv.y) * g0[2] + b0[2]) * bflo(q.y), (bfhi(yv.y) * g0[3] + b0[3]) * bfhi(q.y));
;                 o.z = cvt_pk_bf16((bflo(yv.z) * g1[0] + b1[0]) * bflo(q.z), (bfhi(yv.z) * g1[1] + b1[1]) * bfhi(q.z));
;                 o.w = cvt_pk_bf16((bflo(yv.w) * g1[2] + b1[2]) * bflo(q.w), (bfhi(yv.w) * g1[3] + b1[3]) * bfhi(q.w));
;                 *(u32x4*)(orb + (size_t)(n * 128 + row) * 2048 + h * 512 + ch * 8) = o;
;             }
	ds_read_b128 v[86:89], v86
	s_waitcnt vmcnt(0)
	v_lshlrev_b32_e32 v93, 16, v82
	v_and_b32_e32 v82, 0xffff0000, v82
	v_readlane_b32 s2, v254, 35
	s_add_u32 s0, s2, s0
	s_waitcnt lgkmcnt(0)
	v_lshlrev_b32_e32 v92, 16, v86
	v_and_b32_e32 v86, 0xffff0000, v86
	v_fma_f32 v92, v10, v92, v14
	v_fma_f32 v86, v11, v86, v15
	v_mul_f32_e32 v92, v92, v93
	v_mul_f32_e32 v82, v86, v82
	v_lshlrev_b32_e32 v86, 16, v87
	v_and_b32_e32 v87, 0xffff0000, v87
	v_cvt_pk_bf16_f32 v82, v92, v82
	v_fma_f32 v86, v12, v86, v16
	v_lshlrev_b32_e32 v92, 16, v83
	v_fma_f32 v87, v13, v87, v17
	v_and_b32_e32 v83, 0xffff0000, v83
	v_mul_f32_e32 v86, v86, v92
	v_mul_f32_e32 v83, v87, v83
	v_cvt_pk_bf16_f32 v83, v86, v83
	v_lshlrev_b32_e32 v86, 16, v88
	v_fma_f32 v86, v2, v86, v6
	v_lshlrev_b32_e32 v87, 16, v84
	v_mul_f32_e32 v86, v86, v87
	v_and_b32_e32 v87, 0xffff0000, v88
	v_fma_f32 v87, v3, v87, v7
	v_and_b32_e32 v84, 0xffff0000, v84
	v_mul_f32_e32 v84, v87, v84
	v_cvt_pk_bf16_f32 v84, v86, v84
	v_lshlrev_b32_e32 v86, 16, v89
	v_fma_f32 v86, v4, v86, v8
	v_lshlrev_b32_e32 v87, 16, v85
	v_readlane_b32 s2, v254, 37
	v_mul_f32_e32 v86, v86, v87
	v_and_b32_e32 v87, 0xffff0000, v89
	s_addc_u32 s1, s2, s1
	v_fma_f32 v87, v5, v87, v9
	v_and_b32_e32 v85, 0xffff0000, v85
	v_lshl_add_u64 v[78:79], s[0:1], 0, v[78:79]
	v_mul_f32_e32 v85, v87, v85
	v_cvt_pk_bf16_f32 v85, v86, v85
	v_lshl_add_u64 v[86:87], v[78:79], 0, v[90:91]
	global_store_dwordx4 v[86:87], v[82:85], off
	v_add_u32_e32 v86, 8, v80
	v_lshlrev_b32_e32 v88, 16, v74
	v_lshrrev_b32_e32 v83, 1, v86
	v_bitop3_b32 v83, v83, v1, 6 bitop3:0x6c
	v_lshlrev_b32_e32 v82, 10, v86
	v_lshlrev_b32_e32 v83, 4, v83
	v_add3_u32 v82, 0, v82, v83
	ds_read_b128 v[82:85], v82
	v_and_b32_e32 v74, 0xffff0000, v74
	s_mov_b64 s[0:1], -1
	s_cmpk_gt_i32 s28, 0xff
	s_waitcnt lgkmcnt(0)
	v_lshlrev_b32_e32 v87, 16, v82
	v_and_b32_e32 v82, 0xffff0000, v82
	v_fma_f32 v87, v10, v87, v14
	v_fma_f32 v82, v11, v82, v15
	v_mul_f32_e32 v87, v87, v88
	v_mul_f32_e32 v74, v82, v74
	v_lshlrev_b32_e32 v82, 16, v83
	v_and_b32_e32 v83, 0xffff0000, v83
	v_cvt_pk_bf16_f32 v74, v87, v74
	v_fma_f32 v82, v12, v82, v16
	v_lshlrev_b32_e32 v87, 16, v75
	v_fma_f32 v83, v13, v83, v17
	v_and_b32_e32 v75, 0xffff0000, v75
	v_mul_f32_e32 v82, v82, v87
	v_mul_f32_e32 v75, v83, v75
	v_cvt_pk_bf16_f32 v75, v82, v75
	v_lshlrev_b32_e32 v82, 16, v84
	v_fma_f32 v82, v2, v82, v6
	v_lshlrev_b32_e32 v83, 16, v76
	v_mul_f32_e32 v82, v82, v83
	v_and_b32_e32 v83, 0xffff0000, v84
	v_fma_f32 v83, v3, v83, v7
	v_and_b32_e32 v76, 0xffff0000, v76
	v_mul_f32_e32 v76, v83, v76
	v_cvt_pk_bf16_f32 v76, v82, v76
	v_lshlrev_b32_e32 v82, 16, v85
	v_fma_f32 v82, v4, v82, v8
	v_lshlrev_b32_e32 v83, 16, v77
	v_mul_f32_e32 v82, v82, v83
	v_and_b32_e32 v83, 0xffff0000, v85
	v_fma_f32 v83, v5, v83, v9
	v_and_b32_e32 v77, 0xffff0000, v77
	v_mul_f32_e32 v77, v83, v77
	v_cvt_pk_bf16_f32 v77, v82, v77
	v_add_u32_e32 v82, s29, v86
	v_ashrrev_i32_e32 v83, 31, v82
	v_lshlrev_b64 v[82:83], 12, v[82:83]
	v_lshl_add_u64 v[82:83], v[78:79], 0, v[82:83]
	global_store_dwordx4 v[82:83], v[74:77], off
	v_add_u32_e32 v82, 16, v80
	v_lshlrev_b32_e32 v84, 16, v70
	v_lshlrev_b32_e32 v74, 10, v82
	v_add3_u32 v74, 0, v74, v81
	ds_read_b128 v[74:77], v74
	v_and_b32_e32 v70, 0xffff0000, v70
	s_waitcnt lgkmcnt(0)
	v_lshlrev_b32_e32 v83, 16, v74
	v_and_b32_e32 v74, 0xffff0000, v74
	v_fma_f32 v83, v10, v83, v14
	v_fma_f32 v74, v11, v74, v15
	v_mul_f32_e32 v83, v83, v84
	v_mul_f32_e32 v70, v74, v70
	v_lshlrev_b32_e32 v74, 16, v75
	v_and_b32_e32 v75, 0xffff0000, v75
	v_cvt_pk_bf16_f32 v70, v83, v70
	v_fma_f32 v74, v12, v74, v16
	v_lshlrev_b32_e32 v83, 16, v71
	v_fma_f32 v75, v13, v75, v17
	v_and_b32_e32 v71, 0xffff0000, v71
	v_mul_f32_e32 v74, v74, v83
	v_mul_f32_e32 v71, v75, v71
	v_cvt_pk_bf16_f32 v71, v74, v71
	v_lshlrev_b32_e32 v74, 16, v76
	v_fma_f32 v74, v2, v74, v6
	v_lshlrev_b32_e32 v75, 16, v72
	v_mul_f32_e32 v74, v74, v75
	v_and_b32_e32 v75, 0xffff0000, v76
	v_fma_f32 v75, v3, v75, v7
	v_and_b32_e32 v72, 0xffff0000, v72
	v_mul_f32_e32 v72, v75, v72
	v_cvt_pk_bf16_f32 v72, v74, v72
	v_lshlrev_b32_e32 v74, 16, v77
	v_fma_f32 v74, v4, v74, v8
	v_lshlrev_b32_e32 v75, 16, v73
	v_mul_f32_e32 v74, v74, v75
	v_and_b32_e32 v75, 0xffff0000, v77
	v_fma_f32 v75, v5, v75, v9
	v_and_b32_e32 v73, 0xffff0000, v73
	v_mul_f32_e32 v73, v75, v73
	v_cvt_pk_bf16_f32 v73, v74, v73
	v_add_u32_e32 v74, s29, v82
	v_ashrrev_i32_e32 v75, 31, v74
	v_lshlrev_b64 v[74:75], 12, v[74:75]
	v_lshl_add_u64 v[74:75], v[78:79], 0, v[74:75]
	global_store_dwordx4 v[74:75], v[70:73], off
	v_add_u32_e32 v74, 24, v80
	v_lshlrev_b32_e32 v76, 16, v66
	v_lshrrev_b32_e32 v71, 1, v74
	v_bitop3_b32 v71, v71, v1, 6 bitop3:0x6c
	v_lshlrev_b32_e32 v70, 10, v74
	v_lshlrev_b32_e32 v71, 4, v71
	v_add3_u32 v70, 0, v70, v71
	ds_read_b128 v[70:73], v70
	v_and_b32_e32 v66, 0xffff0000, v66
	s_waitcnt lgkmcnt(0)
	v_lshlrev_b32_e32 v75, 16, v70
	v_and_b32_e32 v70, 0xffff0000, v70
	v_fma_f32 v75, v10, v75, v14
	v_fma_f32 v70, v11, v70, v15
	v_mul_f32_e32 v75, v75, v76
	v_mul_f32_e32 v66, v70, v66
	v_lshlrev_b32_e32 v70, 16, v71
	v_and_b32_e32 v71, 0xffff0000, v71
	v_cvt_pk_bf16_f32 v66, v75, v66
	v_fma_f32 v70, v12, v70, v16
	v_lshlrev_b32_e32 v75, 16, v67
	v_fma_f32 v71, v13, v71, v17
	v_and_b32_e32 v67, 0xffff0000, v67
	v_mul_f32_e32 v70, v70, v75
	v_mul_f32_e32 v67, v71, v67
	v_cvt_pk_bf16_f32 v67, v70, v67
	v_lshlrev_b32_e32 v70, 16, v72
	v_fma_f32 v70, v2, v70, v6
	v_lshlrev_b32_e32 v71, 16, v68
	v_mul_f32_e32 v70, v70, v71
	v_and_b32_e32 v71, 0xffff0000, v72
	v_fma_f32 v71, v3, v71, v7
	v_and_b32_e32 v68, 0xffff0000, v68
	v_mul_f32_e32 v68, v71, v68
	v_cvt_pk_bf16_f32 v68, v70, v68
	v_lshlrev_b32_e32 v70, 16, v73
	v_fma_f32 v70, v4, v70, v8
	v_lshlrev_b32_e32 v71, 16, v69
	v_mul_f32_e32 v70, v70, v71
	v_and_b32_e32 v71, 0xffff0000, v73
	v_fma_f32 v71, v5, v71, v9
	v_and_b32_e32 v69, 0xffff0000, v69
	v_mul_f32_e32 v69, v71, v69
	v_cvt_pk_bf16_f32 v69, v70, v69
	v_add_u32_e32 v70, s29, v74
	v_ashrrev_i32_e32 v71, 31, v70
	v_lshlrev_b64 v[70:71], 12, v[70:71]
	v_lshl_add_u64 v[70:71], v[78:79], 0, v[70:71]
	global_store_dwordx4 v[70:71], v[66:69], off
	v_add_u32_e32 v70, 32, v80
	v_lshlrev_b32_e32 v72, 16, v62
	v_lshlrev_b32_e32 v66, 10, v70
	v_add3_u32 v66, 0, v66, v81
	ds_read_b128 v[66:69], v66
	v_and_b32_e32 v62, 0xffff0000, v62
	s_waitcnt lgkmcnt(0)
; #define LAS __attribute__((address_space(3)))
; __device__ __forceinline__ unsigned cvt_pk_bf16(float lo, float hi) { unsigned r; asm volatile("v_cvt_pk_bf16_f32 %0, %1, %2" : "=v"(r) : "v"(lo), "v"(hi)); return r; }
; __device__ __forceinline__ float bflo(unsigned u) { return __uint_as_float(u << 16); }
; __device__ __forceinline__ float bfhi(unsigned u) { return __uint_as_float(u & 0xffff0000u); }
; __device__ __forceinline__ void retc_stream(const int wv, LAS unsigned char* lds, unsigned ldsb, const float* __restrict__ gn_g, const float* __restrict__ gn_b, const bf16_t* __restrict__ qkvr, const bf16_t* __restrict__ grb, const bf16_t* __restrict__ kv, ...
;     ...
; #pragma unroll
;             for (int k = 0; k < 16; ++k) {
;                 const int row = r0 + 8 * k;
;                 const u32x4 yv = *(const LAS u32x4*)(lds + row * 1024 + ((ch ^ (2 * ((row >> 2) & 3))) << 4));
;                 const u32x4 q = gv[k];
;                 u32x4 o;
;                 o.x = cvt_pk_bf16((bflo(yv.x) * g0[0] + b0[0]) * bflo(q.x), (bfhi(yv.x) * g0[1] + b0[1]) * bfhi(q.x));
;                 o.y = cvt_pk_bf16((bflo(yv.y) * g0[2] + b0[2]) * bflo(q.y), (bfhi(yv.y) * g0[3] + b0[3]) * bfhi(q.y));
;                 o.z = cvt_pk_bf16((bflo(yv.z) * g1[0] + b1[0]) * bflo(q.z), (bfhi(yv.z) * g1[1] + b1[1]) * bfhi(q.z));
;                 o.w = cvt_pk_bf16((bflo(yv.w) * g1[2] + b1[2]) * bflo(q.w), (bfhi(yv.w) * g1[3] + b1[3]) * bfhi(q.w));
;                 *(u32x4*)(orb + (size_t)(n * 128 + row) * 2048 + h * 512 + ch * 8) = o;
;             }
	v_lshlrev_b32_e32 v71, 16, v66
	v_and_b32_e32 v66, 0xffff0000, v66
	v_fma_f32 v71, v10, v71, v14
	v_fma_f32 v66, v11, v66, v15
	v_mul_f32_e32 v71, v71, v72
	v_mul_f32_e32 v62, v66, v62
	v_lshlrev_b32_e32 v66, 16, v67
	v_and_b32_e32 v67, 0xffff0000, v67
	v_cvt_pk_bf16_f32 v62, v71, v62
	v_fma_f32 v66, v12, v66, v16
	v_lshlrev_b32_e32 v71, 16, v63
	v_fma_f32 v67, v13, v67, v17
	v_and_b32_e32 v63, 0xffff0000, v63
	v_mul_f32_e32 v66, v66, v71
	v_mul_f32_e32 v63, v67, v63
	v_cvt_pk_bf16_f32 v63, v66, v63
	v_lshlrev_b32_e32 v66, 16, v68
	v_fma_f32 v66, v2, v66, v6
	v_lshlrev_b32_e32 v67, 16, v64
	v_mul_f32_e32 v66, v66, v67
	v_and_b32_e32 v67, 0xffff0000, v68
	v_fma_f32 v67, v3, v67, v7
	v_and_b32_e32 v64, 0xffff0000, v64
	v_mul_f32_e32 v64, v67, v64
	v_cvt_pk_bf16_f32 v64, v66, v64
	v_lshlrev_b32_e32 v66, 16, v69
	v_fma_f32 v66, v4, v66, v8
	v_lshlrev_b32_e32 v67, 16, v65
	v_mul_f32_e32 v66, v66, v67
	v_and_b32_e32 v67, 0xffff0000, v69
	v_fma_f32 v67, v5, v67, v9
	v_and_b32_e32 v65, 0xffff0000, v65
	v_mul_f32_e32 v65, v67, v65
	v_cvt_pk_bf16_f32 v65, v66, v65
	v_add_u32_e32 v66, s29, v70
	v_ashrrev_i32_e32 v67, 31, v66
	v_lshlrev_b64 v[66:67], 12, v[66:67]
	v_lshl_add_u64 v[66:67], v[78:79], 0, v[66:67]
	global_store_dwordx4 v[66:67], v[62:65], off
	v_add_u32_e32 v66, 40, v80
	v_lshlrev_b32_e32 v68, 16, v58
	v_lshrrev_b32_e32 v63, 1, v66
	v_bitop3_b32 v63, v63, v1, 6 bitop3:0x6c
	v_lshlrev_b32_e32 v62, 10, v66
	v_lshlrev_b32_e32 v63, 4, v63
	v_add3_u32 v62, 0, v62, v63
	ds_read_b128 v[62:65], v62
	v_and_b32_e32 v58, 0xffff0000, v58
	s_waitcnt lgkmcnt(0)
	v_lshlrev_b32_e32 v67, 16, v62
	v_and_b32_e32 v62, 0xffff0000, v62
	v_fma_f32 v67, v10, v67, v14
	v_fma_f32 v62, v11, v62, v15
	v_mul_f32_e32 v67, v67, v68
	v_mul_f32_e32 v58, v62, v58
	v_lshlrev_b32_e32 v62, 16, v63
	v_and_b32_e32 v63, 0xffff0000, v63
	v_cvt_pk_bf16_f32 v58, v67, v58
	v_fma_f32 v62, v12, v62, v16
	v_lshlrev_b32_e32 v67, 16, v59
	v_fma_f32 v63, v13, v63, v17
	v_and_b32_e32 v59, 0xffff0000, v59
	v_mul_f32_e32 v62, v62, v67
	v_mul_f32_e32 v59, v63, v59
	v_cvt_pk_bf16_f32 v59, v62, v59
	v_lshlrev_b32_e32 v62, 16, v64
	v_fma_f32 v62, v2, v62, v6
	v_lshlrev_b32_e32 v63, 16, v60
	v_mul_f32_e32 v62, v62, v63
	v_and_b32_e32 v63, 0xffff0000, v64
	v_fma_f32 v63, v3, v63, v7
	v_and_b32_e32 v60, 0xffff0000, v60
	v_mul_f32_e32 v60, v63, v60
	v_cvt_pk_bf16_f32 v60, v62, v60
	v_lshlrev_b32_e32 v62, 16, v65
	v_fma_f32 v62, v4, v62, v8
	v_lshlrev_b32_e32 v63, 16, v61
	v_mul_f32_e32 v62, v62, v63
	v_and_b32_e32 v63, 0xffff0000, v65
	v_fma_f32 v63, v5, v63, v9
	v_and_b32_e32 v61, 0xffff0000, v61
	v_mul_f32_e32 v61, v63, v61
	v_cvt_pk_bf16_f32 v61, v62, v61
	v_add_u32_e32 v62, s29, v66
	v_ashrrev_i32_e32 v63, 31, v62
	v_lshlrev_b64 v[62:63], 12, v[62:63]
	v_lshl_add_u64 v[62:63], v[78:79], 0, v[62:63]
	global_store_dwordx4 v[62:63], v[58:61], off
	v_add_u32_e32 v62, 48, v80
	v_lshlrev_b32_e32 v64, 16, v54
	v_lshlrev_b32_e32 v58, 10, v62
	v_add3_u32 v58, 0, v58, v81
	ds_read_b128 v[58:61], v58
	v_and_b32_e32 v54, 0xffff0000, v54
	s_waitcnt lgkmcnt(0)
	v_lshlrev_b32_e32 v63, 16, v58
	v_and_b32_e32 v58, 0xffff0000, v58
	v_fma_f32 v63, v10, v63, v14
	v_fma_f32 v58, v11, v58, v15
	v_mul_f32_e32 v63, v63, v64
	v_mul_f32_e32 v54, v58, v54
	v_lshlrev_b32_e32 v58, 16, v59
	v_and_b32_e32 v59, 0xffff0000, v59
	v_cvt_pk_bf16_f32 v54, v63, v54
	v_fma_f32 v58, v12, v58, v16
	v_lshlrev_b32_e32 v63, 16, v55
	v_fma_f32 v59, v13, v59, v17
	v_and_b32_e32 v55, 0xffff0000, v55
	v_mul_f32_e32 v58, v58, v63
	v_mul_f32_e32 v55, v59, v55
	v_cvt_pk_bf16_f32 v55, v58, v55
	v_lshlrev_b32_e32 v58, 16, v60
	v_fma_f32 v58, v2, v58, v6
	v_lshlrev_b32_e32 v59, 16, v56
	v_mul_f32_e32 v58, v58, v59
	v_and_b32_e32 v59, 0xffff0000, v60
	v_fma_f32 v59, v3, v59, v7
	v_and_b32_e32 v56, 0xffff0000, v56
	v_mul_f32_e32 v56, v59, v56
	v_cvt_pk_bf16_f32 v56, v58, v56
	v_lshlrev_b32_e32 v58, 16, v61
	v_fma_f32 v58, v4, v58, v8
	v_lshlrev_b32_e32 v59, 16, v57
	v_mul_f32_e32 v58, v58, v59
	v_and_b32_e32 v59, 0xffff0000, v61
	v_fma_f32 v59, v5, v59, v9
	v_and_b32_e32 v57, 0xffff0000, v57
	v_mul_f32_e32 v57, v59, v57
	v_cvt_pk_bf16_f32 v57, v58, v57
	v_add_u32_e32 v58, s29, v62
	v_ashrrev_i32_e32 v59, 31, v58
	v_lshlrev_b64 v[58:59], 12, v[58:59]
	v_lshl_add_u64 v[58:59], v[78:79], 0, v[58:59]
	global_store_dwordx4 v[58:59], v[54:57], off
	v_add_u32_e32 v58, 56, v80
	v_lshlrev_b32_e32 v60, 16, v50
	v_lshrrev_b32_e32 v55, 1, v58
	v_bitop3_b32 v55, v55, v1, 6 bitop3:0x6c
	v_lshlrev_b32_e32 v54, 10, v58
	v_lshlrev_b32_e32 v55, 4, v55
	v_add3_u32 v54, 0, v54, v55
	ds_read_b128 v[54:57], v54
	v_and_b32_e32 v50, 0xffff0000, v50
	s_waitcnt lgkmcnt(0)
	v_lshlrev_b32_e32 v59, 16, v54
	v_and_b32_e32 v54, 0xffff0000, v54
	v_fma_f32 v59, v10, v59, v14
	v_fma_f32 v54, v11, v54, v15
	v_mul_f32_e32 v59, v59, v60
	v_mul_f32_e32 v50, v54, v50
	v_lshlrev_b32_e32 v54, 16, v55
	v_and_b32_e32 v55, 0xffff0000, v55
	v_cvt_pk_bf16_f32 v50, v59, v50
	v_fma_f32 v54, v12, v54, v16
	v_lshlrev_b32_e32 v59, 16, v51
	v_fma_f32 v55, v13, v55, v17
	v_and_b32_e32 v51, 0xffff0000, v51
	v_mul_f32_e32 v54, v54, v59
	v_mul_f32_e32 v51, v55, v51
	v_cvt_pk_bf16_f32 v51, v54, v51
	v_lshlrev_b32_e32 v54, 16, v56
	v_fma_f32 v54, v2, v54, v6
	v_lshlrev_b32_e32 v55, 16, v52
	v_mul_f32_e32 v54, v54, v55
	v_and_b32_e32 v55, 0xffff0000, v56
	v_fma_f32 v55, v3, v55, v7
	v_and_b32_e32 v52, 0xffff0000, v52
	v_mul_f32_e32 v52, v55, v52
	v_cvt_pk_bf16_f32 v52, v54, v52
	v_lshlrev_b32_e32 v54, 16, v57
	v_fma_f32 v54, v4, v54, v8
	v_lshlrev_b32_e32 v55, 16, v53
	v_mul_f32_e32 v54, v54, v55
	v_and_b32_e32 v55, 0xffff0000, v57
	v_fma_f32 v55, v5, v55, v9
	v_and_b32_e32 v53, 0xffff0000, v53
	v_mul_f32_e32 v53, v55, v53
	v_cvt_pk_bf16_f32 v53, v54, v53
	v_add_u32_e32 v54, s29, v58
	v_ashrrev_i32_e32 v55, 31, v54
	v_lshlrev_b64 v[54:55], 12, v[54:55]
	v_lshl_add_u64 v[54:55], v[78:79], 0, v[54:55]
	global_store_dwordx4 v[54:55], v[50:53], off
	v_add_u32_e32 v54, 64, v80
	v_lshlrev_b32_e32 v56, 16, v46
	v_lshlrev_b32_e32 v50, 10, v54
	v_add3_u32 v50, 0, v50, v81
	ds_read_b128 v[50:53], v50
	v_and_b32_e32 v46, 0xffff0000, v46
	s_waitcnt lgkmcnt(0)
; #define LAS __attribute__((address_space(3)))
; __device__ __forceinline__ unsigned cvt_pk_bf16(float lo, float hi) { unsigned r; asm volatile("v_cvt_pk_bf16_f32 %0, %1, %2" : "=v"(r) : "v"(lo), "v"(hi)); return r; }
; __device__ __forceinline__ float bflo(unsigned u) { return __uint_as_float(u << 16); }
; __device__ __forceinline__ float bfhi(unsigned u) { return __uint_as_float(u & 0xffff0000u); }
; __device__ __forceinline__ void retc_stream(const int wv, LAS unsigned char* lds, unsigned ldsb, const float* __restrict__ gn_g, const float* __restrict__ gn_b, const bf16_t* __restrict__ qkvr, const bf16_t* __restrict__ grb, const bf16_t* __restrict__ kv, ...
;     ...
; #pragma unroll
;             for (int k = 0; k < 16; ++k) {
;                 const int row = r0 + 8 * k;
;                 const u32x4 yv = *(const LAS u32x4*)(lds + row * 1024 + ((ch ^ (2 * ((row >> 2) & 3))) << 4));
;                 const u32x4 q = gv[k];
;                 u32x4 o;
;                 o.x = cvt_pk_bf16((bflo(yv.x) * g0[0] + b0[0]) * bflo(q.x), (bfhi(yv.x) * g0[1] + b0[1]) * bfhi(q.x));
;                 o.y = cvt_pk_bf16((bflo(yv.y) * g0[2] + b0[2]) * bflo(q.y), (bfhi(yv.y) * g0[3] + b0[3]) * bfhi(q.y));
;                 o.z = cvt_pk_bf16((bflo(yv.z) * g1[0] + b1[0]) * bflo(q.z), (bfhi(yv.z) * g1[1] + b1[1]) * bfhi(q.z));
;                 o.w = cvt_pk_bf16((bflo(yv.w) * g1[2] + b1[2]) * bflo(q.w), (bfhi(yv.w) * g1[3] + b1[3]) * bfhi(q.w));
;                 *(u32x4*)(orb + (size_t)(n * 128 + row) * 2048 + h * 512 + ch * 8) = o;
;             }
	v_lshlrev_b32_e32 v55, 16, v50
	v_and_b32_e32 v50, 0xffff0000, v50
	v_fma_f32 v55, v10, v55, v14
	v_fma_f32 v50, v11, v50, v15
	v_mul_f32_e32 v55, v55, v56
	v_mul_f32_e32 v46, v50, v46
	v_lshlrev_b32_e32 v50, 16, v51
	v_and_b32_e32 v51, 0xffff0000, v51
	v_cvt_pk_bf16_f32 v46, v55, v46
	v_fma_f32 v50, v12, v50, v16
	v_lshlrev_b32_e32 v55, 16, v47
	v_fma_f32 v51, v13, v51, v17
	v_and_b32_e32 v47, 0xffff0000, v47
	v_mul_f32_e32 v50, v50, v55
	v_mul_f32_e32 v47, v51, v47
	v_cvt_pk_bf16_f32 v47, v50, v47
	v_lshlrev_b32_e32 v50, 16, v52
	v_fma_f32 v50, v2, v50, v6
	v_lshlrev_b32_e32 v51, 16, v48
	v_mul_f32_e32 v50, v50, v51
	v_and_b32_e32 v51, 0xffff0000, v52
	v_fma_f32 v51, v3, v51, v7
	v_and_b32_e32 v48, 0xffff0000, v48
	v_mul_f32_e32 v48, v51, v48
	v_cvt_pk_bf16_f32 v48, v50, v48
	v_lshlrev_b32_e32 v50, 16, v53
	v_fma_f32 v50, v4, v50, v8
	v_lshlrev_b32_e32 v51, 16, v49
	v_mul_f32_e32 v50, v50, v51
	v_and_b32_e32 v51, 0xffff0000, v53
	v_fma_f32 v51, v5, v51, v9
	v_and_b32_e32 v49, 0xffff0000, v49
	v_mul_f32_e32 v49, v51, v49
	v_cvt_pk_bf16_f32 v49, v50, v49
	v_add_u32_e32 v50, s29, v54
	v_ashrrev_i32_e32 v51, 31, v50
	v_lshlrev_b64 v[50:51], 12, v[50:51]
	v_lshl_add_u64 v[50:51], v[78:79], 0, v[50:51]
	global_store_dwordx4 v[50:51], v[46:49], off
	v_add_u32_e32 v50, 0x48, v80
	v_lshlrev_b32_e32 v52, 16, v42
	v_lshrrev_b32_e32 v47, 1, v50
	v_bitop3_b32 v47, v47, v1, 6 bitop3:0x6c
	v_lshlrev_b32_e32 v46, 10, v50
	v_lshlrev_b32_e32 v47, 4, v47
	v_add3_u32 v46, 0, v46, v47
	ds_read_b128 v[46:49], v46
	v_and_b32_e32 v42, 0xffff0000, v42
	s_waitcnt lgkmcnt(0)
	v_lshlrev_b32_e32 v51, 16, v46
	v_and_b32_e32 v46, 0xffff0000, v46
	v_fma_f32 v51, v10, v51, v14
	v_fma_f32 v46, v11, v46, v15
	v_mul_f32_e32 v51, v51, v52
	v_mul_f32_e32 v42, v46, v42
	v_lshlrev_b32_e32 v46, 16, v47
	v_and_b32_e32 v47, 0xffff0000, v47
	v_cvt_pk_bf16_f32 v42, v51, v42
	v_fma_f32 v46, v12, v46, v16
	v_lshlrev_b32_e32 v51, 16, v43
	v_fma_f32 v47, v13, v47, v17
	v_and_b32_e32 v43, 0xffff0000, v43
	v_mul_f32_e32 v46, v46, v51
	v_mul_f32_e32 v43, v47, v43
	v_cvt_pk_bf16_f32 v43, v46, v43
	v_lshlrev_b32_e32 v46, 16, v48
	v_fma_f32 v46, v2, v46, v6
	v_lshlrev_b32_e32 v47, 16, v44
	v_mul_f32_e32 v46, v46, v47
	v_and_b32_e32 v47, 0xffff0000, v48
	v_fma_f32 v47, v3, v47, v7
	v_and_b32_e32 v44, 0xffff0000, v44
	v_mul_f32_e32 v44, v47, v44
	v_cvt_pk_bf16_f32 v44, v46, v44
	v_lshlrev_b32_e32 v46, 16, v49
	v_fma_f32 v46, v4, v46, v8
	v_lshlrev_b32_e32 v47, 16, v45
	v_mul_f32_e32 v46, v46, v47
	v_and_b32_e32 v47, 0xffff0000, v49
	v_fma_f32 v47, v5, v47, v9
	v_and_b32_e32 v45, 0xffff0000, v45
	v_mul_f32_e32 v45, v47, v45
	v_cvt_pk_bf16_f32 v45, v46, v45
	v_add_u32_e32 v46, s29, v50
	v_ashrrev_i32_e32 v47, 31, v46
	v_lshlrev_b64 v[46:47], 12, v[46:47]
	v_lshl_add_u64 v[46:47], v[78:79], 0, v[46:47]
	global_store_dwordx4 v[46:47], v[42:45], off
	v_add_u32_e32 v46, 0x50, v80
	v_lshlrev_b32_e32 v48, 16, v38
	v_lshlrev_b32_e32 v42, 10, v46
	v_add3_u32 v42, 0, v42, v81
	ds_read_b128 v[42:45], v42
	v_and_b32_e32 v38, 0xffff0000, v38
	s_waitcnt lgkmcnt(0)
	v_lshlrev_b32_e32 v47, 16, v42
	v_and_b32_e32 v42, 0xffff0000, v42
	v_fma_f32 v47, v10, v47, v14
	v_fma_f32 v42, v11, v42, v15
	v_mul_f32_e32 v47, v47, v48
	v_mul_f32_e32 v38, v42, v38
	v_lshlrev_b32_e32 v42, 16, v43
	v_and_b32_e32 v43, 0xffff0000, v43
	v_cvt_pk_bf16_f32 v38, v47, v38
	v_fma_f32 v42, v12, v42, v16
	v_lshlrev_b32_e32 v47, 16, v39
	v_fma_f32 v43, v13, v43, v17
	v_and_b32_e32 v39, 0xffff0000, v39
	v_mul_f32_e32 v42, v42, v47
	v_mul_f32_e32 v39, v43, v39
	v_cvt_pk_bf16_f32 v39, v42, v39
	v_lshlrev_b32_e32 v42, 16, v44
	v_fma_f32 v42, v2, v42, v6
	v_lshlrev_b32_e32 v43, 16, v40
	v_mul_f32_e32 v42, v42, v43
	v_and_b32_e32 v43, 0xffff0000, v44
	v_fma_f32 v43, v3, v43, v7
	v_and_b32_e32 v40, 0xffff0000, v40
	v_mul_f32_e32 v40, v43, v40
	v_cvt_pk_bf16_f32 v40, v42, v40
	v_lshlrev_b32_e32 v42, 16, v45
	v_fma_f32 v42, v4, v42, v8
	v_lshlrev_b32_e32 v43, 16, v41
	v_mul_f32_e32 v42, v42, v43
	v_and_b32_e32 v43, 0xffff0000, v45
	v_fma_f32 v43, v5, v43, v9
	v_and_b32_e32 v41, 0xffff0000, v41
	v_mul_f32_e32 v41, v43, v41
	v_cvt_pk_bf16_f32 v41, v42, v41
	v_add_u32_e32 v42, s29, v46
	v_ashrrev_i32_e32 v43, 31, v42
	v_lshlrev_b64 v[42:43], 12, v[42:43]
	v_lshl_add_u64 v[42:43], v[78:79], 0, v[42:43]
	global_store_dwordx4 v[42:43], v[38:41], off
	v_add_u32_e32 v42, 0x58, v80
	v_lshlrev_b32_e32 v44, 16, v34
	v_lshrrev_b32_e32 v39, 1, v42
	v_bitop3_b32 v39, v39, v1, 6 bitop3:0x6c
	v_lshlrev_b32_e32 v38, 10, v42
	v_lshlrev_b32_e32 v39, 4, v39
	v_add3_u32 v38, 0, v38, v39
	ds_read_b128 v[38:41], v38
	v_and_b32_e32 v34, 0xffff0000, v34
	s_waitcnt lgkmcnt(0)
	v_lshlrev_b32_e32 v43, 16, v38
	v_and_b32_e32 v38, 0xffff0000, v38
	v_fma_f32 v43, v10, v43, v14
	v_fma_f32 v38, v11, v38, v15
	v_mul_f32_e32 v43, v43, v44
	v_mul_f32_e32 v34, v38, v34
	v_lshlrev_b32_e32 v38, 16, v39
	v_and_b32_e32 v39, 0xffff0000, v39
	v_cvt_pk_bf16_f32 v34, v43, v34
	v_fma_f32 v38, v12, v38, v16
	v_lshlrev_b32_e32 v43, 16, v35
	v_fma_f32 v39, v13, v39, v17
	v_and_b32_e32 v35, 0xffff0000, v35
	v_mul_f32_e32 v38, v38, v43
	v_mul_f32_e32 v35, v39, v35
	v_cvt_pk_bf16_f32 v35, v38, v35
	v_lshlrev_b32_e32 v38, 16, v40
	v_fma_f32 v38, v2, v38, v6
	v_lshlrev_b32_e32 v39, 16, v36
	v_mul_f32_e32 v38, v38, v39
	v_and_b32_e32 v39, 0xffff0000, v40
	v_fma_f32 v39, v3, v39, v7
	v_and_b32_e32 v36, 0xffff0000, v36
	v_mul_f32_e32 v36, v39, v36
	v_cvt_pk_bf16_f32 v36, v38, v36
	v_lshlrev_b32_e32 v38, 16, v41
	v_fma_f32 v38, v4, v38, v8
	v_lshlrev_b32_e32 v39, 16, v37
	v_mul_f32_e32 v38, v38, v39
	v_and_b32_e32 v39, 0xffff0000, v41
	v_fma_f32 v39, v5, v39, v9
	v_and_b32_e32 v37, 0xffff0000, v37
	v_mul_f32_e32 v37, v39, v37
	v_cvt_pk_bf16_f32 v37, v38, v37
	v_add_u32_e32 v38, s29, v42
	v_ashrrev_i32_e32 v39, 31, v38
	v_lshlrev_b64 v[38:39], 12, v[38:39]
	v_lshl_add_u64 v[38:39], v[78:79], 0, v[38:39]
	global_store_dwordx4 v[38:39], v[34:37], off
	v_add_u32_e32 v38, 0x60, v80
	v_lshlrev_b32_e32 v40, 16, v30
	v_lshlrev_b32_e32 v34, 10, v38
	v_add3_u32 v34, 0, v34, v81
	ds_read_b128 v[34:37], v34
	v_and_b32_e32 v30, 0xffff0000, v30
	s_waitcnt lgkmcnt(0)
; #define LAS __attribute__((address_space(3)))
; __device__ __forceinline__ unsigned cvt_pk_bf16(float lo, float hi) { unsigned r; asm volatile("v_cvt_pk_bf16_f32 %0, %1, %2" : "=v"(r) : "v"(lo), "v"(hi)); return r; }
; __device__ __forceinline__ float bflo(unsigned u) { return __uint_as_float(u << 16); }
; __device__ __forceinline__ float bfhi(unsigned u) { return __uint_as_float(u & 0xffff0000u); }
; __device__ __forceinline__ void retc_stream(const int wv, LAS unsigned char* lds, unsigned ldsb, const float* __restrict__ gn_g, const float* __restrict__ gn_b, const bf16_t* __restrict__ qkvr, const bf16_t* __restrict__ grb, const bf16_t* __restrict__ kv, ...
;     ...
; #pragma unroll
;             for (int k = 0; k < 16; ++k) {
;                 const int row = r0 + 8 * k;
;                 const u32x4 yv = *(const LAS u32x4*)(lds + row * 1024 + ((ch ^ (2 * ((row >> 2) & 3))) << 4));
;                 const u32x4 q = gv[k];
;                 u32x4 o;
;                 o.x = cvt_pk_bf16((bflo(yv.x) * g0[0] + b0[0]) * bflo(q.x), (bfhi(yv.x) * g0[1] + b0[1]) * bfhi(q.x));
;                 o.y = cvt_pk_bf16((bflo(yv.y) * g0[2] + b0[2]) * bflo(q.y), (bfhi(yv.y) * g0[3] + b0[3]) * bfhi(q.y));
;                 o.z = cvt_pk_bf16((bflo(yv.z) * g1[0] + b1[0]) * bflo(q.z), (bfhi(yv.z) * g1[1] + b1[1]) * bfhi(q.z));
;                 o.w = cvt_pk_bf16((bflo(yv.w) * g1[2] + b1[2]) * bflo(q.w), (bfhi(yv.w) * g1[3] + b1[3]) * bfhi(q.w));
;                 *(u32x4*)(orb + (size_t)(n * 128 + row) * 2048 + h * 512 + ch * 8) = o;
;             }
	v_lshlrev_b32_e32 v39, 16, v34
	v_and_b32_e32 v34, 0xffff0000, v34
	v_fma_f32 v39, v10, v39, v14
	v_fma_f32 v34, v11, v34, v15
	v_mul_f32_e32 v39, v39, v40
	v_mul_f32_e32 v30, v34, v30
	v_lshlrev_b32_e32 v34, 16, v35
	v_and_b32_e32 v35, 0xffff0000, v35
	v_cvt_pk_bf16_f32 v30, v39, v30
	v_fma_f32 v34, v12, v34, v16
	v_lshlrev_b32_e32 v39, 16, v31
	v_fma_f32 v35, v13, v35, v17
	v_and_b32_e32 v31, 0xffff0000, v31
	v_mul_f32_e32 v34, v34, v39
	v_mul_f32_e32 v31, v35, v31
	v_cvt_pk_bf16_f32 v31, v34, v31
	v_lshlrev_b32_e32 v34, 16, v36
	v_fma_f32 v34, v2, v34, v6
	v_lshlrev_b32_e32 v35, 16, v32
	v_mul_f32_e32 v34, v34, v35
	v_and_b32_e32 v35, 0xffff0000, v36
	v_fma_f32 v35, v3, v35, v7
	v_and_b32_e32 v32, 0xffff0000, v32
	v_mul_f32_e32 v32, v35, v32
	v_cvt_pk_bf16_f32 v32, v34, v32
	v_lshlrev_b32_e32 v34, 16, v37
	v_fma_f32 v34, v4, v34, v8
	v_lshlrev_b32_e32 v35, 16, v33
	v_mul_f32_e32 v34, v34, v35
	v_and_b32_e32 v35, 0xffff0000, v37
	v_fma_f32 v35, v5, v35, v9
	v_and_b32_e32 v33, 0xffff0000, v33
	v_mul_f32_e32 v33, v35, v33
	v_cvt_pk_bf16_f32 v33, v34, v33
	v_add_u32_e32 v34, s29, v38
	v_ashrrev_i32_e32 v35, 31, v34
	v_lshlrev_b64 v[34:35], 12, v[34:35]
	v_lshl_add_u64 v[34:35], v[78:79], 0, v[34:35]
	global_store_dwordx4 v[34:35], v[30:33], off
	v_add_u32_e32 v34, 0x68, v80
	v_lshlrev_b32_e32 v36, 16, v26
	v_lshrrev_b32_e32 v31, 1, v34
	v_bitop3_b32 v31, v31, v1, 6 bitop3:0x6c
	v_lshlrev_b32_e32 v30, 10, v34
	v_lshlrev_b32_e32 v31, 4, v31
	v_add3_u32 v30, 0, v30, v31
	ds_read_b128 v[30:33], v30
	v_and_b32_e32 v26, 0xffff0000, v26
	s_waitcnt lgkmcnt(0)
	v_lshlrev_b32_e32 v35, 16, v30
	v_and_b32_e32 v30, 0xffff0000, v30
	v_fma_f32 v35, v10, v35, v14
	v_fma_f32 v30, v11, v30, v15
	v_mul_f32_e32 v35, v35, v36
	v_mul_f32_e32 v26, v30, v26
	v_lshlrev_b32_e32 v30, 16, v31
	v_and_b32_e32 v31, 0xffff0000, v31
	v_cvt_pk_bf16_f32 v26, v35, v26
	v_fma_f32 v30, v12, v30, v16
	v_lshlrev_b32_e32 v35, 16, v27
	v_fma_f32 v31, v13, v31, v17
	v_and_b32_e32 v27, 0xffff0000, v27
	v_mul_f32_e32 v30, v30, v35
	v_mul_f32_e32 v27, v31, v27
	v_cvt_pk_bf16_f32 v27, v30, v27
	v_lshlrev_b32_e32 v30, 16, v32
	v_fma_f32 v30, v2, v30, v6
	v_lshlrev_b32_e32 v31, 16, v28
	v_mul_f32_e32 v30, v30, v31
	v_and_b32_e32 v31, 0xffff0000, v32
	v_fma_f32 v31, v3, v31, v7
	v_and_b32_e32 v28, 0xffff0000, v28
	v_mul_f32_e32 v28, v31, v28
	v_cvt_pk_bf16_f32 v28, v30, v28
	v_lshlrev_b32_e32 v30, 16, v33
	v_fma_f32 v30, v4, v30, v8
	v_lshlrev_b32_e32 v31, 16, v29
	v_mul_f32_e32 v30, v30, v31
	v_and_b32_e32 v31, 0xffff0000, v33
	v_fma_f32 v31, v5, v31, v9
	v_and_b32_e32 v29, 0xffff0000, v29
	v_mul_f32_e32 v29, v31, v29
	v_cvt_pk_bf16_f32 v29, v30, v29
	v_add_u32_e32 v30, s29, v34
	v_ashrrev_i32_e32 v31, 31, v30
	v_lshlrev_b64 v[30:31], 12, v[30:31]
	v_lshl_add_u64 v[30:31], v[78:79], 0, v[30:31]
	global_store_dwordx4 v[30:31], v[26:29], off
	v_add_u32_e32 v30, 0x70, v80
	v_lshlrev_b32_e32 v32, 16, v22
	v_lshlrev_b32_e32 v26, 10, v30
	v_add3_u32 v26, 0, v26, v81
	ds_read_b128 v[26:29], v26
	v_and_b32_e32 v22, 0xffff0000, v22
	s_waitcnt lgkmcnt(0)
	v_lshlrev_b32_e32 v31, 16, v26
	v_and_b32_e32 v26, 0xffff0000, v26
	v_fma_f32 v31, v10, v31, v14
	v_fma_f32 v26, v11, v26, v15
	v_mul_f32_e32 v31, v31, v32
	v_mul_f32_e32 v22, v26, v22
	v_lshlrev_b32_e32 v26, 16, v27
	v_and_b32_e32 v27, 0xffff0000, v27
	v_cvt_pk_bf16_f32 v22, v31, v22
	v_fma_f32 v26, v12, v26, v16
	v_lshlrev_b32_e32 v31, 16, v23
	v_fma_f32 v27, v13, v27, v17
	v_and_b32_e32 v23, 0xffff0000, v23
	v_mul_f32_e32 v26, v26, v31
	v_mul_f32_e32 v23, v27, v23
	v_cvt_pk_bf16_f32 v23, v26, v23
	v_lshlrev_b32_e32 v26, 16, v28
	v_fma_f32 v26, v2, v26, v6
	v_lshlrev_b32_e32 v27, 16, v24
	v_mul_f32_e32 v26, v26, v27
	v_and_b32_e32 v27, 0xffff0000, v28
	v_fma_f32 v27, v3, v27, v7
	v_and_b32_e32 v24, 0xffff0000, v24
	v_mul_f32_e32 v24, v27, v24
	v_cvt_pk_bf16_f32 v24, v26, v24
	v_lshlrev_b32_e32 v26, 16, v29
	v_fma_f32 v26, v4, v26, v8
	v_lshlrev_b32_e32 v27, 16, v25
	v_mul_f32_e32 v26, v26, v27
	v_and_b32_e32 v27, 0xffff0000, v29
	v_fma_f32 v27, v5, v27, v9
	v_and_b32_e32 v25, 0xffff0000, v25
	v_mul_f32_e32 v25, v27, v25
	v_cvt_pk_bf16_f32 v25, v26, v25
	v_add_u32_e32 v26, s29, v30
	v_ashrrev_i32_e32 v27, 31, v26
	v_lshlrev_b64 v[26:27], 12, v[26:27]
	v_lshl_add_u64 v[26:27], v[78:79], 0, v[26:27]
	global_store_dwordx4 v[26:27], v[22:25], off
	v_add_u32_e32 v26, 0x78, v80
	s_nop 0
	v_lshrrev_b32_e32 v23, 1, v26
	v_bitop3_b32 v1, v23, v1, 6 bitop3:0x6c
	v_lshlrev_b32_e32 v22, 10, v26
	v_lshlrev_b32_e32 v1, 4, v1
	v_add3_u32 v1, 0, v22, v1
	ds_read_b128 v[22:25], v1
	s_waitcnt lgkmcnt(0)
	v_lshlrev_b32_e32 v1, 16, v22
	v_fma_f32 v1, v10, v1, v14
	v_lshlrev_b32_e32 v10, 16, v18
	v_mul_f32_e32 v1, v1, v10
	v_and_b32_e32 v10, 0xffff0000, v22
	v_fma_f32 v10, v11, v10, v15
	v_and_b32_e32 v11, 0xffff0000, v18
	v_mul_f32_e32 v10, v10, v11
	v_cvt_pk_bf16_f32 v10, v1, v10
	v_lshlrev_b32_e32 v1, 16, v23
	v_fma_f32 v1, v12, v1, v16
	v_lshlrev_b32_e32 v11, 16, v19
	v_mul_f32_e32 v1, v1, v11
	v_and_b32_e32 v11, 0xffff0000, v23
	v_fmac_f32_e32 v17, v13, v11
	v_and_b32_e32 v11, 0xffff0000, v19
	v_mul_f32_e32 v11, v17, v11
	v_cvt_pk_bf16_f32 v11, v1, v11
	v_lshlrev_b32_e32 v1, 16, v24
	v_fma_f32 v1, v2, v1, v6
	v_lshlrev_b32_e32 v2, 16, v20
	v_mul_f32_e32 v1, v1, v2
	v_and_b32_e32 v2, 0xffff0000, v24
	v_fma_f32 v2, v3, v2, v7
	v_and_b32_e32 v3, 0xffff0000, v20
	v_mul_f32_e32 v2, v2, v3
	v_cvt_pk_bf16_f32 v12, v1, v2
	v_lshlrev_b32_e32 v1, 16, v25
	v_fma_f32 v1, v4, v1, v8
	v_lshlrev_b32_e32 v2, 16, v21
	v_mul_f32_e32 v1, v1, v2
	v_and_b32_e32 v2, 0xffff0000, v25
	v_fmac_f32_e32 v9, v5, v2
	v_and_b32_e32 v2, 0xffff0000, v21
	v_mul_f32_e32 v2, v9, v2
	v_cvt_pk_bf16_f32 v13, v1, v2
	v_add_u32_e32 v2, s29, v26
	v_ashrrev_i32_e32 v3, 31, v2
	v_lshlrev_b64 v[2:3], 12, v[2:3]
	v_lshl_add_u64 v[2:3], v[78:79], 0, v[2:3]
	global_store_dwordx4 v[2:3], v[10:13], off
	s_cbranch_scc1 .LBB0_468
; #define LBAR() do { asm volatile("s_waitcnt lgkmcnt(0)" ::: "memory"); __builtin_amdgcn_s_barrier(); asm volatile("" ::: "memory"); } while (0)
; __device__ __forceinline__ void retc_stream(const int wv, LAS unsigned char* lds, unsigned ldsb, const float* __restrict__ gn_g, const float* __restrict__ gn_b, const bf16_t* __restrict__ qkvr, const bf16_t* __restrict__ grb, const bf16_t* __restrict__ kv, ...
;     ...
;         if (inext >= count) break;
;         LBAR();
;         RETC_ISSUE(inext, 0);
;         item = inext;
	s_and_b32 s1, s60, 0x1f80
	s_and_b32 s0, s61, 0xffffff00
	s_mulk_i32 s1, 0x4400
	s_add_u32 s2, s82, s1
	s_addc_u32 s3, s39, 0
	s_ashr_i32 s1, s0, 31
	s_lshl_b64 s[0:1], s[0:1], 1
	s_add_u32 s0, s2, s0
	s_addc_u32 s1, s3, s1
	v_lshl_add_u64 v[2:3], s[0:1], 0, v[180:181]
	s_mov_b64 s[0:1], 0x2400
	s_mov_b32 m0, s58
	s_waitcnt lgkmcnt(0)
	s_barrier
	v_lshl_add_u64 v[4:5], v[2:3], 0, s[0:1]
	s_mov_b64 s[0:1], 0x46400
	global_load_lds_dwordx4 v[4:5], off nt
	v_lshl_add_u64 v[4:5], v[2:3], 0, s[0:1]
	s_mov_b32 m0, s47
	s_mov_b64 s[0:1], 0x8a400
	global_load_lds_dwordx4 v[4:5], off nt
	v_lshl_add_u64 v[4:5], v[2:3], 0, s[0:1]
	s_mov_b32 m0, s24
	s_mov_b64 s[0:1], 0xce400
	global_load_lds_dwordx4 v[4:5], off nt
	v_lshl_add_u64 v[4:5], v[2:3], 0, s[0:1]
	s_mov_b32 m0, s25
	s_mov_b64 s[0:1], 0x112400
	global_load_lds_dwordx4 v[4:5], off nt
	v_lshl_add_u64 v[4:5], v[2:3], 0, s[0:1]
	s_mov_b32 m0, s48
	s_mov_b64 s[0:1], 0x156400
	global_load_lds_dwordx4 v[4:5], off nt
	v_lshl_add_u64 v[4:5], v[2:3], 0, s[0:1]
	s_mov_b32 m0, s49
	s_mov_b64 s[0:1], 0x19a400
	global_load_lds_dwordx4 v[4:5], off nt
	v_lshl_add_u64 v[4:5], v[2:3], 0, s[0:1]
	s_mov_b32 m0, s50
	s_mov_b64 s[0:1], 0x1de400
	global_load_lds_dwordx4 v[4:5], off nt
	v_lshl_add_u64 v[2:3], v[2:3], 0, s[0:1]
	s_mov_b32 m0, s51
	v_readlane_b32 s0, v253, 62
	global_load_lds_dwordx4 v[2:3], off nt
	v_readlane_b32 s1, v253, 63
	s_nop 1
	v_lshl_add_u64 v[182:183], v[182:183], 0, s[0:1]
	v_readlane_b32 s0, v253, 55
	s_add_i32 s61, s61, s0
	v_readlane_b32 s0, v253, 57
	s_add_i32 s60, s60, s0
	s_mov_b64 s[0:1], 0
	s_branch .LBB0_468
